# P5 post-LN rows hand-written (16 consecutive rows per wave, loads two rows ahead, DPP reductions) on top of P8 DMA
# speedup vs baseline: 1.0092x; 1.0092x over previous
.LBB0_569:
	s_or_b64 exec, exec, s[2:3]
	s_waitcnt lgkmcnt(0)
	v_mov_b32_e32 v0, v208
	s_barrier
	v_lshrrev_b32_e32 v168, 6, v208
	v_and_b32_e32 v169, 63, v208
	v_readfirstlane_b32 s42, v168
	v_lshlrev_b32_e32 v176, 4, v169
	v_lshlrev_b32_e32 v177, 3, v169
	s_nop 1
	s_add_u32 s1, s60, s42
	s_lshl_b32 s42, s1, 16
	s_add_u32 s2, s52, s42
	s_addc_u32 s3, s53, 0
	s_add_u32 s8, s90, s42
	s_addc_u32 s9, s91, 0
	s_add_u32 s8, s8, 0xec00000
	s_addc_u32 s9, s9, 0
	s_lshr_b32 s42, s42, 1
	s_add_u32 s6, s90, s42
	s_addc_u32 s7, s91, 0
	s_add_u32 s12, s6, 0x2400000
	s_addc_u32 s13, s7, 0
	s_add_u32 s6, s6, 0x16c00000
	s_addc_u32 s7, s7, 0
	s_lshr_b32 s42, s1, 7
	s_mul_i32 s42, s42, 0x3000
	s_add_u32 s38, s90, s42
	s_addc_u32 s39, s91, 0
	s_add_u32 s38, s38, 0x21b3000
	s_addc_u32 s39, s39, 0
	s_add_u32 s40, s38, 0x1000
	s_addc_u32 s41, s39, 0
	global_load_dwordx4 v[0:3], v176, s[64:65] offset:0
	global_load_dwordx4 v[4:7], v176, s[64:65] offset:1024
	global_load_dwordx4 v[8:11], v176, s[64:65] offset:2048
	global_load_dwordx4 v[12:15], v176, s[64:65] offset:3072
	global_load_dwordx4 v[16:19], v176, s[66:67] offset:0
	global_load_dwordx4 v[20:23], v176, s[66:67] offset:1024
	global_load_dwordx4 v[24:27], v176, s[66:67] offset:2048
	global_load_dwordx4 v[28:31], v176, s[66:67] offset:3072
	global_load_dwordx4 v[32:35], v176, s[40:41] offset:0
	global_load_dwordx4 v[36:39], v176, s[40:41] offset:1024
	global_load_dwordx4 v[40:43], v176, s[40:41] offset:2048
	global_load_dwordx4 v[44:47], v176, s[40:41] offset:3072
	global_load_dwordx4 v[48:51], v176, s[38:39] offset:0
	global_load_dwordx4 v[52:55], v176, s[38:39] offset:1024
	global_load_dwordx4 v[56:59], v176, s[38:39] offset:2048
	global_load_dwordx4 v[60:63], v176, s[38:39] offset:3072
	v_mov_b32_e32 v172, 0xba800000
	v_mov_b32_e32 v173, 0xba800000
	v_mov_b32_e32 v178, 0x3a800000
	v_mov_b32_e32 v179, 0x358637bd
	s_mov_b32 s44, 0x3fb504f3
	s_mov_b32 s45, 0x3fb504f3
	global_load_dwordx4 v[64:67], v176, s[2:3] offset:0
	global_load_dwordx4 v[68:71], v176, s[2:3] offset:1024
	global_load_dwordx4 v[72:75], v176, s[2:3] offset:2048
	global_load_dwordx4 v[76:79], v176, s[2:3] offset:3072
	global_load_dwordx2 v[112:113], v177, s[6:7] offset:0
	global_load_dwordx2 v[114:115], v177, s[6:7] offset:512
	global_load_dwordx2 v[116:117], v177, s[6:7] offset:1024
	global_load_dwordx2 v[118:119], v177, s[6:7] offset:1536
	s_add_u32 s2, s2, 0x1000
	s_addc_u32 s3, s3, 0
	s_add_u32 s6, s6, 0x800
	s_addc_u32 s7, s7, 0
	global_load_dwordx4 v[80:83], v176, s[2:3] offset:0
	global_load_dwordx4 v[84:87], v176, s[2:3] offset:1024
	global_load_dwordx4 v[88:91], v176, s[2:3] offset:2048
	global_load_dwordx4 v[92:95], v176, s[2:3] offset:3072
	global_load_dwordx2 v[120:121], v177, s[6:7] offset:0
	global_load_dwordx2 v[122:123], v177, s[6:7] offset:512
	global_load_dwordx2 v[124:125], v177, s[6:7] offset:1024
	global_load_dwordx2 v[126:127], v177, s[6:7] offset:1536
	s_add_u32 s2, s2, 0x1000
	s_addc_u32 s3, s3, 0
	s_add_u32 s6, s6, 0x800
	s_addc_u32 s7, s7, 0
	global_load_dwordx4 v[96:99], v176, s[2:3] offset:0
	global_load_dwordx4 v[100:103], v176, s[2:3] offset:1024
	global_load_dwordx4 v[104:107], v176, s[2:3] offset:2048
	global_load_dwordx4 v[108:111], v176, s[2:3] offset:3072
	global_load_dwordx2 v[128:129], v177, s[6:7] offset:0
	global_load_dwordx2 v[130:131], v177, s[6:7] offset:512
	global_load_dwordx2 v[132:133], v177, s[6:7] offset:1024
	global_load_dwordx2 v[134:135], v177, s[6:7] offset:1536
	s_add_u32 s2, s2, 0x1000
	s_addc_u32 s3, s3, 0
	s_add_u32 s6, s6, 0x800
	s_addc_u32 s7, s7, 0
	s_waitcnt vmcnt(16)
	v_pk_add_f32 v[32:33], v[32:33], 1.0 op_sel_hi:[1,0]
	v_pk_add_f32 v[34:35], v[34:35], 1.0 op_sel_hi:[1,0]
	v_pk_add_f32 v[36:37], v[36:37], 1.0 op_sel_hi:[1,0]
	v_pk_add_f32 v[38:39], v[38:39], 1.0 op_sel_hi:[1,0]
	v_pk_add_f32 v[40:41], v[40:41], 1.0 op_sel_hi:[1,0]
	v_pk_add_f32 v[42:43], v[42:43], 1.0 op_sel_hi:[1,0]
	v_pk_add_f32 v[44:45], v[44:45], 1.0 op_sel_hi:[1,0]
	v_pk_add_f32 v[46:47], v[46:47], 1.0 op_sel_hi:[1,0]
	v_lshlrev_b32_e32 v136, 16, v112
	v_and_b32_e32 v137, 0xffff0000, v112
	v_lshlrev_b32_e32 v138, 16, v113
	v_and_b32_e32 v139, 0xffff0000, v113
	v_lshlrev_b32_e32 v140, 16, v114
	v_and_b32_e32 v141, 0xffff0000, v114
	v_lshlrev_b32_e32 v142, 16, v115
	v_and_b32_e32 v143, 0xffff0000, v115
	v_lshlrev_b32_e32 v144, 16, v116
	v_and_b32_e32 v145, 0xffff0000, v116
	v_lshlrev_b32_e32 v146, 16, v117
	v_and_b32_e32 v147, 0xffff0000, v117
	v_lshlrev_b32_e32 v148, 16, v118
	v_and_b32_e32 v149, 0xffff0000, v118
	v_lshlrev_b32_e32 v150, 16, v119
	v_and_b32_e32 v151, 0xffff0000, v119
	v_pk_fma_f32 v[136:137], v[64:65], s[44:45], v[136:137]
	v_pk_fma_f32 v[138:139], v[66:67], s[44:45], v[138:139]
	v_pk_fma_f32 v[140:141], v[68:69], s[44:45], v[140:141]
	v_pk_fma_f32 v[142:143], v[70:71], s[44:45], v[142:143]
	v_pk_fma_f32 v[144:145], v[72:73], s[44:45], v[144:145]
	v_pk_fma_f32 v[146:147], v[74:75], s[44:45], v[146:147]
	v_pk_fma_f32 v[148:149], v[76:77], s[44:45], v[148:149]
	v_pk_fma_f32 v[150:151], v[78:79], s[44:45], v[150:151]
	v_pk_add_f32 v[152:153], v[136:137], v[138:139]
	v_pk_add_f32 v[152:153], v[152:153], v[140:141]
	v_pk_add_f32 v[152:153], v[152:153], v[142:143]
	v_pk_add_f32 v[152:153], v[152:153], v[144:145]
	v_pk_add_f32 v[152:153], v[152:153], v[146:147]
	v_pk_add_f32 v[152:153], v[152:153], v[148:149]
	v_pk_add_f32 v[152:153], v[152:153], v[150:151]
	v_add_f32_e32 v170, v152, v153
	s_nop 1
	v_add_f32_dpp v168, v170, v170 quad_perm:[1,0,3,2] row_mask:0xf bank_mask:0xf
	s_nop 1
	v_add_f32_dpp v168, v168, v168 quad_perm:[2,3,0,1] row_mask:0xf bank_mask:0xf
	s_nop 1
	v_add_f32_dpp v168, v168, v168 row_half_mirror row_mask:0xf bank_mask:0xf
	s_nop 1
	v_add_f32_dpp v168, v168, v168 row_mirror row_mask:0xf bank_mask:0xf
	s_nop 1
	v_add_f32_dpp v168, v168, v168 row_bcast:15 row_mask:0xa bank_mask:0xf
	s_nop 1
	v_add_f32_dpp v168, v168, v168 row_bcast:31 row_mask:0xc bank_mask:0xf
	s_nop 1
	v_readlane_b32 s42, v168, 63
	s_nop 3
	s_mov_b32 s43, s42
	v_pk_fma_f32 v[136:137], s[42:43], v[172:173], v[136:137]
	v_pk_fma_f32 v[138:139], s[42:43], v[172:173], v[138:139]
	v_pk_fma_f32 v[140:141], s[42:43], v[172:173], v[140:141]
	v_pk_fma_f32 v[142:143], s[42:43], v[172:173], v[142:143]
	v_pk_fma_f32 v[144:145], s[42:43], v[172:173], v[144:145]
	v_pk_fma_f32 v[146:147], s[42:43], v[172:173], v[146:147]
	v_pk_fma_f32 v[148:149], s[42:43], v[172:173], v[148:149]
	v_pk_fma_f32 v[150:151], s[42:43], v[172:173], v[150:151]
	v_pk_mul_f32 v[152:153], v[136:137], v[136:137]
	v_pk_fma_f32 v[152:153], v[138:139], v[138:139], v[152:153]
	v_pk_fma_f32 v[152:153], v[140:141], v[140:141], v[152:153]
	v_pk_fma_f32 v[152:153], v[142:143], v[142:143], v[152:153]
	v_pk_fma_f32 v[152:153], v[144:145], v[144:145], v[152:153]
	v_pk_fma_f32 v[152:153], v[146:147], v[146:147], v[152:153]
	v_pk_fma_f32 v[152:153], v[148:149], v[148:149], v[152:153]
	v_pk_fma_f32 v[152:153], v[150:151], v[150:151], v[152:153]
	v_add_f32_e32 v170, v152, v153
	s_nop 1
	v_add_f32_dpp v168, v170, v170 quad_perm:[1,0,3,2] row_mask:0xf bank_mask:0xf
	s_nop 1
	v_add_f32_dpp v168, v168, v168 quad_perm:[2,3,0,1] row_mask:0xf bank_mask:0xf
	s_nop 1
	v_add_f32_dpp v168, v168, v168 row_half_mirror row_mask:0xf bank_mask:0xf
	s_nop 1
	v_add_f32_dpp v168, v168, v168 row_mirror row_mask:0xf bank_mask:0xf
	s_nop 1
	v_add_f32_dpp v168, v168, v168 row_bcast:15 row_mask:0xa bank_mask:0xf
	s_nop 1
	v_add_f32_dpp v168, v168, v168 row_bcast:31 row_mask:0xc bank_mask:0xf
	s_nop 1
	v_readlane_b32 s42, v168, 63
	s_nop 3
	v_fma_f32 v174, s42, v178, v179
	v_rsq_f32_e32 v174, v174
	s_nop 0
	v_pk_mul_f32 v[136:137], v[136:137], v[174:175] op_sel_hi:[1,0]
	v_pk_mul_f32 v[138:139], v[138:139], v[174:175] op_sel_hi:[1,0]
	v_pk_mul_f32 v[140:141], v[140:141], v[174:175] op_sel_hi:[1,0]
	v_pk_mul_f32 v[142:143], v[142:143], v[174:175] op_sel_hi:[1,0]
	v_pk_mul_f32 v[144:145], v[144:145], v[174:175] op_sel_hi:[1,0]
	v_pk_mul_f32 v[146:147], v[146:147], v[174:175] op_sel_hi:[1,0]
	v_pk_mul_f32 v[148:149], v[148:149], v[174:175] op_sel_hi:[1,0]
	v_pk_mul_f32 v[150:151], v[150:151], v[174:175] op_sel_hi:[1,0]
	v_pk_fma_f32 v[136:137], v[136:137], v[0:1], v[16:17]
	v_pk_fma_f32 v[138:139], v[138:139], v[2:3], v[18:19]
	v_pk_fma_f32 v[140:141], v[140:141], v[4:5], v[20:21]
	v_pk_fma_f32 v[142:143], v[142:143], v[6:7], v[22:23]
	v_pk_fma_f32 v[144:145], v[144:145], v[8:9], v[24:25]
	v_pk_fma_f32 v[146:147], v[146:147], v[10:11], v[26:27]
	v_pk_fma_f32 v[148:149], v[148:149], v[12:13], v[28:29]
	v_pk_fma_f32 v[150:151], v[150:151], v[14:15], v[30:31]
	global_store_dwordx4 v176, v[136:139], s[8:9] offset:0
	global_store_dwordx4 v176, v[140:143], s[8:9] offset:1024
	global_store_dwordx4 v176, v[144:147], s[8:9] offset:2048
	global_store_dwordx4 v176, v[148:151], s[8:9] offset:3072
	v_pk_add_f32 v[152:153], v[136:137], v[138:139]
	v_pk_add_f32 v[152:153], v[152:153], v[140:141]
	v_pk_add_f32 v[152:153], v[152:153], v[142:143]
	v_pk_add_f32 v[152:153], v[152:153], v[144:145]
	v_pk_add_f32 v[152:153], v[152:153], v[146:147]
	v_pk_add_f32 v[152:153], v[152:153], v[148:149]
	v_pk_add_f32 v[152:153], v[152:153], v[150:151]
	v_add_f32_e32 v170, v152, v153
	s_nop 1
	v_add_f32_dpp v168, v170, v170 quad_perm:[1,0,3,2] row_mask:0xf bank_mask:0xf
	s_nop 1
	v_add_f32_dpp v168, v168, v168 quad_perm:[2,3,0,1] row_mask:0xf bank_mask:0xf
	s_nop 1
	v_add_f32_dpp v168, v168, v168 row_half_mirror row_mask:0xf bank_mask:0xf
	s_nop 1
	v_add_f32_dpp v168, v168, v168 row_mirror row_mask:0xf bank_mask:0xf
	s_nop 1
	v_add_f32_dpp v168, v168, v168 row_bcast:15 row_mask:0xa bank_mask:0xf
	s_nop 1
	v_add_f32_dpp v168, v168, v168 row_bcast:31 row_mask:0xc bank_mask:0xf
	s_nop 1
	v_readlane_b32 s42, v168, 63
	s_nop 3
	s_mov_b32 s43, s42
	v_pk_fma_f32 v[136:137], s[42:43], v[172:173], v[136:137]
	v_pk_fma_f32 v[138:139], s[42:43], v[172:173], v[138:139]
	v_pk_fma_f32 v[140:141], s[42:43], v[172:173], v[140:141]
	v_pk_fma_f32 v[142:143], s[42:43], v[172:173], v[142:143]
	v_pk_fma_f32 v[144:145], s[42:43], v[172:173], v[144:145]
	v_pk_fma_f32 v[146:147], s[42:43], v[172:173], v[146:147]
	v_pk_fma_f32 v[148:149], s[42:43], v[172:173], v[148:149]
	v_pk_fma_f32 v[150:151], s[42:43], v[172:173], v[150:151]
	v_pk_mul_f32 v[152:153], v[136:137], v[136:137]
	v_pk_fma_f32 v[152:153], v[138:139], v[138:139], v[152:153]
	v_pk_fma_f32 v[152:153], v[140:141], v[140:141], v[152:153]
	v_pk_fma_f32 v[152:153], v[142:143], v[142:143], v[152:153]
	v_pk_fma_f32 v[152:153], v[144:145], v[144:145], v[152:153]
	v_pk_fma_f32 v[152:153], v[146:147], v[146:147], v[152:153]
	v_pk_fma_f32 v[152:153], v[148:149], v[148:149], v[152:153]
	v_pk_fma_f32 v[152:153], v[150:151], v[150:151], v[152:153]
	v_add_f32_e32 v170, v152, v153
	s_nop 1
	v_add_f32_dpp v168, v170, v170 quad_perm:[1,0,3,2] row_mask:0xf bank_mask:0xf
	s_nop 1
	v_add_f32_dpp v168, v168, v168 quad_perm:[2,3,0,1] row_mask:0xf bank_mask:0xf
	s_nop 1
	v_add_f32_dpp v168, v168, v168 row_half_mirror row_mask:0xf bank_mask:0xf
	s_nop 1
	v_add_f32_dpp v168, v168, v168 row_mirror row_mask:0xf bank_mask:0xf
	s_nop 1
	v_add_f32_dpp v168, v168, v168 row_bcast:15 row_mask:0xa bank_mask:0xf
	s_nop 1
	v_add_f32_dpp v168, v168, v168 row_bcast:31 row_mask:0xc bank_mask:0xf
	s_nop 1
	v_readlane_b32 s42, v168, 63
	s_nop 3
	v_fma_f32 v174, s42, v178, v179
	v_rsq_f32_e32 v174, v174
	s_nop 0
	v_pk_mul_f32 v[136:137], v[136:137], v[174:175] op_sel_hi:[1,0]
	v_pk_mul_f32 v[138:139], v[138:139], v[174:175] op_sel_hi:[1,0]
	v_pk_mul_f32 v[140:141], v[140:141], v[174:175] op_sel_hi:[1,0]
	v_pk_mul_f32 v[142:143], v[142:143], v[174:175] op_sel_hi:[1,0]
	v_pk_mul_f32 v[144:145], v[144:145], v[174:175] op_sel_hi:[1,0]
	v_pk_mul_f32 v[146:147], v[146:147], v[174:175] op_sel_hi:[1,0]
	v_pk_mul_f32 v[148:149], v[148:149], v[174:175] op_sel_hi:[1,0]
	v_pk_mul_f32 v[150:151], v[150:151], v[174:175] op_sel_hi:[1,0]
	v_pk_fma_f32 v[136:137], v[136:137], v[32:33], v[48:49]
	v_pk_fma_f32 v[138:139], v[138:139], v[34:35], v[50:51]
	v_pk_fma_f32 v[140:141], v[140:141], v[36:37], v[52:53]
	v_pk_fma_f32 v[142:143], v[142:143], v[38:39], v[54:55]
	v_pk_fma_f32 v[144:145], v[144:145], v[40:41], v[56:57]
	v_pk_fma_f32 v[146:147], v[146:147], v[42:43], v[58:59]
	v_pk_fma_f32 v[148:149], v[148:149], v[44:45], v[60:61]
	v_pk_fma_f32 v[150:151], v[150:151], v[46:47], v[62:63]
	v_cvt_pk_bf16_f32 v152, v136, v137
	v_cvt_pk_bf16_f32 v153, v138, v139
	v_cvt_pk_bf16_f32 v154, v140, v141
	v_cvt_pk_bf16_f32 v155, v142, v143
	v_cvt_pk_bf16_f32 v156, v144, v145
	v_cvt_pk_bf16_f32 v157, v146, v147
	v_cvt_pk_bf16_f32 v158, v148, v149
	v_cvt_pk_bf16_f32 v159, v150, v151
	global_store_dwordx2 v177, v[152:153], s[12:13] offset:0
	global_store_dwordx2 v177, v[154:155], s[12:13] offset:512
	global_store_dwordx2 v177, v[156:157], s[12:13] offset:1024
	global_store_dwordx2 v177, v[158:159], s[12:13] offset:1536
	s_add_u32 s8, s8, 0x1000
	s_addc_u32 s9, s9, 0
	s_add_u32 s12, s12, 0x800
	s_addc_u32 s13, s13, 0
	global_load_dwordx4 v[64:67], v176, s[2:3] offset:0
	global_load_dwordx4 v[68:71], v176, s[2:3] offset:1024
	global_load_dwordx4 v[72:75], v176, s[2:3] offset:2048
	global_load_dwordx4 v[76:79], v176, s[2:3] offset:3072
	global_load_dwordx2 v[112:113], v177, s[6:7] offset:0
	global_load_dwordx2 v[114:115], v177, s[6:7] offset:512
	global_load_dwordx2 v[116:117], v177, s[6:7] offset:1024
	global_load_dwordx2 v[118:119], v177, s[6:7] offset:1536
	s_add_u32 s2, s2, 0x1000
	s_addc_u32 s3, s3, 0
	s_add_u32 s6, s6, 0x800
	s_addc_u32 s7, s7, 0
	s_waitcnt vmcnt(24)
	v_lshlrev_b32_e32 v136, 16, v120
	v_and_b32_e32 v137, 0xffff0000, v120
	v_lshlrev_b32_e32 v138, 16, v121
	v_and_b32_e32 v139, 0xffff0000, v121
	v_lshlrev_b32_e32 v140, 16, v122
	v_and_b32_e32 v141, 0xffff0000, v122
	v_lshlrev_b32_e32 v142, 16, v123
	v_and_b32_e32 v143, 0xffff0000, v123
	v_lshlrev_b32_e32 v144, 16, v124
	v_and_b32_e32 v145, 0xffff0000, v124
	v_lshlrev_b32_e32 v146, 16, v125
	v_and_b32_e32 v147, 0xffff0000, v125
	v_lshlrev_b32_e32 v148, 16, v126
	v_and_b32_e32 v149, 0xffff0000, v126
	v_lshlrev_b32_e32 v150, 16, v127
	v_and_b32_e32 v151, 0xffff0000, v127
	v_pk_fma_f32 v[136:137], v[80:81], s[44:45], v[136:137]
	v_pk_fma_f32 v[138:139], v[82:83], s[44:45], v[138:139]
	v_pk_fma_f32 v[140:141], v[84:85], s[44:45], v[140:141]
	v_pk_fma_f32 v[142:143], v[86:87], s[44:45], v[142:143]
	v_pk_fma_f32 v[144:145], v[88:89], s[44:45], v[144:145]
	v_pk_fma_f32 v[146:147], v[90:91], s[44:45], v[146:147]
	v_pk_fma_f32 v[148:149], v[92:93], s[44:45], v[148:149]
	v_pk_fma_f32 v[150:151], v[94:95], s[44:45], v[150:151]
	v_pk_add_f32 v[152:153], v[136:137], v[138:139]
	v_pk_add_f32 v[152:153], v[152:153], v[140:141]
	v_pk_add_f32 v[152:153], v[152:153], v[142:143]
	v_pk_add_f32 v[152:153], v[152:153], v[144:145]
	v_pk_add_f32 v[152:153], v[152:153], v[146:147]
	v_pk_add_f32 v[152:153], v[152:153], v[148:149]
	v_pk_add_f32 v[152:153], v[152:153], v[150:151]
	v_add_f32_e32 v170, v152, v153
	s_nop 1
	v_add_f32_dpp v168, v170, v170 quad_perm:[1,0,3,2] row_mask:0xf bank_mask:0xf
	s_nop 1
	v_add_f32_dpp v168, v168, v168 quad_perm:[2,3,0,1] row_mask:0xf bank_mask:0xf
	s_nop 1
	v_add_f32_dpp v168, v168, v168 row_half_mirror row_mask:0xf bank_mask:0xf
	s_nop 1
	v_add_f32_dpp v168, v168, v168 row_mirror row_mask:0xf bank_mask:0xf
	s_nop 1
	v_add_f32_dpp v168, v168, v168 row_bcast:15 row_mask:0xa bank_mask:0xf
	s_nop 1
	v_add_f32_dpp v168, v168, v168 row_bcast:31 row_mask:0xc bank_mask:0xf
	s_nop 1
	v_readlane_b32 s42, v168, 63
	s_nop 3
	s_mov_b32 s43, s42
	v_pk_fma_f32 v[136:137], s[42:43], v[172:173], v[136:137]
	v_pk_fma_f32 v[138:139], s[42:43], v[172:173], v[138:139]
	v_pk_fma_f32 v[140:141], s[42:43], v[172:173], v[140:141]
	v_pk_fma_f32 v[142:143], s[42:43], v[172:173], v[142:143]
	v_pk_fma_f32 v[144:145], s[42:43], v[172:173], v[144:145]
	v_pk_fma_f32 v[146:147], s[42:43], v[172:173], v[146:147]
	v_pk_fma_f32 v[148:149], s[42:43], v[172:173], v[148:149]
	v_pk_fma_f32 v[150:151], s[42:43], v[172:173], v[150:151]
	v_pk_mul_f32 v[152:153], v[136:137], v[136:137]
	v_pk_fma_f32 v[152:153], v[138:139], v[138:139], v[152:153]
	v_pk_fma_f32 v[152:153], v[140:141], v[140:141], v[152:153]
	v_pk_fma_f32 v[152:153], v[142:143], v[142:143], v[152:153]
	v_pk_fma_f32 v[152:153], v[144:145], v[144:145], v[152:153]
	v_pk_fma_f32 v[152:153], v[146:147], v[146:147], v[152:153]
	v_pk_fma_f32 v[152:153], v[148:149], v[148:149], v[152:153]
	v_pk_fma_f32 v[152:153], v[150:151], v[150:151], v[152:153]
	v_add_f32_e32 v170, v152, v153
	s_nop 1
	v_add_f32_dpp v168, v170, v170 quad_perm:[1,0,3,2] row_mask:0xf bank_mask:0xf
	s_nop 1
	v_add_f32_dpp v168, v168, v168 quad_perm:[2,3,0,1] row_mask:0xf bank_mask:0xf
	s_nop 1
	v_add_f32_dpp v168, v168, v168 row_half_mirror row_mask:0xf bank_mask:0xf
	s_nop 1
	v_add_f32_dpp v168, v168, v168 row_mirror row_mask:0xf bank_mask:0xf
	s_nop 1
	v_add_f32_dpp v168, v168, v168 row_bcast:15 row_mask:0xa bank_mask:0xf
	s_nop 1
	v_add_f32_dpp v168, v168, v168 row_bcast:31 row_mask:0xc bank_mask:0xf
	s_nop 1
	v_readlane_b32 s42, v168, 63
	s_nop 3
	v_fma_f32 v174, s42, v178, v179
	v_rsq_f32_e32 v174, v174
	s_nop 0
	v_pk_mul_f32 v[136:137], v[136:137], v[174:175] op_sel_hi:[1,0]
	v_pk_mul_f32 v[138:139], v[138:139], v[174:175] op_sel_hi:[1,0]
	v_pk_mul_f32 v[140:141], v[140:141], v[174:175] op_sel_hi:[1,0]
	v_pk_mul_f32 v[142:143], v[142:143], v[174:175] op_sel_hi:[1,0]
	v_pk_mul_f32 v[144:145], v[144:145], v[174:175] op_sel_hi:[1,0]
	v_pk_mul_f32 v[146:147], v[146:147], v[174:175] op_sel_hi:[1,0]
	v_pk_mul_f32 v[148:149], v[148:149], v[174:175] op_sel_hi:[1,0]
	v_pk_mul_f32 v[150:151], v[150:151], v[174:175] op_sel_hi:[1,0]
	v_pk_fma_f32 v[136:137], v[136:137], v[0:1], v[16:17]
	v_pk_fma_f32 v[138:139], v[138:139], v[2:3], v[18:19]
	v_pk_fma_f32 v[140:141], v[140:141], v[4:5], v[20:21]
	v_pk_fma_f32 v[142:143], v[142:143], v[6:7], v[22:23]
	v_pk_fma_f32 v[144:145], v[144:145], v[8:9], v[24:25]
	v_pk_fma_f32 v[146:147], v[146:147], v[10:11], v[26:27]
	v_pk_fma_f32 v[148:149], v[148:149], v[12:13], v[28:29]
	v_pk_fma_f32 v[150:151], v[150:151], v[14:15], v[30:31]
	global_store_dwordx4 v176, v[136:139], s[8:9] offset:0
	global_store_dwordx4 v176, v[140:143], s[8:9] offset:1024
	global_store_dwordx4 v176, v[144:147], s[8:9] offset:2048
	global_store_dwordx4 v176, v[148:151], s[8:9] offset:3072
	v_pk_add_f32 v[152:153], v[136:137], v[138:139]
	v_pk_add_f32 v[152:153], v[152:153], v[140:141]
	v_pk_add_f32 v[152:153], v[152:153], v[142:143]
	v_pk_add_f32 v[152:153], v[152:153], v[144:145]
	v_pk_add_f32 v[152:153], v[152:153], v[146:147]
	v_pk_add_f32 v[152:153], v[152:153], v[148:149]
	v_pk_add_f32 v[152:153], v[152:153], v[150:151]
	v_add_f32_e32 v170, v152, v153
	s_nop 1
	v_add_f32_dpp v168, v170, v170 quad_perm:[1,0,3,2] row_mask:0xf bank_mask:0xf
	s_nop 1
	v_add_f32_dpp v168, v168, v168 quad_perm:[2,3,0,1] row_mask:0xf bank_mask:0xf
	s_nop 1
	v_add_f32_dpp v168, v168, v168 row_half_mirror row_mask:0xf bank_mask:0xf
	s_nop 1
	v_add_f32_dpp v168, v168, v168 row_mirror row_mask:0xf bank_mask:0xf
	s_nop 1
	v_add_f32_dpp v168, v168, v168 row_bcast:15 row_mask:0xa bank_mask:0xf
	s_nop 1
	v_add_f32_dpp v168, v168, v168 row_bcast:31 row_mask:0xc bank_mask:0xf
	s_nop 1
	v_readlane_b32 s42, v168, 63
	s_nop 3
	s_mov_b32 s43, s42
	v_pk_fma_f32 v[136:137], s[42:43], v[172:173], v[136:137]
	v_pk_fma_f32 v[138:139], s[42:43], v[172:173], v[138:139]
	v_pk_fma_f32 v[140:141], s[42:43], v[172:173], v[140:141]
	v_pk_fma_f32 v[142:143], s[42:43], v[172:173], v[142:143]
	v_pk_fma_f32 v[144:145], s[42:43], v[172:173], v[144:145]
	v_pk_fma_f32 v[146:147], s[42:43], v[172:173], v[146:147]
	v_pk_fma_f32 v[148:149], s[42:43], v[172:173], v[148:149]
	v_pk_fma_f32 v[150:151], s[42:43], v[172:173], v[150:151]
	v_pk_mul_f32 v[152:153], v[136:137], v[136:137]
	v_pk_fma_f32 v[152:153], v[138:139], v[138:139], v[152:153]
	v_pk_fma_f32 v[152:153], v[140:141], v[140:141], v[152:153]
	v_pk_fma_f32 v[152:153], v[142:143], v[142:143], v[152:153]
	v_pk_fma_f32 v[152:153], v[144:145], v[144:145], v[152:153]
	v_pk_fma_f32 v[152:153], v[146:147], v[146:147], v[152:153]
	v_pk_fma_f32 v[152:153], v[148:149], v[148:149], v[152:153]
	v_pk_fma_f32 v[152:153], v[150:151], v[150:151], v[152:153]
	v_add_f32_e32 v170, v152, v153
	s_nop 1
	v_add_f32_dpp v168, v170, v170 quad_perm:[1,0,3,2] row_mask:0xf bank_mask:0xf
	s_nop 1
	v_add_f32_dpp v168, v168, v168 quad_perm:[2,3,0,1] row_mask:0xf bank_mask:0xf
	s_nop 1
	v_add_f32_dpp v168, v168, v168 row_half_mirror row_mask:0xf bank_mask:0xf
	s_nop 1
	v_add_f32_dpp v168, v168, v168 row_mirror row_mask:0xf bank_mask:0xf
	s_nop 1
	v_add_f32_dpp v168, v168, v168 row_bcast:15 row_mask:0xa bank_mask:0xf
	s_nop 1
	v_add_f32_dpp v168, v168, v168 row_bcast:31 row_mask:0xc bank_mask:0xf
	s_nop 1
	v_readlane_b32 s42, v168, 63
	s_nop 3
	v_fma_f32 v174, s42, v178, v179
	v_rsq_f32_e32 v174, v174
	s_nop 0
	v_pk_mul_f32 v[136:137], v[136:137], v[174:175] op_sel_hi:[1,0]
	v_pk_mul_f32 v[138:139], v[138:139], v[174:175] op_sel_hi:[1,0]
	v_pk_mul_f32 v[140:141], v[140:141], v[174:175] op_sel_hi:[1,0]
	v_pk_mul_f32 v[142:143], v[142:143], v[174:175] op_sel_hi:[1,0]
	v_pk_mul_f32 v[144:145], v[144:145], v[174:175] op_sel_hi:[1,0]
	v_pk_mul_f32 v[146:147], v[146:147], v[174:175] op_sel_hi:[1,0]
	v_pk_mul_f32 v[148:149], v[148:149], v[174:175] op_sel_hi:[1,0]
	v_pk_mul_f32 v[150:151], v[150:151], v[174:175] op_sel_hi:[1,0]
	v_pk_fma_f32 v[136:137], v[136:137], v[32:33], v[48:49]
	v_pk_fma_f32 v[138:139], v[138:139], v[34:35], v[50:51]
	v_pk_fma_f32 v[140:141], v[140:141], v[36:37], v[52:53]
	v_pk_fma_f32 v[142:143], v[142:143], v[38:39], v[54:55]
	v_pk_fma_f32 v[144:145], v[144:145], v[40:41], v[56:57]
	v_pk_fma_f32 v[146:147], v[146:147], v[42:43], v[58:59]
	v_pk_fma_f32 v[148:149], v[148:149], v[44:45], v[60:61]
	v_pk_fma_f32 v[150:151], v[150:151], v[46:47], v[62:63]
	v_cvt_pk_bf16_f32 v152, v136, v137
	v_cvt_pk_bf16_f32 v153, v138, v139
	v_cvt_pk_bf16_f32 v154, v140, v141
	v_cvt_pk_bf16_f32 v155, v142, v143
	v_cvt_pk_bf16_f32 v156, v144, v145
	v_cvt_pk_bf16_f32 v157, v146, v147
	v_cvt_pk_bf16_f32 v158, v148, v149
	v_cvt_pk_bf16_f32 v159, v150, v151
	global_store_dwordx2 v177, v[152:153], s[12:13] offset:0
	global_store_dwordx2 v177, v[154:155], s[12:13] offset:512
	global_store_dwordx2 v177, v[156:157], s[12:13] offset:1024
	global_store_dwordx2 v177, v[158:159], s[12:13] offset:1536
	s_add_u32 s8, s8, 0x1000
	s_addc_u32 s9, s9, 0
	s_add_u32 s12, s12, 0x800
	s_addc_u32 s13, s13, 0
	global_load_dwordx4 v[80:83], v176, s[2:3] offset:0
	global_load_dwordx4 v[84:87], v176, s[2:3] offset:1024
	global_load_dwordx4 v[88:91], v176, s[2:3] offset:2048
	global_load_dwordx4 v[92:95], v176, s[2:3] offset:3072
	global_load_dwordx2 v[120:121], v177, s[6:7] offset:0
	global_load_dwordx2 v[122:123], v177, s[6:7] offset:512
	global_load_dwordx2 v[124:125], v177, s[6:7] offset:1024
	global_load_dwordx2 v[126:127], v177, s[6:7] offset:1536
	s_add_u32 s2, s2, 0x1000
	s_addc_u32 s3, s3, 0
	s_add_u32 s6, s6, 0x800
	s_addc_u32 s7, s7, 0
	s_waitcnt vmcnt(32)
	v_lshlrev_b32_e32 v136, 16, v128
	v_and_b32_e32 v137, 0xffff0000, v128
	v_lshlrev_b32_e32 v138, 16, v129
	v_and_b32_e32 v139, 0xffff0000, v129
	v_lshlrev_b32_e32 v140, 16, v130
	v_and_b32_e32 v141, 0xffff0000, v130
	v_lshlrev_b32_e32 v142, 16, v131
	v_and_b32_e32 v143, 0xffff0000, v131
	v_lshlrev_b32_e32 v144, 16, v132
	v_and_b32_e32 v145, 0xffff0000, v132
	v_lshlrev_b32_e32 v146, 16, v133
	v_and_b32_e32 v147, 0xffff0000, v133
	v_lshlrev_b32_e32 v148, 16, v134
	v_and_b32_e32 v149, 0xffff0000, v134
	v_lshlrev_b32_e32 v150, 16, v135
	v_and_b32_e32 v151, 0xffff0000, v135
	v_pk_fma_f32 v[136:137], v[96:97], s[44:45], v[136:137]
	v_pk_fma_f32 v[138:139], v[98:99], s[44:45], v[138:139]
	v_pk_fma_f32 v[140:141], v[100:101], s[44:45], v[140:141]
	v_pk_fma_f32 v[142:143], v[102:103], s[44:45], v[142:143]
	v_pk_fma_f32 v[144:145], v[104:105], s[44:45], v[144:145]
	v_pk_fma_f32 v[146:147], v[106:107], s[44:45], v[146:147]
	v_pk_fma_f32 v[148:149], v[108:109], s[44:45], v[148:149]
	v_pk_fma_f32 v[150:151], v[110:111], s[44:45], v[150:151]
	v_pk_add_f32 v[152:153], v[136:137], v[138:139]
	v_pk_add_f32 v[152:153], v[152:153], v[140:141]
	v_pk_add_f32 v[152:153], v[152:153], v[142:143]
	v_pk_add_f32 v[152:153], v[152:153], v[144:145]
	v_pk_add_f32 v[152:153], v[152:153], v[146:147]
	v_pk_add_f32 v[152:153], v[152:153], v[148:149]
	v_pk_add_f32 v[152:153], v[152:153], v[150:151]
	v_add_f32_e32 v170, v152, v153
	s_nop 1
	v_add_f32_dpp v168, v170, v170 quad_perm:[1,0,3,2] row_mask:0xf bank_mask:0xf
	s_nop 1
	v_add_f32_dpp v168, v168, v168 quad_perm:[2,3,0,1] row_mask:0xf bank_mask:0xf
	s_nop 1
	v_add_f32_dpp v168, v168, v168 row_half_mirror row_mask:0xf bank_mask:0xf
	s_nop 1
	v_add_f32_dpp v168, v168, v168 row_mirror row_mask:0xf bank_mask:0xf
	s_nop 1
	v_add_f32_dpp v168, v168, v168 row_bcast:15 row_mask:0xa bank_mask:0xf
	s_nop 1
	v_add_f32_dpp v168, v168, v168 row_bcast:31 row_mask:0xc bank_mask:0xf
	s_nop 1
	v_readlane_b32 s42, v168, 63
	s_nop 3
	s_mov_b32 s43, s42
	v_pk_fma_f32 v[136:137], s[42:43], v[172:173], v[136:137]
	v_pk_fma_f32 v[138:139], s[42:43], v[172:173], v[138:139]
	v_pk_fma_f32 v[140:141], s[42:43], v[172:173], v[140:141]
	v_pk_fma_f32 v[142:143], s[42:43], v[172:173], v[142:143]
	v_pk_fma_f32 v[144:145], s[42:43], v[172:173], v[144:145]
	v_pk_fma_f32 v[146:147], s[42:43], v[172:173], v[146:147]
	v_pk_fma_f32 v[148:149], s[42:43], v[172:173], v[148:149]
	v_pk_fma_f32 v[150:151], s[42:43], v[172:173], v[150:151]
	v_pk_mul_f32 v[152:153], v[136:137], v[136:137]
	v_pk_fma_f32 v[152:153], v[138:139], v[138:139], v[152:153]
	v_pk_fma_f32 v[152:153], v[140:141], v[140:141], v[152:153]
	v_pk_fma_f32 v[152:153], v[142:143], v[142:143], v[152:153]
	v_pk_fma_f32 v[152:153], v[144:145], v[144:145], v[152:153]
	v_pk_fma_f32 v[152:153], v[146:147], v[146:147], v[152:153]
	v_pk_fma_f32 v[152:153], v[148:149], v[148:149], v[152:153]
	v_pk_fma_f32 v[152:153], v[150:151], v[150:151], v[152:153]
	v_add_f32_e32 v170, v152, v153
	s_nop 1
	v_add_f32_dpp v168, v170, v170 quad_perm:[1,0,3,2] row_mask:0xf bank_mask:0xf
	s_nop 1
	v_add_f32_dpp v168, v168, v168 quad_perm:[2,3,0,1] row_mask:0xf bank_mask:0xf
	s_nop 1
	v_add_f32_dpp v168, v168, v168 row_half_mirror row_mask:0xf bank_mask:0xf
	s_nop 1
	v_add_f32_dpp v168, v168, v168 row_mirror row_mask:0xf bank_mask:0xf
	s_nop 1
	v_add_f32_dpp v168, v168, v168 row_bcast:15 row_mask:0xa bank_mask:0xf
	s_nop 1
	v_add_f32_dpp v168, v168, v168 row_bcast:31 row_mask:0xc bank_mask:0xf
	s_nop 1
	v_readlane_b32 s42, v168, 63
	s_nop 3
	v_fma_f32 v174, s42, v178, v179
	v_rsq_f32_e32 v174, v174
	s_nop 0
	v_pk_mul_f32 v[136:137], v[136:137], v[174:175] op_sel_hi:[1,0]
	v_pk_mul_f32 v[138:139], v[138:139], v[174:175] op_sel_hi:[1,0]
	v_pk_mul_f32 v[140:141], v[140:141], v[174:175] op_sel_hi:[1,0]
	v_pk_mul_f32 v[142:143], v[142:143], v[174:175] op_sel_hi:[1,0]
	v_pk_mul_f32 v[144:145], v[144:145], v[174:175] op_sel_hi:[1,0]
	v_pk_mul_f32 v[146:147], v[146:147], v[174:175] op_sel_hi:[1,0]
	v_pk_mul_f32 v[148:149], v[148:149], v[174:175] op_sel_hi:[1,0]
	v_pk_mul_f32 v[150:151], v[150:151], v[174:175] op_sel_hi:[1,0]
	v_pk_fma_f32 v[136:137], v[136:137], v[0:1], v[16:17]
	v_pk_fma_f32 v[138:139], v[138:139], v[2:3], v[18:19]
	v_pk_fma_f32 v[140:141], v[140:141], v[4:5], v[20:21]
	v_pk_fma_f32 v[142:143], v[142:143], v[6:7], v[22:23]
	v_pk_fma_f32 v[144:145], v[144:145], v[8:9], v[24:25]
	v_pk_fma_f32 v[146:147], v[146:147], v[10:11], v[26:27]
	v_pk_fma_f32 v[148:149], v[148:149], v[12:13], v[28:29]
	v_pk_fma_f32 v[150:151], v[150:151], v[14:15], v[30:31]
	global_store_dwordx4 v176, v[136:139], s[8:9] offset:0
	global_store_dwordx4 v176, v[140:143], s[8:9] offset:1024
	global_store_dwordx4 v176, v[144:147], s[8:9] offset:2048
	global_store_dwordx4 v176, v[148:151], s[8:9] offset:3072
	v_pk_add_f32 v[152:153], v[136:137], v[138:139]
	v_pk_add_f32 v[152:153], v[152:153], v[140:141]
	v_pk_add_f32 v[152:153], v[152:153], v[142:143]
	v_pk_add_f32 v[152:153], v[152:153], v[144:145]
	v_pk_add_f32 v[152:153], v[152:153], v[146:147]
	v_pk_add_f32 v[152:153], v[152:153], v[148:149]
	v_pk_add_f32 v[152:153], v[152:153], v[150:151]
	v_add_f32_e32 v170, v152, v153
	s_nop 1
	v_add_f32_dpp v168, v170, v170 quad_perm:[1,0,3,2] row_mask:0xf bank_mask:0xf
	s_nop 1
	v_add_f32_dpp v168, v168, v168 quad_perm:[2,3,0,1] row_mask:0xf bank_mask:0xf
	s_nop 1
	v_add_f32_dpp v168, v168, v168 row_half_mirror row_mask:0xf bank_mask:0xf
	s_nop 1
	v_add_f32_dpp v168, v168, v168 row_mirror row_mask:0xf bank_mask:0xf
	s_nop 1
	v_add_f32_dpp v168, v168, v168 row_bcast:15 row_mask:0xa bank_mask:0xf
	s_nop 1
	v_add_f32_dpp v168, v168, v168 row_bcast:31 row_mask:0xc bank_mask:0xf
	s_nop 1
	v_readlane_b32 s42, v168, 63
	s_nop 3
	s_mov_b32 s43, s42
	v_pk_fma_f32 v[136:137], s[42:43], v[172:173], v[136:137]
	v_pk_fma_f32 v[138:139], s[42:43], v[172:173], v[138:139]
	v_pk_fma_f32 v[140:141], s[42:43], v[172:173], v[140:141]
	v_pk_fma_f32 v[142:143], s[42:43], v[172:173], v[142:143]
	v_pk_fma_f32 v[144:145], s[42:43], v[172:173], v[144:145]
	v_pk_fma_f32 v[146:147], s[42:43], v[172:173], v[146:147]
	v_pk_fma_f32 v[148:149], s[42:43], v[172:173], v[148:149]
	v_pk_fma_f32 v[150:151], s[42:43], v[172:173], v[150:151]
	v_pk_mul_f32 v[152:153], v[136:137], v[136:137]
	v_pk_fma_f32 v[152:153], v[138:139], v[138:139], v[152:153]
	v_pk_fma_f32 v[152:153], v[140:141], v[140:141], v[152:153]
	v_pk_fma_f32 v[152:153], v[142:143], v[142:143], v[152:153]
	v_pk_fma_f32 v[152:153], v[144:145], v[144:145], v[152:153]
	v_pk_fma_f32 v[152:153], v[146:147], v[146:147], v[152:153]
	v_pk_fma_f32 v[152:153], v[148:149], v[148:149], v[152:153]
	v_pk_fma_f32 v[152:153], v[150:151], v[150:151], v[152:153]
	v_add_f32_e32 v170, v152, v153
	s_nop 1
	v_add_f32_dpp v168, v170, v170 quad_perm:[1,0,3,2] row_mask:0xf bank_mask:0xf
	s_nop 1
	v_add_f32_dpp v168, v168, v168 quad_perm:[2,3,0,1] row_mask:0xf bank_mask:0xf
	s_nop 1
	v_add_f32_dpp v168, v168, v168 row_half_mirror row_mask:0xf bank_mask:0xf
	s_nop 1
	v_add_f32_dpp v168, v168, v168 row_mirror row_mask:0xf bank_mask:0xf
	s_nop 1
	v_add_f32_dpp v168, v168, v168 row_bcast:15 row_mask:0xa bank_mask:0xf
	s_nop 1
	v_add_f32_dpp v168, v168, v168 row_bcast:31 row_mask:0xc bank_mask:0xf
	s_nop 1
	v_readlane_b32 s42, v168, 63
	s_nop 3
	v_fma_f32 v174, s42, v178, v179
	v_rsq_f32_e32 v174, v174
	s_nop 0
	v_pk_mul_f32 v[136:137], v[136:137], v[174:175] op_sel_hi:[1,0]
	v_pk_mul_f32 v[138:139], v[138:139], v[174:175] op_sel_hi:[1,0]
	v_pk_mul_f32 v[140:141], v[140:141], v[174:175] op_sel_hi:[1,0]
	v_pk_mul_f32 v[142:143], v[142:143], v[174:175] op_sel_hi:[1,0]
	v_pk_mul_f32 v[144:145], v[144:145], v[174:175] op_sel_hi:[1,0]
	v_pk_mul_f32 v[146:147], v[146:147], v[174:175] op_sel_hi:[1,0]
	v_pk_mul_f32 v[148:149], v[148:149], v[174:175] op_sel_hi:[1,0]
	v_pk_mul_f32 v[150:151], v[150:151], v[174:175] op_sel_hi:[1,0]
	v_pk_fma_f32 v[136:137], v[136:137], v[32:33], v[48:49]
	v_pk_fma_f32 v[138:139], v[138:139], v[34:35], v[50:51]
	v_pk_fma_f32 v[140:141], v[140:141], v[36:37], v[52:53]
	v_pk_fma_f32 v[142:143], v[142:143], v[38:39], v[54:55]
	v_pk_fma_f32 v[144:145], v[144:145], v[40:41], v[56:57]
	v_pk_fma_f32 v[146:147], v[146:147], v[42:43], v[58:59]
	v_pk_fma_f32 v[148:149], v[148:149], v[44:45], v[60:61]
	v_pk_fma_f32 v[150:151], v[150:151], v[46:47], v[62:63]
	v_cvt_pk_bf16_f32 v152, v136, v137
	v_cvt_pk_bf16_f32 v153, v138, v139
	v_cvt_pk_bf16_f32 v154, v140, v141
	v_cvt_pk_bf16_f32 v155, v142, v143
	v_cvt_pk_bf16_f32 v156, v144, v145
	v_cvt_pk_bf16_f32 v157, v146, v147
	v_cvt_pk_bf16_f32 v158, v148, v149
	v_cvt_pk_bf16_f32 v159, v150, v151
	global_store_dwordx2 v177, v[152:153], s[12:13] offset:0
	global_store_dwordx2 v177, v[154:155], s[12:13] offset:512
	global_store_dwordx2 v177, v[156:157], s[12:13] offset:1024
	global_store_dwordx2 v177, v[158:159], s[12:13] offset:1536
	s_add_u32 s8, s8, 0x1000
	s_addc_u32 s9, s9, 0
	s_add_u32 s12, s12, 0x800
	s_addc_u32 s13, s13, 0
	global_load_dwordx4 v[96:99], v176, s[2:3] offset:0
	global_load_dwordx4 v[100:103], v176, s[2:3] offset:1024
	global_load_dwordx4 v[104:107], v176, s[2:3] offset:2048
	global_load_dwordx4 v[108:111], v176, s[2:3] offset:3072
	global_load_dwordx2 v[128:129], v177, s[6:7] offset:0
	global_load_dwordx2 v[130:131], v177, s[6:7] offset:512
	global_load_dwordx2 v[132:133], v177, s[6:7] offset:1024
	global_load_dwordx2 v[134:135], v177, s[6:7] offset:1536
	s_add_u32 s2, s2, 0x1000
	s_addc_u32 s3, s3, 0
	s_add_u32 s6, s6, 0x800
	s_addc_u32 s7, s7, 0
	s_waitcnt vmcnt(32)
	v_lshlrev_b32_e32 v136, 16, v112
	v_and_b32_e32 v137, 0xffff0000, v112
	v_lshlrev_b32_e32 v138, 16, v113
	v_and_b32_e32 v139, 0xffff0000, v113
	v_lshlrev_b32_e32 v140, 16, v114
	v_and_b32_e32 v141, 0xffff0000, v114
	v_lshlrev_b32_e32 v142, 16, v115
	v_and_b32_e32 v143, 0xffff0000, v115
	v_lshlrev_b32_e32 v144, 16, v116
	v_and_b32_e32 v145, 0xffff0000, v116
	v_lshlrev_b32_e32 v146, 16, v117
	v_and_b32_e32 v147, 0xffff0000, v117
	v_lshlrev_b32_e32 v148, 16, v118
	v_and_b32_e32 v149, 0xffff0000, v118
	v_lshlrev_b32_e32 v150, 16, v119
	v_and_b32_e32 v151, 0xffff0000, v119
	v_pk_fma_f32 v[136:137], v[64:65], s[44:45], v[136:137]
	v_pk_fma_f32 v[138:139], v[66:67], s[44:45], v[138:139]
	v_pk_fma_f32 v[140:141], v[68:69], s[44:45], v[140:141]
	v_pk_fma_f32 v[142:143], v[70:71], s[44:45], v[142:143]
	v_pk_fma_f32 v[144:145], v[72:73], s[44:45], v[144:145]
	v_pk_fma_f32 v[146:147], v[74:75], s[44:45], v[146:147]
	v_pk_fma_f32 v[148:149], v[76:77], s[44:45], v[148:149]
	v_pk_fma_f32 v[150:151], v[78:79], s[44:45], v[150:151]
	v_pk_add_f32 v[152:153], v[136:137], v[138:139]
	v_pk_add_f32 v[152:153], v[152:153], v[140:141]
	v_pk_add_f32 v[152:153], v[152:153], v[142:143]
	v_pk_add_f32 v[152:153], v[152:153], v[144:145]
	v_pk_add_f32 v[152:153], v[152:153], v[146:147]
	v_pk_add_f32 v[152:153], v[152:153], v[148:149]
	v_pk_add_f32 v[152:153], v[152:153], v[150:151]
	v_add_f32_e32 v170, v152, v153
	s_nop 1
	v_add_f32_dpp v168, v170, v170 quad_perm:[1,0,3,2] row_mask:0xf bank_mask:0xf
	s_nop 1
	v_add_f32_dpp v168, v168, v168 quad_perm:[2,3,0,1] row_mask:0xf bank_mask:0xf
	s_nop 1
	v_add_f32_dpp v168, v168, v168 row_half_mirror row_mask:0xf bank_mask:0xf
	s_nop 1
	v_add_f32_dpp v168, v168, v168 row_mirror row_mask:0xf bank_mask:0xf
	s_nop 1
	v_add_f32_dpp v168, v168, v168 row_bcast:15 row_mask:0xa bank_mask:0xf
	s_nop 1
	v_add_f32_dpp v168, v168, v168 row_bcast:31 row_mask:0xc bank_mask:0xf
	s_nop 1
	v_readlane_b32 s42, v168, 63
	s_nop 3
	s_mov_b32 s43, s42
	v_pk_fma_f32 v[136:137], s[42:43], v[172:173], v[136:137]
	v_pk_fma_f32 v[138:139], s[42:43], v[172:173], v[138:139]
	v_pk_fma_f32 v[140:141], s[42:43], v[172:173], v[140:141]
	v_pk_fma_f32 v[142:143], s[42:43], v[172:173], v[142:143]
	v_pk_fma_f32 v[144:145], s[42:43], v[172:173], v[144:145]
	v_pk_fma_f32 v[146:147], s[42:43], v[172:173], v[146:147]
	v_pk_fma_f32 v[148:149], s[42:43], v[172:173], v[148:149]
	v_pk_fma_f32 v[150:151], s[42:43], v[172:173], v[150:151]
	v_pk_mul_f32 v[152:153], v[136:137], v[136:137]
	v_pk_fma_f32 v[152:153], v[138:139], v[138:139], v[152:153]
	v_pk_fma_f32 v[152:153], v[140:141], v[140:141], v[152:153]
	v_pk_fma_f32 v[152:153], v[142:143], v[142:143], v[152:153]
	v_pk_fma_f32 v[152:153], v[144:145], v[144:145], v[152:153]
	v_pk_fma_f32 v[152:153], v[146:147], v[146:147], v[152:153]
	v_pk_fma_f32 v[152:153], v[148:149], v[148:149], v[152:153]
	v_pk_fma_f32 v[152:153], v[150:151], v[150:151], v[152:153]
	v_add_f32_e32 v170, v152, v153
	s_nop 1
	v_add_f32_dpp v168, v170, v170 quad_perm:[1,0,3,2] row_mask:0xf bank_mask:0xf
	s_nop 1
	v_add_f32_dpp v168, v168, v168 quad_perm:[2,3,0,1] row_mask:0xf bank_mask:0xf
	s_nop 1
	v_add_f32_dpp v168, v168, v168 row_half_mirror row_mask:0xf bank_mask:0xf
	s_nop 1
	v_add_f32_dpp v168, v168, v168 row_mirror row_mask:0xf bank_mask:0xf
	s_nop 1
	v_add_f32_dpp v168, v168, v168 row_bcast:15 row_mask:0xa bank_mask:0xf
	s_nop 1
	v_add_f32_dpp v168, v168, v168 row_bcast:31 row_mask:0xc bank_mask:0xf
	s_nop 1
	v_readlane_b32 s42, v168, 63
	s_nop 3
	v_fma_f32 v174, s42, v178, v179
	v_rsq_f32_e32 v174, v174
	s_nop 0
	v_pk_mul_f32 v[136:137], v[136:137], v[174:175] op_sel_hi:[1,0]
	v_pk_mul_f32 v[138:139], v[138:139], v[174:175] op_sel_hi:[1,0]
	v_pk_mul_f32 v[140:141], v[140:141], v[174:175] op_sel_hi:[1,0]
	v_pk_mul_f32 v[142:143], v[142:143], v[174:175] op_sel_hi:[1,0]
	v_pk_mul_f32 v[144:145], v[144:145], v[174:175] op_sel_hi:[1,0]
	v_pk_mul_f32 v[146:147], v[146:147], v[174:175] op_sel_hi:[1,0]
	v_pk_mul_f32 v[148:149], v[148:149], v[174:175] op_sel_hi:[1,0]
	v_pk_mul_f32 v[150:151], v[150:151], v[174:175] op_sel_hi:[1,0]
	v_pk_fma_f32 v[136:137], v[136:137], v[0:1], v[16:17]
	v_pk_fma_f32 v[138:139], v[138:139], v[2:3], v[18:19]
	v_pk_fma_f32 v[140:141], v[140:141], v[4:5], v[20:21]
	v_pk_fma_f32 v[142:143], v[142:143], v[6:7], v[22:23]
	v_pk_fma_f32 v[144:145], v[144:145], v[8:9], v[24:25]
	v_pk_fma_f32 v[146:147], v[146:147], v[10:11], v[26:27]
	v_pk_fma_f32 v[148:149], v[148:149], v[12:13], v[28:29]
	v_pk_fma_f32 v[150:151], v[150:151], v[14:15], v[30:31]
	global_store_dwordx4 v176, v[136:139], s[8:9] offset:0
	global_store_dwordx4 v176, v[140:143], s[8:9] offset:1024
	global_store_dwordx4 v176, v[144:147], s[8:9] offset:2048
	global_store_dwordx4 v176, v[148:151], s[8:9] offset:3072
	v_pk_add_f32 v[152:153], v[136:137], v[138:139]
	v_pk_add_f32 v[152:153], v[152:153], v[140:141]
	v_pk_add_f32 v[152:153], v[152:153], v[142:143]
	v_pk_add_f32 v[152:153], v[152:153], v[144:145]
	v_pk_add_f32 v[152:153], v[152:153], v[146:147]
	v_pk_add_f32 v[152:153], v[152:153], v[148:149]
	v_pk_add_f32 v[152:153], v[152:153], v[150:151]
	v_add_f32_e32 v170, v152, v153
	s_nop 1
	v_add_f32_dpp v168, v170, v170 quad_perm:[1,0,3,2] row_mask:0xf bank_mask:0xf
	s_nop 1
	v_add_f32_dpp v168, v168, v168 quad_perm:[2,3,0,1] row_mask:0xf bank_mask:0xf
	s_nop 1
	v_add_f32_dpp v168, v168, v168 row_half_mirror row_mask:0xf bank_mask:0xf
	s_nop 1
	v_add_f32_dpp v168, v168, v168 row_mirror row_mask:0xf bank_mask:0xf
	s_nop 1
	v_add_f32_dpp v168, v168, v168 row_bcast:15 row_mask:0xa bank_mask:0xf
	s_nop 1
	v_add_f32_dpp v168, v168, v168 row_bcast:31 row_mask:0xc bank_mask:0xf
	s_nop 1
	v_readlane_b32 s42, v168, 63
	s_nop 3
	s_mov_b32 s43, s42
	v_pk_fma_f32 v[136:137], s[42:43], v[172:173], v[136:137]
	v_pk_fma_f32 v[138:139], s[42:43], v[172:173], v[138:139]
	v_pk_fma_f32 v[140:141], s[42:43], v[172:173], v[140:141]
	v_pk_fma_f32 v[142:143], s[42:43], v[172:173], v[142:143]
	v_pk_fma_f32 v[144:145], s[42:43], v[172:173], v[144:145]
	v_pk_fma_f32 v[146:147], s[42:43], v[172:173], v[146:147]
	v_pk_fma_f32 v[148:149], s[42:43], v[172:173], v[148:149]
	v_pk_fma_f32 v[150:151], s[42:43], v[172:173], v[150:151]
	v_pk_mul_f32 v[152:153], v[136:137], v[136:137]
	v_pk_fma_f32 v[152:153], v[138:139], v[138:139], v[152:153]
	v_pk_fma_f32 v[152:153], v[140:141], v[140:141], v[152:153]
	v_pk_fma_f32 v[152:153], v[142:143], v[142:143], v[152:153]
	v_pk_fma_f32 v[152:153], v[144:145], v[144:145], v[152:153]
	v_pk_fma_f32 v[152:153], v[146:147], v[146:147], v[152:153]
	v_pk_fma_f32 v[152:153], v[148:149], v[148:149], v[152:153]
	v_pk_fma_f32 v[152:153], v[150:151], v[150:151], v[152:153]
	v_add_f32_e32 v170, v152, v153
	s_nop 1
	v_add_f32_dpp v168, v170, v170 quad_perm:[1,0,3,2] row_mask:0xf bank_mask:0xf
	s_nop 1
	v_add_f32_dpp v168, v168, v168 quad_perm:[2,3,0,1] row_mask:0xf bank_mask:0xf
	s_nop 1
	v_add_f32_dpp v168, v168, v168 row_half_mirror row_mask:0xf bank_mask:0xf
	s_nop 1
	v_add_f32_dpp v168, v168, v168 row_mirror row_mask:0xf bank_mask:0xf
	s_nop 1
	v_add_f32_dpp v168, v168, v168 row_bcast:15 row_mask:0xa bank_mask:0xf
	s_nop 1
	v_add_f32_dpp v168, v168, v168 row_bcast:31 row_mask:0xc bank_mask:0xf
	s_nop 1
	v_readlane_b32 s42, v168, 63
	s_nop 3
	v_fma_f32 v174, s42, v178, v179
	v_rsq_f32_e32 v174, v174
	s_nop 0
	v_pk_mul_f32 v[136:137], v[136:137], v[174:175] op_sel_hi:[1,0]
	v_pk_mul_f32 v[138:139], v[138:139], v[174:175] op_sel_hi:[1,0]
	v_pk_mul_f32 v[140:141], v[140:141], v[174:175] op_sel_hi:[1,0]
	v_pk_mul_f32 v[142:143], v[142:143], v[174:175] op_sel_hi:[1,0]
	v_pk_mul_f32 v[144:145], v[144:145], v[174:175] op_sel_hi:[1,0]
	v_pk_mul_f32 v[146:147], v[146:147], v[174:175] op_sel_hi:[1,0]
	v_pk_mul_f32 v[148:149], v[148:149], v[174:175] op_sel_hi:[1,0]
	v_pk_mul_f32 v[150:151], v[150:151], v[174:175] op_sel_hi:[1,0]
	v_pk_fma_f32 v[136:137], v[136:137], v[32:33], v[48:49]
	v_pk_fma_f32 v[138:139], v[138:139], v[34:35], v[50:51]
	v_pk_fma_f32 v[140:141], v[140:141], v[36:37], v[52:53]
	v_pk_fma_f32 v[142:143], v[142:143], v[38:39], v[54:55]
	v_pk_fma_f32 v[144:145], v[144:145], v[40:41], v[56:57]
	v_pk_fma_f32 v[146:147], v[146:147], v[42:43], v[58:59]
	v_pk_fma_f32 v[148:149], v[148:149], v[44:45], v[60:61]
	v_pk_fma_f32 v[150:151], v[150:151], v[46:47], v[62:63]
	v_cvt_pk_bf16_f32 v152, v136, v137
	v_cvt_pk_bf16_f32 v153, v138, v139
	v_cvt_pk_bf16_f32 v154, v140, v141
	v_cvt_pk_bf16_f32 v155, v142, v143
	v_cvt_pk_bf16_f32 v156, v144, v145
	v_cvt_pk_bf16_f32 v157, v146, v147
	v_cvt_pk_bf16_f32 v158, v148, v149
	v_cvt_pk_bf16_f32 v159, v150, v151
	global_store_dwordx2 v177, v[152:153], s[12:13] offset:0
	global_store_dwordx2 v177, v[154:155], s[12:13] offset:512
	global_store_dwordx2 v177, v[156:157], s[12:13] offset:1024
	global_store_dwordx2 v177, v[158:159], s[12:13] offset:1536
	s_add_u32 s8, s8, 0x1000
	s_addc_u32 s9, s9, 0
	s_add_u32 s12, s12, 0x800
	s_addc_u32 s13, s13, 0
	global_load_dwordx4 v[64:67], v176, s[2:3] offset:0
	global_load_dwordx4 v[68:71], v176, s[2:3] offset:1024
	global_load_dwordx4 v[72:75], v176, s[2:3] offset:2048
	global_load_dwordx4 v[76:79], v176, s[2:3] offset:3072
	global_load_dwordx2 v[112:113], v177, s[6:7] offset:0
	global_load_dwordx2 v[114:115], v177, s[6:7] offset:512
	global_load_dwordx2 v[116:117], v177, s[6:7] offset:1024
	global_load_dwordx2 v[118:119], v177, s[6:7] offset:1536
	s_add_u32 s2, s2, 0x1000
	s_addc_u32 s3, s3, 0
	s_add_u32 s6, s6, 0x800
	s_addc_u32 s7, s7, 0
	s_waitcnt vmcnt(32)
	v_lshlrev_b32_e32 v136, 16, v120
	v_and_b32_e32 v137, 0xffff0000, v120
	v_lshlrev_b32_e32 v138, 16, v121
	v_and_b32_e32 v139, 0xffff0000, v121
	v_lshlrev_b32_e32 v140, 16, v122
	v_and_b32_e32 v141, 0xffff0000, v122
	v_lshlrev_b32_e32 v142, 16, v123
	v_and_b32_e32 v143, 0xffff0000, v123
	v_lshlrev_b32_e32 v144, 16, v124
	v_and_b32_e32 v145, 0xffff0000, v124
	v_lshlrev_b32_e32 v146, 16, v125
	v_and_b32_e32 v147, 0xffff0000, v125
	v_lshlrev_b32_e32 v148, 16, v126
	v_and_b32_e32 v149, 0xffff0000, v126
	v_lshlrev_b32_e32 v150, 16, v127
	v_and_b32_e32 v151, 0xffff0000, v127
	v_pk_fma_f32 v[136:137], v[80:81], s[44:45], v[136:137]
	v_pk_fma_f32 v[138:139], v[82:83], s[44:45], v[138:139]
	v_pk_fma_f32 v[140:141], v[84:85], s[44:45], v[140:141]
	v_pk_fma_f32 v[142:143], v[86:87], s[44:45], v[142:143]
	v_pk_fma_f32 v[144:145], v[88:89], s[44:45], v[144:145]
	v_pk_fma_f32 v[146:147], v[90:91], s[44:45], v[146:147]
	v_pk_fma_f32 v[148:149], v[92:93], s[44:45], v[148:149]
	v_pk_fma_f32 v[150:151], v[94:95], s[44:45], v[150:151]
	v_pk_add_f32 v[152:153], v[136:137], v[138:139]
	v_pk_add_f32 v[152:153], v[152:153], v[140:141]
	v_pk_add_f32 v[152:153], v[152:153], v[142:143]
	v_pk_add_f32 v[152:153], v[152:153], v[144:145]
	v_pk_add_f32 v[152:153], v[152:153], v[146:147]
	v_pk_add_f32 v[152:153], v[152:153], v[148:149]
	v_pk_add_f32 v[152:153], v[152:153], v[150:151]
	v_add_f32_e32 v170, v152, v153
	s_nop 1
	v_add_f32_dpp v168, v170, v170 quad_perm:[1,0,3,2] row_mask:0xf bank_mask:0xf
	s_nop 1
	v_add_f32_dpp v168, v168, v168 quad_perm:[2,3,0,1] row_mask:0xf bank_mask:0xf
	s_nop 1
	v_add_f32_dpp v168, v168, v168 row_half_mirror row_mask:0xf bank_mask:0xf
	s_nop 1
	v_add_f32_dpp v168, v168, v168 row_mirror row_mask:0xf bank_mask:0xf
	s_nop 1
	v_add_f32_dpp v168, v168, v168 row_bcast:15 row_mask:0xa bank_mask:0xf
	s_nop 1
	v_add_f32_dpp v168, v168, v168 row_bcast:31 row_mask:0xc bank_mask:0xf
	s_nop 1
	v_readlane_b32 s42, v168, 63
	s_nop 3
	s_mov_b32 s43, s42
	v_pk_fma_f32 v[136:137], s[42:43], v[172:173], v[136:137]
	v_pk_fma_f32 v[138:139], s[42:43], v[172:173], v[138:139]
	v_pk_fma_f32 v[140:141], s[42:43], v[172:173], v[140:141]
	v_pk_fma_f32 v[142:143], s[42:43], v[172:173], v[142:143]
	v_pk_fma_f32 v[144:145], s[42:43], v[172:173], v[144:145]
	v_pk_fma_f32 v[146:147], s[42:43], v[172:173], v[146:147]
	v_pk_fma_f32 v[148:149], s[42:43], v[172:173], v[148:149]
	v_pk_fma_f32 v[150:151], s[42:43], v[172:173], v[150:151]
	v_pk_mul_f32 v[152:153], v[136:137], v[136:137]
	v_pk_fma_f32 v[152:153], v[138:139], v[138:139], v[152:153]
	v_pk_fma_f32 v[152:153], v[140:141], v[140:141], v[152:153]
	v_pk_fma_f32 v[152:153], v[142:143], v[142:143], v[152:153]
	v_pk_fma_f32 v[152:153], v[144:145], v[144:145], v[152:153]
	v_pk_fma_f32 v[152:153], v[146:147], v[146:147], v[152:153]
	v_pk_fma_f32 v[152:153], v[148:149], v[148:149], v[152:153]
	v_pk_fma_f32 v[152:153], v[150:151], v[150:151], v[152:153]
	v_add_f32_e32 v170, v152, v153
	s_nop 1
	v_add_f32_dpp v168, v170, v170 quad_perm:[1,0,3,2] row_mask:0xf bank_mask:0xf
	s_nop 1
	v_add_f32_dpp v168, v168, v168 quad_perm:[2,3,0,1] row_mask:0xf bank_mask:0xf
	s_nop 1
	v_add_f32_dpp v168, v168, v168 row_half_mirror row_mask:0xf bank_mask:0xf
	s_nop 1
	v_add_f32_dpp v168, v168, v168 row_mirror row_mask:0xf bank_mask:0xf
	s_nop 1
	v_add_f32_dpp v168, v168, v168 row_bcast:15 row_mask:0xa bank_mask:0xf
	s_nop 1
	v_add_f32_dpp v168, v168, v168 row_bcast:31 row_mask:0xc bank_mask:0xf
	s_nop 1
	v_readlane_b32 s42, v168, 63
	s_nop 3
	v_fma_f32 v174, s42, v178, v179
	v_rsq_f32_e32 v174, v174
	s_nop 0
	v_pk_mul_f32 v[136:137], v[136:137], v[174:175] op_sel_hi:[1,0]
	v_pk_mul_f32 v[138:139], v[138:139], v[174:175] op_sel_hi:[1,0]
	v_pk_mul_f32 v[140:141], v[140:141], v[174:175] op_sel_hi:[1,0]
	v_pk_mul_f32 v[142:143], v[142:143], v[174:175] op_sel_hi:[1,0]
	v_pk_mul_f32 v[144:145], v[144:145], v[174:175] op_sel_hi:[1,0]
	v_pk_mul_f32 v[146:147], v[146:147], v[174:175] op_sel_hi:[1,0]
	v_pk_mul_f32 v[148:149], v[148:149], v[174:175] op_sel_hi:[1,0]
	v_pk_mul_f32 v[150:151], v[150:151], v[174:175] op_sel_hi:[1,0]
	v_pk_fma_f32 v[136:137], v[136:137], v[0:1], v[16:17]
	v_pk_fma_f32 v[138:139], v[138:139], v[2:3], v[18:19]
	v_pk_fma_f32 v[140:141], v[140:141], v[4:5], v[20:21]
	v_pk_fma_f32 v[142:143], v[142:143], v[6:7], v[22:23]
	v_pk_fma_f32 v[144:145], v[144:145], v[8:9], v[24:25]
	v_pk_fma_f32 v[146:147], v[146:147], v[10:11], v[26:27]
	v_pk_fma_f32 v[148:149], v[148:149], v[12:13], v[28:29]
	v_pk_fma_f32 v[150:151], v[150:151], v[14:15], v[30:31]
	global_store_dwordx4 v176, v[136:139], s[8:9] offset:0
	global_store_dwordx4 v176, v[140:143], s[8:9] offset:1024
	global_store_dwordx4 v176, v[144:147], s[8:9] offset:2048
	global_store_dwordx4 v176, v[148:151], s[8:9] offset:3072
	v_pk_add_f32 v[152:153], v[136:137], v[138:139]
	v_pk_add_f32 v[152:153], v[152:153], v[140:141]
	v_pk_add_f32 v[152:153], v[152:153], v[142:143]
	v_pk_add_f32 v[152:153], v[152:153], v[144:145]
	v_pk_add_f32 v[152:153], v[152:153], v[146:147]
	v_pk_add_f32 v[152:153], v[152:153], v[148:149]
	v_pk_add_f32 v[152:153], v[152:153], v[150:151]
	v_add_f32_e32 v170, v152, v153
	s_nop 1
	v_add_f32_dpp v168, v170, v170 quad_perm:[1,0,3,2] row_mask:0xf bank_mask:0xf
	s_nop 1
	v_add_f32_dpp v168, v168, v168 quad_perm:[2,3,0,1] row_mask:0xf bank_mask:0xf
	s_nop 1
	v_add_f32_dpp v168, v168, v168 row_half_mirror row_mask:0xf bank_mask:0xf
	s_nop 1
	v_add_f32_dpp v168, v168, v168 row_mirror row_mask:0xf bank_mask:0xf
	s_nop 1
	v_add_f32_dpp v168, v168, v168 row_bcast:15 row_mask:0xa bank_mask:0xf
	s_nop 1
	v_add_f32_dpp v168, v168, v168 row_bcast:31 row_mask:0xc bank_mask:0xf
	s_nop 1
	v_readlane_b32 s42, v168, 63
	s_nop 3
	s_mov_b32 s43, s42
	v_pk_fma_f32 v[136:137], s[42:43], v[172:173], v[136:137]
	v_pk_fma_f32 v[138:139], s[42:43], v[172:173], v[138:139]
	v_pk_fma_f32 v[140:141], s[42:43], v[172:173], v[140:141]
	v_pk_fma_f32 v[142:143], s[42:43], v[172:173], v[142:143]
	v_pk_fma_f32 v[144:145], s[42:43], v[172:173], v[144:145]
	v_pk_fma_f32 v[146:147], s[42:43], v[172:173], v[146:147]
	v_pk_fma_f32 v[148:149], s[42:43], v[172:173], v[148:149]
	v_pk_fma_f32 v[150:151], s[42:43], v[172:173], v[150:151]
	v_pk_mul_f32 v[152:153], v[136:137], v[136:137]
	v_pk_fma_f32 v[152:153], v[138:139], v[138:139], v[152:153]
	v_pk_fma_f32 v[152:153], v[140:141], v[140:141], v[152:153]
	v_pk_fma_f32 v[152:153], v[142:143], v[142:143], v[152:153]
	v_pk_fma_f32 v[152:153], v[144:145], v[144:145], v[152:153]
	v_pk_fma_f32 v[152:153], v[146:147], v[146:147], v[152:153]
	v_pk_fma_f32 v[152:153], v[148:149], v[148:149], v[152:153]
	v_pk_fma_f32 v[152:153], v[150:151], v[150:151], v[152:153]
	v_add_f32_e32 v170, v152, v153
	s_nop 1
	v_add_f32_dpp v168, v170, v170 quad_perm:[1,0,3,2] row_mask:0xf bank_mask:0xf
	s_nop 1
	v_add_f32_dpp v168, v168, v168 quad_perm:[2,3,0,1] row_mask:0xf bank_mask:0xf
	s_nop 1
	v_add_f32_dpp v168, v168, v168 row_half_mirror row_mask:0xf bank_mask:0xf
	s_nop 1
	v_add_f32_dpp v168, v168, v168 row_mirror row_mask:0xf bank_mask:0xf
	s_nop 1
	v_add_f32_dpp v168, v168, v168 row_bcast:15 row_mask:0xa bank_mask:0xf
	s_nop 1
	v_add_f32_dpp v168, v168, v168 row_bcast:31 row_mask:0xc bank_mask:0xf
	s_nop 1
	v_readlane_b32 s42, v168, 63
	s_nop 3
	v_fma_f32 v174, s42, v178, v179
	v_rsq_f32_e32 v174, v174
	s_nop 0
	v_pk_mul_f32 v[136:137], v[136:137], v[174:175] op_sel_hi:[1,0]
	v_pk_mul_f32 v[138:139], v[138:139], v[174:175] op_sel_hi:[1,0]
	v_pk_mul_f32 v[140:141], v[140:141], v[174:175] op_sel_hi:[1,0]
	v_pk_mul_f32 v[142:143], v[142:143], v[174:175] op_sel_hi:[1,0]
	v_pk_mul_f32 v[144:145], v[144:145], v[174:175] op_sel_hi:[1,0]
	v_pk_mul_f32 v[146:147], v[146:147], v[174:175] op_sel_hi:[1,0]
	v_pk_mul_f32 v[148:149], v[148:149], v[174:175] op_sel_hi:[1,0]
	v_pk_mul_f32 v[150:151], v[150:151], v[174:175] op_sel_hi:[1,0]
	v_pk_fma_f32 v[136:137], v[136:137], v[32:33], v[48:49]
	v_pk_fma_f32 v[138:139], v[138:139], v[34:35], v[50:51]
	v_pk_fma_f32 v[140:141], v[140:141], v[36:37], v[52:53]
	v_pk_fma_f32 v[142:143], v[142:143], v[38:39], v[54:55]
	v_pk_fma_f32 v[144:145], v[144:145], v[40:41], v[56:57]
	v_pk_fma_f32 v[146:147], v[146:147], v[42:43], v[58:59]
	v_pk_fma_f32 v[148:149], v[148:149], v[44:45], v[60:61]
	v_pk_fma_f32 v[150:151], v[150:151], v[46:47], v[62:63]
	v_cvt_pk_bf16_f32 v152, v136, v137
	v_cvt_pk_bf16_f32 v153, v138, v139
	v_cvt_pk_bf16_f32 v154, v140, v141
	v_cvt_pk_bf16_f32 v155, v142, v143
	v_cvt_pk_bf16_f32 v156, v144, v145
	v_cvt_pk_bf16_f32 v157, v146, v147
	v_cvt_pk_bf16_f32 v158, v148, v149
	v_cvt_pk_bf16_f32 v159, v150, v151
	global_store_dwordx2 v177, v[152:153], s[12:13] offset:0
	global_store_dwordx2 v177, v[154:155], s[12:13] offset:512
	global_store_dwordx2 v177, v[156:157], s[12:13] offset:1024
	global_store_dwordx2 v177, v[158:159], s[12:13] offset:1536
	s_add_u32 s8, s8, 0x1000
	s_addc_u32 s9, s9, 0
	s_add_u32 s12, s12, 0x800
	s_addc_u32 s13, s13, 0
	global_load_dwordx4 v[80:83], v176, s[2:3] offset:0
	global_load_dwordx4 v[84:87], v176, s[2:3] offset:1024
	global_load_dwordx4 v[88:91], v176, s[2:3] offset:2048
	global_load_dwordx4 v[92:95], v176, s[2:3] offset:3072
	global_load_dwordx2 v[120:121], v177, s[6:7] offset:0
	global_load_dwordx2 v[122:123], v177, s[6:7] offset:512
	global_load_dwordx2 v[124:125], v177, s[6:7] offset:1024
	global_load_dwordx2 v[126:127], v177, s[6:7] offset:1536
	s_add_u32 s2, s2, 0x1000
	s_addc_u32 s3, s3, 0
	s_add_u32 s6, s6, 0x800
	s_addc_u32 s7, s7, 0
	s_waitcnt vmcnt(32)
	v_lshlrev_b32_e32 v136, 16, v128
	v_and_b32_e32 v137, 0xffff0000, v128
	v_lshlrev_b32_e32 v138, 16, v129
	v_and_b32_e32 v139, 0xffff0000, v129
	v_lshlrev_b32_e32 v140, 16, v130
	v_and_b32_e32 v141, 0xffff0000, v130
	v_lshlrev_b32_e32 v142, 16, v131
	v_and_b32_e32 v143, 0xffff0000, v131
	v_lshlrev_b32_e32 v144, 16, v132
	v_and_b32_e32 v145, 0xffff0000, v132
	v_lshlrev_b32_e32 v146, 16, v133
	v_and_b32_e32 v147, 0xffff0000, v133
	v_lshlrev_b32_e32 v148, 16, v134
	v_and_b32_e32 v149, 0xffff0000, v134
	v_lshlrev_b32_e32 v150, 16, v135
	v_and_b32_e32 v151, 0xffff0000, v135
	v_pk_fma_f32 v[136:137], v[96:97], s[44:45], v[136:137]
	v_pk_fma_f32 v[138:139], v[98:99], s[44:45], v[138:139]
	v_pk_fma_f32 v[140:141], v[100:101], s[44:45], v[140:141]
	v_pk_fma_f32 v[142:143], v[102:103], s[44:45], v[142:143]
	v_pk_fma_f32 v[144:145], v[104:105], s[44:45], v[144:145]
	v_pk_fma_f32 v[146:147], v[106:107], s[44:45], v[146:147]
	v_pk_fma_f32 v[148:149], v[108:109], s[44:45], v[148:149]
	v_pk_fma_f32 v[150:151], v[110:111], s[44:45], v[150:151]
	v_pk_add_f32 v[152:153], v[136:137], v[138:139]
	v_pk_add_f32 v[152:153], v[152:153], v[140:141]
	v_pk_add_f32 v[152:153], v[152:153], v[142:143]
	v_pk_add_f32 v[152:153], v[152:153], v[144:145]
	v_pk_add_f32 v[152:153], v[152:153], v[146:147]
	v_pk_add_f32 v[152:153], v[152:153], v[148:149]
	v_pk_add_f32 v[152:153], v[152:153], v[150:151]
	v_add_f32_e32 v170, v152, v153
	s_nop 1
	v_add_f32_dpp v168, v170, v170 quad_perm:[1,0,3,2] row_mask:0xf bank_mask:0xf
	s_nop 1
	v_add_f32_dpp v168, v168, v168 quad_perm:[2,3,0,1] row_mask:0xf bank_mask:0xf
	s_nop 1
	v_add_f32_dpp v168, v168, v168 row_half_mirror row_mask:0xf bank_mask:0xf
	s_nop 1
	v_add_f32_dpp v168, v168, v168 row_mirror row_mask:0xf bank_mask:0xf
	s_nop 1
	v_add_f32_dpp v168, v168, v168 row_bcast:15 row_mask:0xa bank_mask:0xf
	s_nop 1
	v_add_f32_dpp v168, v168, v168 row_bcast:31 row_mask:0xc bank_mask:0xf
	s_nop 1
	v_readlane_b32 s42, v168, 63
	s_nop 3
	s_mov_b32 s43, s42
	v_pk_fma_f32 v[136:137], s[42:43], v[172:173], v[136:137]
	v_pk_fma_f32 v[138:139], s[42:43], v[172:173], v[138:139]
	v_pk_fma_f32 v[140:141], s[42:43], v[172:173], v[140:141]
	v_pk_fma_f32 v[142:143], s[42:43], v[172:173], v[142:143]
	v_pk_fma_f32 v[144:145], s[42:43], v[172:173], v[144:145]
	v_pk_fma_f32 v[146:147], s[42:43], v[172:173], v[146:147]
	v_pk_fma_f32 v[148:149], s[42:43], v[172:173], v[148:149]
	v_pk_fma_f32 v[150:151], s[42:43], v[172:173], v[150:151]
	v_pk_mul_f32 v[152:153], v[136:137], v[136:137]
	v_pk_fma_f32 v[152:153], v[138:139], v[138:139], v[152:153]
	v_pk_fma_f32 v[152:153], v[140:141], v[140:141], v[152:153]
	v_pk_fma_f32 v[152:153], v[142:143], v[142:143], v[152:153]
	v_pk_fma_f32 v[152:153], v[144:145], v[144:145], v[152:153]
	v_pk_fma_f32 v[152:153], v[146:147], v[146:147], v[152:153]
	v_pk_fma_f32 v[152:153], v[148:149], v[148:149], v[152:153]
	v_pk_fma_f32 v[152:153], v[150:151], v[150:151], v[152:153]
	v_add_f32_e32 v170, v152, v153
	s_nop 1
	v_add_f32_dpp v168, v170, v170 quad_perm:[1,0,3,2] row_mask:0xf bank_mask:0xf
	s_nop 1
	v_add_f32_dpp v168, v168, v168 quad_perm:[2,3,0,1] row_mask:0xf bank_mask:0xf
	s_nop 1
	v_add_f32_dpp v168, v168, v168 row_half_mirror row_mask:0xf bank_mask:0xf
	s_nop 1
	v_add_f32_dpp v168, v168, v168 row_mirror row_mask:0xf bank_mask:0xf
	s_nop 1
	v_add_f32_dpp v168, v168, v168 row_bcast:15 row_mask:0xa bank_mask:0xf
	s_nop 1
	v_add_f32_dpp v168, v168, v168 row_bcast:31 row_mask:0xc bank_mask:0xf
	s_nop 1
	v_readlane_b32 s42, v168, 63
	s_nop 3
	v_fma_f32 v174, s42, v178, v179
	v_rsq_f32_e32 v174, v174
	s_nop 0
	v_pk_mul_f32 v[136:137], v[136:137], v[174:175] op_sel_hi:[1,0]
	v_pk_mul_f32 v[138:139], v[138:139], v[174:175] op_sel_hi:[1,0]
	v_pk_mul_f32 v[140:141], v[140:141], v[174:175] op_sel_hi:[1,0]
	v_pk_mul_f32 v[142:143], v[142:143], v[174:175] op_sel_hi:[1,0]
	v_pk_mul_f32 v[144:145], v[144:145], v[174:175] op_sel_hi:[1,0]
	v_pk_mul_f32 v[146:147], v[146:147], v[174:175] op_sel_hi:[1,0]
	v_pk_mul_f32 v[148:149], v[148:149], v[174:175] op_sel_hi:[1,0]
	v_pk_mul_f32 v[150:151], v[150:151], v[174:175] op_sel_hi:[1,0]
	v_pk_fma_f32 v[136:137], v[136:137], v[0:1], v[16:17]
	v_pk_fma_f32 v[138:139], v[138:139], v[2:3], v[18:19]
	v_pk_fma_f32 v[140:141], v[140:141], v[4:5], v[20:21]
	v_pk_fma_f32 v[142:143], v[142:143], v[6:7], v[22:23]
	v_pk_fma_f32 v[144:145], v[144:145], v[8:9], v[24:25]
	v_pk_fma_f32 v[146:147], v[146:147], v[10:11], v[26:27]
	v_pk_fma_f32 v[148:149], v[148:149], v[12:13], v[28:29]
	v_pk_fma_f32 v[150:151], v[150:151], v[14:15], v[30:31]
	global_store_dwordx4 v176, v[136:139], s[8:9] offset:0
	global_store_dwordx4 v176, v[140:143], s[8:9] offset:1024
	global_store_dwordx4 v176, v[144:147], s[8:9] offset:2048
	global_store_dwordx4 v176, v[148:151], s[8:9] offset:3072
	v_pk_add_f32 v[152:153], v[136:137], v[138:139]
	v_pk_add_f32 v[152:153], v[152:153], v[140:141]
	v_pk_add_f32 v[152:153], v[152:153], v[142:143]
	v_pk_add_f32 v[152:153], v[152:153], v[144:145]
	v_pk_add_f32 v[152:153], v[152:153], v[146:147]
	v_pk_add_f32 v[152:153], v[152:153], v[148:149]
	v_pk_add_f32 v[152:153], v[152:153], v[150:151]
	v_add_f32_e32 v170, v152, v153
	s_nop 1
	v_add_f32_dpp v168, v170, v170 quad_perm:[1,0,3,2] row_mask:0xf bank_mask:0xf
	s_nop 1
	v_add_f32_dpp v168, v168, v168 quad_perm:[2,3,0,1] row_mask:0xf bank_mask:0xf
	s_nop 1
	v_add_f32_dpp v168, v168, v168 row_half_mirror row_mask:0xf bank_mask:0xf
	s_nop 1
	v_add_f32_dpp v168, v168, v168 row_mirror row_mask:0xf bank_mask:0xf
	s_nop 1
	v_add_f32_dpp v168, v168, v168 row_bcast:15 row_mask:0xa bank_mask:0xf
	s_nop 1
	v_add_f32_dpp v168, v168, v168 row_bcast:31 row_mask:0xc bank_mask:0xf
	s_nop 1
	v_readlane_b32 s42, v168, 63
	s_nop 3
	s_mov_b32 s43, s42
	v_pk_fma_f32 v[136:137], s[42:43], v[172:173], v[136:137]
	v_pk_fma_f32 v[138:139], s[42:43], v[172:173], v[138:139]
	v_pk_fma_f32 v[140:141], s[42:43], v[172:173], v[140:141]
	v_pk_fma_f32 v[142:143], s[42:43], v[172:173], v[142:143]
	v_pk_fma_f32 v[144:145], s[42:43], v[172:173], v[144:145]
	v_pk_fma_f32 v[146:147], s[42:43], v[172:173], v[146:147]
	v_pk_fma_f32 v[148:149], s[42:43], v[172:173], v[148:149]
	v_pk_fma_f32 v[150:151], s[42:43], v[172:173], v[150:151]
	v_pk_mul_f32 v[152:153], v[136:137], v[136:137]
	v_pk_fma_f32 v[152:153], v[138:139], v[138:139], v[152:153]
	v_pk_fma_f32 v[152:153], v[140:141], v[140:141], v[152:153]
	v_pk_fma_f32 v[152:153], v[142:143], v[142:143], v[152:153]
	v_pk_fma_f32 v[152:153], v[144:145], v[144:145], v[152:153]
	v_pk_fma_f32 v[152:153], v[146:147], v[146:147], v[152:153]
	v_pk_fma_f32 v[152:153], v[148:149], v[148:149], v[152:153]
	v_pk_fma_f32 v[152:153], v[150:151], v[150:151], v[152:153]
	v_add_f32_e32 v170, v152, v153
	s_nop 1
	v_add_f32_dpp v168, v170, v170 quad_perm:[1,0,3,2] row_mask:0xf bank_mask:0xf
	s_nop 1
	v_add_f32_dpp v168, v168, v168 quad_perm:[2,3,0,1] row_mask:0xf bank_mask:0xf
	s_nop 1
	v_add_f32_dpp v168, v168, v168 row_half_mirror row_mask:0xf bank_mask:0xf
	s_nop 1
	v_add_f32_dpp v168, v168, v168 row_mirror row_mask:0xf bank_mask:0xf
	s_nop 1
	v_add_f32_dpp v168, v168, v168 row_bcast:15 row_mask:0xa bank_mask:0xf
	s_nop 1
	v_add_f32_dpp v168, v168, v168 row_bcast:31 row_mask:0xc bank_mask:0xf
	s_nop 1
	v_readlane_b32 s42, v168, 63
	s_nop 3
	v_fma_f32 v174, s42, v178, v179
	v_rsq_f32_e32 v174, v174
	s_nop 0
	v_pk_mul_f32 v[136:137], v[136:137], v[174:175] op_sel_hi:[1,0]
	v_pk_mul_f32 v[138:139], v[138:139], v[174:175] op_sel_hi:[1,0]
	v_pk_mul_f32 v[140:141], v[140:141], v[174:175] op_sel_hi:[1,0]
	v_pk_mul_f32 v[142:143], v[142:143], v[174:175] op_sel_hi:[1,0]
	v_pk_mul_f32 v[144:145], v[144:145], v[174:175] op_sel_hi:[1,0]
	v_pk_mul_f32 v[146:147], v[146:147], v[174:175] op_sel_hi:[1,0]
	v_pk_mul_f32 v[148:149], v[148:149], v[174:175] op_sel_hi:[1,0]
	v_pk_mul_f32 v[150:151], v[150:151], v[174:175] op_sel_hi:[1,0]
	v_pk_fma_f32 v[136:137], v[136:137], v[32:33], v[48:49]
	v_pk_fma_f32 v[138:139], v[138:139], v[34:35], v[50:51]
	v_pk_fma_f32 v[140:141], v[140:141], v[36:37], v[52:53]
	v_pk_fma_f32 v[142:143], v[142:143], v[38:39], v[54:55]
	v_pk_fma_f32 v[144:145], v[144:145], v[40:41], v[56:57]
	v_pk_fma_f32 v[146:147], v[146:147], v[42:43], v[58:59]
	v_pk_fma_f32 v[148:149], v[148:149], v[44:45], v[60:61]
	v_pk_fma_f32 v[150:151], v[150:151], v[46:47], v[62:63]
	v_cvt_pk_bf16_f32 v152, v136, v137
	v_cvt_pk_bf16_f32 v153, v138, v139
	v_cvt_pk_bf16_f32 v154, v140, v141
	v_cvt_pk_bf16_f32 v155, v142, v143
	v_cvt_pk_bf16_f32 v156, v144, v145
	v_cvt_pk_bf16_f32 v157, v146, v147
	v_cvt_pk_bf16_f32 v158, v148, v149
	v_cvt_pk_bf16_f32 v159, v150, v151
	global_store_dwordx2 v177, v[152:153], s[12:13] offset:0
	global_store_dwordx2 v177, v[154:155], s[12:13] offset:512
	global_store_dwordx2 v177, v[156:157], s[12:13] offset:1024
	global_store_dwordx2 v177, v[158:159], s[12:13] offset:1536
	s_add_u32 s8, s8, 0x1000
	s_addc_u32 s9, s9, 0
	s_add_u32 s12, s12, 0x800
	s_addc_u32 s13, s13, 0
	global_load_dwordx4 v[96:99], v176, s[2:3] offset:0
	global_load_dwordx4 v[100:103], v176, s[2:3] offset:1024
	global_load_dwordx4 v[104:107], v176, s[2:3] offset:2048
	global_load_dwordx4 v[108:111], v176, s[2:3] offset:3072
	global_load_dwordx2 v[128:129], v177, s[6:7] offset:0
	global_load_dwordx2 v[130:131], v177, s[6:7] offset:512
	global_load_dwordx2 v[132:133], v177, s[6:7] offset:1024
	global_load_dwordx2 v[134:135], v177, s[6:7] offset:1536
	s_add_u32 s2, s2, 0x1000
	s_addc_u32 s3, s3, 0
	s_add_u32 s6, s6, 0x800
	s_addc_u32 s7, s7, 0
	s_waitcnt vmcnt(32)
	v_lshlrev_b32_e32 v136, 16, v112
	v_and_b32_e32 v137, 0xffff0000, v112
	v_lshlrev_b32_e32 v138, 16, v113
	v_and_b32_e32 v139, 0xffff0000, v113
	v_lshlrev_b32_e32 v140, 16, v114
	v_and_b32_e32 v141, 0xffff0000, v114
	v_lshlrev_b32_e32 v142, 16, v115
	v_and_b32_e32 v143, 0xffff0000, v115
	v_lshlrev_b32_e32 v144, 16, v116
	v_and_b32_e32 v145, 0xffff0000, v116
	v_lshlrev_b32_e32 v146, 16, v117
	v_and_b32_e32 v147, 0xffff0000, v117
	v_lshlrev_b32_e32 v148, 16, v118
	v_and_b32_e32 v149, 0xffff0000, v118
	v_lshlrev_b32_e32 v150, 16, v119
	v_and_b32_e32 v151, 0xffff0000, v119
	v_pk_fma_f32 v[136:137], v[64:65], s[44:45], v[136:137]
	v_pk_fma_f32 v[138:139], v[66:67], s[44:45], v[138:139]
	v_pk_fma_f32 v[140:141], v[68:69], s[44:45], v[140:141]
	v_pk_fma_f32 v[142:143], v[70:71], s[44:45], v[142:143]
	v_pk_fma_f32 v[144:145], v[72:73], s[44:45], v[144:145]
	v_pk_fma_f32 v[146:147], v[74:75], s[44:45], v[146:147]
	v_pk_fma_f32 v[148:149], v[76:77], s[44:45], v[148:149]
	v_pk_fma_f32 v[150:151], v[78:79], s[44:45], v[150:151]
	v_pk_add_f32 v[152:153], v[136:137], v[138:139]
	v_pk_add_f32 v[152:153], v[152:153], v[140:141]
	v_pk_add_f32 v[152:153], v[152:153], v[142:143]
	v_pk_add_f32 v[152:153], v[152:153], v[144:145]
	v_pk_add_f32 v[152:153], v[152:153], v[146:147]
	v_pk_add_f32 v[152:153], v[152:153], v[148:149]
	v_pk_add_f32 v[152:153], v[152:153], v[150:151]
	v_add_f32_e32 v170, v152, v153
	s_nop 1
	v_add_f32_dpp v168, v170, v170 quad_perm:[1,0,3,2] row_mask:0xf bank_mask:0xf
	s_nop 1
	v_add_f32_dpp v168, v168, v168 quad_perm:[2,3,0,1] row_mask:0xf bank_mask:0xf
	s_nop 1
	v_add_f32_dpp v168, v168, v168 row_half_mirror row_mask:0xf bank_mask:0xf
	s_nop 1
	v_add_f32_dpp v168, v168, v168 row_mirror row_mask:0xf bank_mask:0xf
	s_nop 1
	v_add_f32_dpp v168, v168, v168 row_bcast:15 row_mask:0xa bank_mask:0xf
	s_nop 1
	v_add_f32_dpp v168, v168, v168 row_bcast:31 row_mask:0xc bank_mask:0xf
	s_nop 1
	v_readlane_b32 s42, v168, 63
	s_nop 3
	s_mov_b32 s43, s42
	v_pk_fma_f32 v[136:137], s[42:43], v[172:173], v[136:137]
	v_pk_fma_f32 v[138:139], s[42:43], v[172:173], v[138:139]
	v_pk_fma_f32 v[140:141], s[42:43], v[172:173], v[140:141]
	v_pk_fma_f32 v[142:143], s[42:43], v[172:173], v[142:143]
	v_pk_fma_f32 v[144:145], s[42:43], v[172:173], v[144:145]
	v_pk_fma_f32 v[146:147], s[42:43], v[172:173], v[146:147]
	v_pk_fma_f32 v[148:149], s[42:43], v[172:173], v[148:149]
	v_pk_fma_f32 v[150:151], s[42:43], v[172:173], v[150:151]
	v_pk_mul_f32 v[152:153], v[136:137], v[136:137]
	v_pk_fma_f32 v[152:153], v[138:139], v[138:139], v[152:153]
	v_pk_fma_f32 v[152:153], v[140:141], v[140:141], v[152:153]
	v_pk_fma_f32 v[152:153], v[142:143], v[142:143], v[152:153]
	v_pk_fma_f32 v[152:153], v[144:145], v[144:145], v[152:153]
	v_pk_fma_f32 v[152:153], v[146:147], v[146:147], v[152:153]
	v_pk_fma_f32 v[152:153], v[148:149], v[148:149], v[152:153]
	v_pk_fma_f32 v[152:153], v[150:151], v[150:151], v[152:153]
	v_add_f32_e32 v170, v152, v153
	s_nop 1
	v_add_f32_dpp v168, v170, v170 quad_perm:[1,0,3,2] row_mask:0xf bank_mask:0xf
	s_nop 1
	v_add_f32_dpp v168, v168, v168 quad_perm:[2,3,0,1] row_mask:0xf bank_mask:0xf
	s_nop 1
	v_add_f32_dpp v168, v168, v168 row_half_mirror row_mask:0xf bank_mask:0xf
	s_nop 1
	v_add_f32_dpp v168, v168, v168 row_mirror row_mask:0xf bank_mask:0xf
	s_nop 1
	v_add_f32_dpp v168, v168, v168 row_bcast:15 row_mask:0xa bank_mask:0xf
	s_nop 1
	v_add_f32_dpp v168, v168, v168 row_bcast:31 row_mask:0xc bank_mask:0xf
	s_nop 1
	v_readlane_b32 s42, v168, 63
	s_nop 3
	v_fma_f32 v174, s42, v178, v179
	v_rsq_f32_e32 v174, v174
	s_nop 0
	v_pk_mul_f32 v[136:137], v[136:137], v[174:175] op_sel_hi:[1,0]
	v_pk_mul_f32 v[138:139], v[138:139], v[174:175] op_sel_hi:[1,0]
	v_pk_mul_f32 v[140:141], v[140:141], v[174:175] op_sel_hi:[1,0]
	v_pk_mul_f32 v[142:143], v[142:143], v[174:175] op_sel_hi:[1,0]
	v_pk_mul_f32 v[144:145], v[144:145], v[174:175] op_sel_hi:[1,0]
	v_pk_mul_f32 v[146:147], v[146:147], v[174:175] op_sel_hi:[1,0]
	v_pk_mul_f32 v[148:149], v[148:149], v[174:175] op_sel_hi:[1,0]
	v_pk_mul_f32 v[150:151], v[150:151], v[174:175] op_sel_hi:[1,0]
	v_pk_fma_f32 v[136:137], v[136:137], v[0:1], v[16:17]
	v_pk_fma_f32 v[138:139], v[138:139], v[2:3], v[18:19]
	v_pk_fma_f32 v[140:141], v[140:141], v[4:5], v[20:21]
	v_pk_fma_f32 v[142:143], v[142:143], v[6:7], v[22:23]
	v_pk_fma_f32 v[144:145], v[144:145], v[8:9], v[24:25]
	v_pk_fma_f32 v[146:147], v[146:147], v[10:11], v[26:27]
	v_pk_fma_f32 v[148:149], v[148:149], v[12:13], v[28:29]
	v_pk_fma_f32 v[150:151], v[150:151], v[14:15], v[30:31]
	global_store_dwordx4 v176, v[136:139], s[8:9] offset:0
	global_store_dwordx4 v176, v[140:143], s[8:9] offset:1024
	global_store_dwordx4 v176, v[144:147], s[8:9] offset:2048
	global_store_dwordx4 v176, v[148:151], s[8:9] offset:3072
	v_pk_add_f32 v[152:153], v[136:137], v[138:139]
	v_pk_add_f32 v[152:153], v[152:153], v[140:141]
	v_pk_add_f32 v[152:153], v[152:153], v[142:143]
	v_pk_add_f32 v[152:153], v[152:153], v[144:145]
	v_pk_add_f32 v[152:153], v[152:153], v[146:147]
	v_pk_add_f32 v[152:153], v[152:153], v[148:149]
	v_pk_add_f32 v[152:153], v[152:153], v[150:151]
	v_add_f32_e32 v170, v152, v153
	s_nop 1
	v_add_f32_dpp v168, v170, v170 quad_perm:[1,0,3,2] row_mask:0xf bank_mask:0xf
	s_nop 1
	v_add_f32_dpp v168, v168, v168 quad_perm:[2,3,0,1] row_mask:0xf bank_mask:0xf
	s_nop 1
	v_add_f32_dpp v168, v168, v168 row_half_mirror row_mask:0xf bank_mask:0xf
	s_nop 1
	v_add_f32_dpp v168, v168, v168 row_mirror row_mask:0xf bank_mask:0xf
	s_nop 1
	v_add_f32_dpp v168, v168, v168 row_bcast:15 row_mask:0xa bank_mask:0xf
	s_nop 1
	v_add_f32_dpp v168, v168, v168 row_bcast:31 row_mask:0xc bank_mask:0xf
	s_nop 1
	v_readlane_b32 s42, v168, 63
	s_nop 3
	s_mov_b32 s43, s42
	v_pk_fma_f32 v[136:137], s[42:43], v[172:173], v[136:137]
	v_pk_fma_f32 v[138:139], s[42:43], v[172:173], v[138:139]
	v_pk_fma_f32 v[140:141], s[42:43], v[172:173], v[140:141]
	v_pk_fma_f32 v[142:143], s[42:43], v[172:173], v[142:143]
	v_pk_fma_f32 v[144:145], s[42:43], v[172:173], v[144:145]
	v_pk_fma_f32 v[146:147], s[42:43], v[172:173], v[146:147]
	v_pk_fma_f32 v[148:149], s[42:43], v[172:173], v[148:149]
	v_pk_fma_f32 v[150:151], s[42:43], v[172:173], v[150:151]
	v_pk_mul_f32 v[152:153], v[136:137], v[136:137]
	v_pk_fma_f32 v[152:153], v[138:139], v[138:139], v[152:153]
	v_pk_fma_f32 v[152:153], v[140:141], v[140:141], v[152:153]
	v_pk_fma_f32 v[152:153], v[142:143], v[142:143], v[152:153]
	v_pk_fma_f32 v[152:153], v[144:145], v[144:145], v[152:153]
	v_pk_fma_f32 v[152:153], v[146:147], v[146:147], v[152:153]
	v_pk_fma_f32 v[152:153], v[148:149], v[148:149], v[152:153]
	v_pk_fma_f32 v[152:153], v[150:151], v[150:151], v[152:153]
	v_add_f32_e32 v170, v152, v153
	s_nop 1
	v_add_f32_dpp v168, v170, v170 quad_perm:[1,0,3,2] row_mask:0xf bank_mask:0xf
	s_nop 1
	v_add_f32_dpp v168, v168, v168 quad_perm:[2,3,0,1] row_mask:0xf bank_mask:0xf
	s_nop 1
	v_add_f32_dpp v168, v168, v168 row_half_mirror row_mask:0xf bank_mask:0xf
	s_nop 1
	v_add_f32_dpp v168, v168, v168 row_mirror row_mask:0xf bank_mask:0xf
	s_nop 1
	v_add_f32_dpp v168, v168, v168 row_bcast:15 row_mask:0xa bank_mask:0xf
	s_nop 1
	v_add_f32_dpp v168, v168, v168 row_bcast:31 row_mask:0xc bank_mask:0xf
	s_nop 1
	v_readlane_b32 s42, v168, 63
	s_nop 3
	v_fma_f32 v174, s42, v178, v179
	v_rsq_f32_e32 v174, v174
	s_nop 0
	v_pk_mul_f32 v[136:137], v[136:137], v[174:175] op_sel_hi:[1,0]
	v_pk_mul_f32 v[138:139], v[138:139], v[174:175] op_sel_hi:[1,0]
	v_pk_mul_f32 v[140:141], v[140:141], v[174:175] op_sel_hi:[1,0]
	v_pk_mul_f32 v[142:143], v[142:143], v[174:175] op_sel_hi:[1,0]
	v_pk_mul_f32 v[144:145], v[144:145], v[174:175] op_sel_hi:[1,0]
	v_pk_mul_f32 v[146:147], v[146:147], v[174:175] op_sel_hi:[1,0]
	v_pk_mul_f32 v[148:149], v[148:149], v[174:175] op_sel_hi:[1,0]
	v_pk_mul_f32 v[150:151], v[150:151], v[174:175] op_sel_hi:[1,0]
	v_pk_fma_f32 v[136:137], v[136:137], v[32:33], v[48:49]
	v_pk_fma_f32 v[138:139], v[138:139], v[34:35], v[50:51]
	v_pk_fma_f32 v[140:141], v[140:141], v[36:37], v[52:53]
	v_pk_fma_f32 v[142:143], v[142:143], v[38:39], v[54:55]
	v_pk_fma_f32 v[144:145], v[144:145], v[40:41], v[56:57]
	v_pk_fma_f32 v[146:147], v[146:147], v[42:43], v[58:59]
	v_pk_fma_f32 v[148:149], v[148:149], v[44:45], v[60:61]
	v_pk_fma_f32 v[150:151], v[150:151], v[46:47], v[62:63]
	v_cvt_pk_bf16_f32 v152, v136, v137
	v_cvt_pk_bf16_f32 v153, v138, v139
	v_cvt_pk_bf16_f32 v154, v140, v141
	v_cvt_pk_bf16_f32 v155, v142, v143
	v_cvt_pk_bf16_f32 v156, v144, v145
	v_cvt_pk_bf16_f32 v157, v146, v147
	v_cvt_pk_bf16_f32 v158, v148, v149
	v_cvt_pk_bf16_f32 v159, v150, v151
	global_store_dwordx2 v177, v[152:153], s[12:13] offset:0
	global_store_dwordx2 v177, v[154:155], s[12:13] offset:512
	global_store_dwordx2 v177, v[156:157], s[12:13] offset:1024
	global_store_dwordx2 v177, v[158:159], s[12:13] offset:1536
	s_add_u32 s8, s8, 0x1000
	s_addc_u32 s9, s9, 0
	s_add_u32 s12, s12, 0x800
	s_addc_u32 s13, s13, 0
	global_load_dwordx4 v[64:67], v176, s[2:3] offset:0
	global_load_dwordx4 v[68:71], v176, s[2:3] offset:1024
	global_load_dwordx4 v[72:75], v176, s[2:3] offset:2048
	global_load_dwordx4 v[76:79], v176, s[2:3] offset:3072
	global_load_dwordx2 v[112:113], v177, s[6:7] offset:0
	global_load_dwordx2 v[114:115], v177, s[6:7] offset:512
	global_load_dwordx2 v[116:117], v177, s[6:7] offset:1024
	global_load_dwordx2 v[118:119], v177, s[6:7] offset:1536
	s_add_u32 s2, s2, 0x1000
	s_addc_u32 s3, s3, 0
	s_add_u32 s6, s6, 0x800
	s_addc_u32 s7, s7, 0
	s_waitcnt vmcnt(32)
	v_lshlrev_b32_e32 v136, 16, v120
	v_and_b32_e32 v137, 0xffff0000, v120
	v_lshlrev_b32_e32 v138, 16, v121
	v_and_b32_e32 v139, 0xffff0000, v121
	v_lshlrev_b32_e32 v140, 16, v122
	v_and_b32_e32 v141, 0xffff0000, v122
	v_lshlrev_b32_e32 v142, 16, v123
	v_and_b32_e32 v143, 0xffff0000, v123
	v_lshlrev_b32_e32 v144, 16, v124
	v_and_b32_e32 v145, 0xffff0000, v124
	v_lshlrev_b32_e32 v146, 16, v125
	v_and_b32_e32 v147, 0xffff0000, v125
	v_lshlrev_b32_e32 v148, 16, v126
	v_and_b32_e32 v149, 0xffff0000, v126
	v_lshlrev_b32_e32 v150, 16, v127
	v_and_b32_e32 v151, 0xffff0000, v127
	v_pk_fma_f32 v[136:137], v[80:81], s[44:45], v[136:137]
	v_pk_fma_f32 v[138:139], v[82:83], s[44:45], v[138:139]
	v_pk_fma_f32 v[140:141], v[84:85], s[44:45], v[140:141]
	v_pk_fma_f32 v[142:143], v[86:87], s[44:45], v[142:143]
	v_pk_fma_f32 v[144:145], v[88:89], s[44:45], v[144:145]
	v_pk_fma_f32 v[146:147], v[90:91], s[44:45], v[146:147]
	v_pk_fma_f32 v[148:149], v[92:93], s[44:45], v[148:149]
	v_pk_fma_f32 v[150:151], v[94:95], s[44:45], v[150:151]
	v_pk_add_f32 v[152:153], v[136:137], v[138:139]
	v_pk_add_f32 v[152:153], v[152:153], v[140:141]
	v_pk_add_f32 v[152:153], v[152:153], v[142:143]
	v_pk_add_f32 v[152:153], v[152:153], v[144:145]
	v_pk_add_f32 v[152:153], v[152:153], v[146:147]
	v_pk_add_f32 v[152:153], v[152:153], v[148:149]
	v_pk_add_f32 v[152:153], v[152:153], v[150:151]
	v_add_f32_e32 v170, v152, v153
	s_nop 1
	v_add_f32_dpp v168, v170, v170 quad_perm:[1,0,3,2] row_mask:0xf bank_mask:0xf
	s_nop 1
	v_add_f32_dpp v168, v168, v168 quad_perm:[2,3,0,1] row_mask:0xf bank_mask:0xf
	s_nop 1
	v_add_f32_dpp v168, v168, v168 row_half_mirror row_mask:0xf bank_mask:0xf
	s_nop 1
	v_add_f32_dpp v168, v168, v168 row_mirror row_mask:0xf bank_mask:0xf
	s_nop 1
	v_add_f32_dpp v168, v168, v168 row_bcast:15 row_mask:0xa bank_mask:0xf
	s_nop 1
	v_add_f32_dpp v168, v168, v168 row_bcast:31 row_mask:0xc bank_mask:0xf
	s_nop 1
	v_readlane_b32 s42, v168, 63
	s_nop 3
	s_mov_b32 s43, s42
	v_pk_fma_f32 v[136:137], s[42:43], v[172:173], v[136:137]
	v_pk_fma_f32 v[138:139], s[42:43], v[172:173], v[138:139]
	v_pk_fma_f32 v[140:141], s[42:43], v[172:173], v[140:141]
	v_pk_fma_f32 v[142:143], s[42:43], v[172:173], v[142:143]
	v_pk_fma_f32 v[144:145], s[42:43], v[172:173], v[144:145]
	v_pk_fma_f32 v[146:147], s[42:43], v[172:173], v[146:147]
	v_pk_fma_f32 v[148:149], s[42:43], v[172:173], v[148:149]
	v_pk_fma_f32 v[150:151], s[42:43], v[172:173], v[150:151]
	v_pk_mul_f32 v[152:153], v[136:137], v[136:137]
	v_pk_fma_f32 v[152:153], v[138:139], v[138:139], v[152:153]
	v_pk_fma_f32 v[152:153], v[140:141], v[140:141], v[152:153]
	v_pk_fma_f32 v[152:153], v[142:143], v[142:143], v[152:153]
	v_pk_fma_f32 v[152:153], v[144:145], v[144:145], v[152:153]
	v_pk_fma_f32 v[152:153], v[146:147], v[146:147], v[152:153]
	v_pk_fma_f32 v[152:153], v[148:149], v[148:149], v[152:153]
	v_pk_fma_f32 v[152:153], v[150:151], v[150:151], v[152:153]
	v_add_f32_e32 v170, v152, v153
	s_nop 1
	v_add_f32_dpp v168, v170, v170 quad_perm:[1,0,3,2] row_mask:0xf bank_mask:0xf
	s_nop 1
	v_add_f32_dpp v168, v168, v168 quad_perm:[2,3,0,1] row_mask:0xf bank_mask:0xf
	s_nop 1
	v_add_f32_dpp v168, v168, v168 row_half_mirror row_mask:0xf bank_mask:0xf
	s_nop 1
	v_add_f32_dpp v168, v168, v168 row_mirror row_mask:0xf bank_mask:0xf
	s_nop 1
	v_add_f32_dpp v168, v168, v168 row_bcast:15 row_mask:0xa bank_mask:0xf
	s_nop 1
	v_add_f32_dpp v168, v168, v168 row_bcast:31 row_mask:0xc bank_mask:0xf
	s_nop 1
	v_readlane_b32 s42, v168, 63
	s_nop 3
	v_fma_f32 v174, s42, v178, v179
	v_rsq_f32_e32 v174, v174
	s_nop 0
	v_pk_mul_f32 v[136:137], v[136:137], v[174:175] op_sel_hi:[1,0]
	v_pk_mul_f32 v[138:139], v[138:139], v[174:175] op_sel_hi:[1,0]
	v_pk_mul_f32 v[140:141], v[140:141], v[174:175] op_sel_hi:[1,0]
	v_pk_mul_f32 v[142:143], v[142:143], v[174:175] op_sel_hi:[1,0]
	v_pk_mul_f32 v[144:145], v[144:145], v[174:175] op_sel_hi:[1,0]
	v_pk_mul_f32 v[146:147], v[146:147], v[174:175] op_sel_hi:[1,0]
	v_pk_mul_f32 v[148:149], v[148:149], v[174:175] op_sel_hi:[1,0]
	v_pk_mul_f32 v[150:151], v[150:151], v[174:175] op_sel_hi:[1,0]
	v_pk_fma_f32 v[136:137], v[136:137], v[0:1], v[16:17]
	v_pk_fma_f32 v[138:139], v[138:139], v[2:3], v[18:19]
	v_pk_fma_f32 v[140:141], v[140:141], v[4:5], v[20:21]
	v_pk_fma_f32 v[142:143], v[142:143], v[6:7], v[22:23]
	v_pk_fma_f32 v[144:145], v[144:145], v[8:9], v[24:25]
	v_pk_fma_f32 v[146:147], v[146:147], v[10:11], v[26:27]
	v_pk_fma_f32 v[148:149], v[148:149], v[12:13], v[28:29]
	v_pk_fma_f32 v[150:151], v[150:151], v[14:15], v[30:31]
	global_store_dwordx4 v176, v[136:139], s[8:9] offset:0
	global_store_dwordx4 v176, v[140:143], s[8:9] offset:1024
	global_store_dwordx4 v176, v[144:147], s[8:9] offset:2048
	global_store_dwordx4 v176, v[148:151], s[8:9] offset:3072
	v_pk_add_f32 v[152:153], v[136:137], v[138:139]
	v_pk_add_f32 v[152:153], v[152:153], v[140:141]
	v_pk_add_f32 v[152:153], v[152:153], v[142:143]
	v_pk_add_f32 v[152:153], v[152:153], v[144:145]
	v_pk_add_f32 v[152:153], v[152:153], v[146:147]
	v_pk_add_f32 v[152:153], v[152:153], v[148:149]
	v_pk_add_f32 v[152:153], v[152:153], v[150:151]
	v_add_f32_e32 v170, v152, v153
	s_nop 1
	v_add_f32_dpp v168, v170, v170 quad_perm:[1,0,3,2] row_mask:0xf bank_mask:0xf
	s_nop 1
	v_add_f32_dpp v168, v168, v168 quad_perm:[2,3,0,1] row_mask:0xf bank_mask:0xf
	s_nop 1
	v_add_f32_dpp v168, v168, v168 row_half_mirror row_mask:0xf bank_mask:0xf
	s_nop 1
	v_add_f32_dpp v168, v168, v168 row_mirror row_mask:0xf bank_mask:0xf
	s_nop 1
	v_add_f32_dpp v168, v168, v168 row_bcast:15 row_mask:0xa bank_mask:0xf
	s_nop 1
	v_add_f32_dpp v168, v168, v168 row_bcast:31 row_mask:0xc bank_mask:0xf
	s_nop 1
	v_readlane_b32 s42, v168, 63
	s_nop 3
	s_mov_b32 s43, s42
	v_pk_fma_f32 v[136:137], s[42:43], v[172:173], v[136:137]
	v_pk_fma_f32 v[138:139], s[42:43], v[172:173], v[138:139]
	v_pk_fma_f32 v[140:141], s[42:43], v[172:173], v[140:141]
	v_pk_fma_f32 v[142:143], s[42:43], v[172:173], v[142:143]
	v_pk_fma_f32 v[144:145], s[42:43], v[172:173], v[144:145]
	v_pk_fma_f32 v[146:147], s[42:43], v[172:173], v[146:147]
	v_pk_fma_f32 v[148:149], s[42:43], v[172:173], v[148:149]
	v_pk_fma_f32 v[150:151], s[42:43], v[172:173], v[150:151]
	v_pk_mul_f32 v[152:153], v[136:137], v[136:137]
	v_pk_fma_f32 v[152:153], v[138:139], v[138:139], v[152:153]
	v_pk_fma_f32 v[152:153], v[140:141], v[140:141], v[152:153]
	v_pk_fma_f32 v[152:153], v[142:143], v[142:143], v[152:153]
	v_pk_fma_f32 v[152:153], v[144:145], v[144:145], v[152:153]
	v_pk_fma_f32 v[152:153], v[146:147], v[146:147], v[152:153]
	v_pk_fma_f32 v[152:153], v[148:149], v[148:149], v[152:153]
	v_pk_fma_f32 v[152:153], v[150:151], v[150:151], v[152:153]
	v_add_f32_e32 v170, v152, v153
	s_nop 1
	v_add_f32_dpp v168, v170, v170 quad_perm:[1,0,3,2] row_mask:0xf bank_mask:0xf
	s_nop 1
	v_add_f32_dpp v168, v168, v168 quad_perm:[2,3,0,1] row_mask:0xf bank_mask:0xf
	s_nop 1
	v_add_f32_dpp v168, v168, v168 row_half_mirror row_mask:0xf bank_mask:0xf
	s_nop 1
	v_add_f32_dpp v168, v168, v168 row_mirror row_mask:0xf bank_mask:0xf
	s_nop 1
	v_add_f32_dpp v168, v168, v168 row_bcast:15 row_mask:0xa bank_mask:0xf
	s_nop 1
	v_add_f32_dpp v168, v168, v168 row_bcast:31 row_mask:0xc bank_mask:0xf
	s_nop 1
	v_readlane_b32 s42, v168, 63
	s_nop 3
	v_fma_f32 v174, s42, v178, v179
	v_rsq_f32_e32 v174, v174
	s_nop 0
	v_pk_mul_f32 v[136:137], v[136:137], v[174:175] op_sel_hi:[1,0]
	v_pk_mul_f32 v[138:139], v[138:139], v[174:175] op_sel_hi:[1,0]
	v_pk_mul_f32 v[140:141], v[140:141], v[174:175] op_sel_hi:[1,0]
	v_pk_mul_f32 v[142:143], v[142:143], v[174:175] op_sel_hi:[1,0]
	v_pk_mul_f32 v[144:145], v[144:145], v[174:175] op_sel_hi:[1,0]
	v_pk_mul_f32 v[146:147], v[146:147], v[174:175] op_sel_hi:[1,0]
	v_pk_mul_f32 v[148:149], v[148:149], v[174:175] op_sel_hi:[1,0]
	v_pk_mul_f32 v[150:151], v[150:151], v[174:175] op_sel_hi:[1,0]
	v_pk_fma_f32 v[136:137], v[136:137], v[32:33], v[48:49]
	v_pk_fma_f32 v[138:139], v[138:139], v[34:35], v[50:51]
	v_pk_fma_f32 v[140:141], v[140:141], v[36:37], v[52:53]
	v_pk_fma_f32 v[142:143], v[142:143], v[38:39], v[54:55]
	v_pk_fma_f32 v[144:145], v[144:145], v[40:41], v[56:57]
	v_pk_fma_f32 v[146:147], v[146:147], v[42:43], v[58:59]
	v_pk_fma_f32 v[148:149], v[148:149], v[44:45], v[60:61]
	v_pk_fma_f32 v[150:151], v[150:151], v[46:47], v[62:63]
	v_cvt_pk_bf16_f32 v152, v136, v137
	v_cvt_pk_bf16_f32 v153, v138, v139
	v_cvt_pk_bf16_f32 v154, v140, v141
	v_cvt_pk_bf16_f32 v155, v142, v143
	v_cvt_pk_bf16_f32 v156, v144, v145
	v_cvt_pk_bf16_f32 v157, v146, v147
	v_cvt_pk_bf16_f32 v158, v148, v149
	v_cvt_pk_bf16_f32 v159, v150, v151
	global_store_dwordx2 v177, v[152:153], s[12:13] offset:0
	global_store_dwordx2 v177, v[154:155], s[12:13] offset:512
	global_store_dwordx2 v177, v[156:157], s[12:13] offset:1024
	global_store_dwordx2 v177, v[158:159], s[12:13] offset:1536
	s_add_u32 s8, s8, 0x1000
	s_addc_u32 s9, s9, 0
	s_add_u32 s12, s12, 0x800
	s_addc_u32 s13, s13, 0
	global_load_dwordx4 v[80:83], v176, s[2:3] offset:0
	global_load_dwordx4 v[84:87], v176, s[2:3] offset:1024
	global_load_dwordx4 v[88:91], v176, s[2:3] offset:2048
	global_load_dwordx4 v[92:95], v176, s[2:3] offset:3072
	global_load_dwordx2 v[120:121], v177, s[6:7] offset:0
	global_load_dwordx2 v[122:123], v177, s[6:7] offset:512
	global_load_dwordx2 v[124:125], v177, s[6:7] offset:1024
	global_load_dwordx2 v[126:127], v177, s[6:7] offset:1536
	s_add_u32 s2, s2, 0x1000
	s_addc_u32 s3, s3, 0
	s_add_u32 s6, s6, 0x800
	s_addc_u32 s7, s7, 0
	s_waitcnt vmcnt(32)
	v_lshlrev_b32_e32 v136, 16, v128
	v_and_b32_e32 v137, 0xffff0000, v128
	v_lshlrev_b32_e32 v138, 16, v129
	v_and_b32_e32 v139, 0xffff0000, v129
	v_lshlrev_b32_e32 v140, 16, v130
	v_and_b32_e32 v141, 0xffff0000, v130
	v_lshlrev_b32_e32 v142, 16, v131
	v_and_b32_e32 v143, 0xffff0000, v131
	v_lshlrev_b32_e32 v144, 16, v132
	v_and_b32_e32 v145, 0xffff0000, v132
	v_lshlrev_b32_e32 v146, 16, v133
	v_and_b32_e32 v147, 0xffff0000, v133
	v_lshlrev_b32_e32 v148, 16, v134
	v_and_b32_e32 v149, 0xffff0000, v134
	v_lshlrev_b32_e32 v150, 16, v135
	v_and_b32_e32 v151, 0xffff0000, v135
	v_pk_fma_f32 v[136:137], v[96:97], s[44:45], v[136:137]
	v_pk_fma_f32 v[138:139], v[98:99], s[44:45], v[138:139]
	v_pk_fma_f32 v[140:141], v[100:101], s[44:45], v[140:141]
	v_pk_fma_f32 v[142:143], v[102:103], s[44:45], v[142:143]
	v_pk_fma_f32 v[144:145], v[104:105], s[44:45], v[144:145]
	v_pk_fma_f32 v[146:147], v[106:107], s[44:45], v[146:147]
	v_pk_fma_f32 v[148:149], v[108:109], s[44:45], v[148:149]
	v_pk_fma_f32 v[150:151], v[110:111], s[44:45], v[150:151]
	v_pk_add_f32 v[152:153], v[136:137], v[138:139]
	v_pk_add_f32 v[152:153], v[152:153], v[140:141]
	v_pk_add_f32 v[152:153], v[152:153], v[142:143]
	v_pk_add_f32 v[152:153], v[152:153], v[144:145]
	v_pk_add_f32 v[152:153], v[152:153], v[146:147]
	v_pk_add_f32 v[152:153], v[152:153], v[148:149]
	v_pk_add_f32 v[152:153], v[152:153], v[150:151]
	v_add_f32_e32 v170, v152, v153
	s_nop 1
	v_add_f32_dpp v168, v170, v170 quad_perm:[1,0,3,2] row_mask:0xf bank_mask:0xf
	s_nop 1
	v_add_f32_dpp v168, v168, v168 quad_perm:[2,3,0,1] row_mask:0xf bank_mask:0xf
	s_nop 1
	v_add_f32_dpp v168, v168, v168 row_half_mirror row_mask:0xf bank_mask:0xf
	s_nop 1
	v_add_f32_dpp v168, v168, v168 row_mirror row_mask:0xf bank_mask:0xf
	s_nop 1
	v_add_f32_dpp v168, v168, v168 row_bcast:15 row_mask:0xa bank_mask:0xf
	s_nop 1
	v_add_f32_dpp v168, v168, v168 row_bcast:31 row_mask:0xc bank_mask:0xf
	s_nop 1
	v_readlane_b32 s42, v168, 63
	s_nop 3
	s_mov_b32 s43, s42
	v_pk_fma_f32 v[136:137], s[42:43], v[172:173], v[136:137]
	v_pk_fma_f32 v[138:139], s[42:43], v[172:173], v[138:139]
	v_pk_fma_f32 v[140:141], s[42:43], v[172:173], v[140:141]
	v_pk_fma_f32 v[142:143], s[42:43], v[172:173], v[142:143]
	v_pk_fma_f32 v[144:145], s[42:43], v[172:173], v[144:145]
	v_pk_fma_f32 v[146:147], s[42:43], v[172:173], v[146:147]
	v_pk_fma_f32 v[148:149], s[42:43], v[172:173], v[148:149]
	v_pk_fma_f32 v[150:151], s[42:43], v[172:173], v[150:151]
	v_pk_mul_f32 v[152:153], v[136:137], v[136:137]
	v_pk_fma_f32 v[152:153], v[138:139], v[138:139], v[152:153]
	v_pk_fma_f32 v[152:153], v[140:141], v[140:141], v[152:153]
	v_pk_fma_f32 v[152:153], v[142:143], v[142:143], v[152:153]
	v_pk_fma_f32 v[152:153], v[144:145], v[144:145], v[152:153]
	v_pk_fma_f32 v[152:153], v[146:147], v[146:147], v[152:153]
	v_pk_fma_f32 v[152:153], v[148:149], v[148:149], v[152:153]
	v_pk_fma_f32 v[152:153], v[150:151], v[150:151], v[152:153]
	v_add_f32_e32 v170, v152, v153
	s_nop 1
	v_add_f32_dpp v168, v170, v170 quad_perm:[1,0,3,2] row_mask:0xf bank_mask:0xf
	s_nop 1
	v_add_f32_dpp v168, v168, v168 quad_perm:[2,3,0,1] row_mask:0xf bank_mask:0xf
	s_nop 1
	v_add_f32_dpp v168, v168, v168 row_half_mirror row_mask:0xf bank_mask:0xf
	s_nop 1
	v_add_f32_dpp v168, v168, v168 row_mirror row_mask:0xf bank_mask:0xf
	s_nop 1
	v_add_f32_dpp v168, v168, v168 row_bcast:15 row_mask:0xa bank_mask:0xf
	s_nop 1
	v_add_f32_dpp v168, v168, v168 row_bcast:31 row_mask:0xc bank_mask:0xf
	s_nop 1
	v_readlane_b32 s42, v168, 63
	s_nop 3
	v_fma_f32 v174, s42, v178, v179
	v_rsq_f32_e32 v174, v174
	s_nop 0
	v_pk_mul_f32 v[136:137], v[136:137], v[174:175] op_sel_hi:[1,0]
	v_pk_mul_f32 v[138:139], v[138:139], v[174:175] op_sel_hi:[1,0]
	v_pk_mul_f32 v[140:141], v[140:141], v[174:175] op_sel_hi:[1,0]
	v_pk_mul_f32 v[142:143], v[142:143], v[174:175] op_sel_hi:[1,0]
	v_pk_mul_f32 v[144:145], v[144:145], v[174:175] op_sel_hi:[1,0]
	v_pk_mul_f32 v[146:147], v[146:147], v[174:175] op_sel_hi:[1,0]
	v_pk_mul_f32 v[148:149], v[148:149], v[174:175] op_sel_hi:[1,0]
	v_pk_mul_f32 v[150:151], v[150:151], v[174:175] op_sel_hi:[1,0]
	v_pk_fma_f32 v[136:137], v[136:137], v[0:1], v[16:17]
	v_pk_fma_f32 v[138:139], v[138:139], v[2:3], v[18:19]
	v_pk_fma_f32 v[140:141], v[140:141], v[4:5], v[20:21]
	v_pk_fma_f32 v[142:143], v[142:143], v[6:7], v[22:23]
	v_pk_fma_f32 v[144:145], v[144:145], v[8:9], v[24:25]
	v_pk_fma_f32 v[146:147], v[146:147], v[10:11], v[26:27]
	v_pk_fma_f32 v[148:149], v[148:149], v[12:13], v[28:29]
	v_pk_fma_f32 v[150:151], v[150:151], v[14:15], v[30:31]
	global_store_dwordx4 v176, v[136:139], s[8:9] offset:0
	global_store_dwordx4 v176, v[140:143], s[8:9] offset:1024
	global_store_dwordx4 v176, v[144:147], s[8:9] offset:2048
	global_store_dwordx4 v176, v[148:151], s[8:9] offset:3072
	v_pk_add_f32 v[152:153], v[136:137], v[138:139]
	v_pk_add_f32 v[152:153], v[152:153], v[140:141]
	v_pk_add_f32 v[152:153], v[152:153], v[142:143]
	v_pk_add_f32 v[152:153], v[152:153], v[144:145]
	v_pk_add_f32 v[152:153], v[152:153], v[146:147]
	v_pk_add_f32 v[152:153], v[152:153], v[148:149]
	v_pk_add_f32 v[152:153], v[152:153], v[150:151]
	v_add_f32_e32 v170, v152, v153
	s_nop 1
	v_add_f32_dpp v168, v170, v170 quad_perm:[1,0,3,2] row_mask:0xf bank_mask:0xf
	s_nop 1
	v_add_f32_dpp v168, v168, v168 quad_perm:[2,3,0,1] row_mask:0xf bank_mask:0xf
	s_nop 1
	v_add_f32_dpp v168, v168, v168 row_half_mirror row_mask:0xf bank_mask:0xf
	s_nop 1
	v_add_f32_dpp v168, v168, v168 row_mirror row_mask:0xf bank_mask:0xf
	s_nop 1
	v_add_f32_dpp v168, v168, v168 row_bcast:15 row_mask:0xa bank_mask:0xf
	s_nop 1
	v_add_f32_dpp v168, v168, v168 row_bcast:31 row_mask:0xc bank_mask:0xf
	s_nop 1
	v_readlane_b32 s42, v168, 63
	s_nop 3
	s_mov_b32 s43, s42
	v_pk_fma_f32 v[136:137], s[42:43], v[172:173], v[136:137]
	v_pk_fma_f32 v[138:139], s[42:43], v[172:173], v[138:139]
	v_pk_fma_f32 v[140:141], s[42:43], v[172:173], v[140:141]
	v_pk_fma_f32 v[142:143], s[42:43], v[172:173], v[142:143]
	v_pk_fma_f32 v[144:145], s[42:43], v[172:173], v[144:145]
	v_pk_fma_f32 v[146:147], s[42:43], v[172:173], v[146:147]
	v_pk_fma_f32 v[148:149], s[42:43], v[172:173], v[148:149]
	v_pk_fma_f32 v[150:151], s[42:43], v[172:173], v[150:151]
	v_pk_mul_f32 v[152:153], v[136:137], v[136:137]
	v_pk_fma_f32 v[152:153], v[138:139], v[138:139], v[152:153]
	v_pk_fma_f32 v[152:153], v[140:141], v[140:141], v[152:153]
	v_pk_fma_f32 v[152:153], v[142:143], v[142:143], v[152:153]
	v_pk_fma_f32 v[152:153], v[144:145], v[144:145], v[152:153]
	v_pk_fma_f32 v[152:153], v[146:147], v[146:147], v[152:153]
	v_pk_fma_f32 v[152:153], v[148:149], v[148:149], v[152:153]
	v_pk_fma_f32 v[152:153], v[150:151], v[150:151], v[152:153]
	v_add_f32_e32 v170, v152, v153
	s_nop 1
	v_add_f32_dpp v168, v170, v170 quad_perm:[1,0,3,2] row_mask:0xf bank_mask:0xf
	s_nop 1
	v_add_f32_dpp v168, v168, v168 quad_perm:[2,3,0,1] row_mask:0xf bank_mask:0xf
	s_nop 1
	v_add_f32_dpp v168, v168, v168 row_half_mirror row_mask:0xf bank_mask:0xf
	s_nop 1
	v_add_f32_dpp v168, v168, v168 row_mirror row_mask:0xf bank_mask:0xf
	s_nop 1
	v_add_f32_dpp v168, v168, v168 row_bcast:15 row_mask:0xa bank_mask:0xf
	s_nop 1
	v_add_f32_dpp v168, v168, v168 row_bcast:31 row_mask:0xc bank_mask:0xf
	s_nop 1
	v_readlane_b32 s42, v168, 63
	s_nop 3
	v_fma_f32 v174, s42, v178, v179
	v_rsq_f32_e32 v174, v174
	s_nop 0
	v_pk_mul_f32 v[136:137], v[136:137], v[174:175] op_sel_hi:[1,0]
	v_pk_mul_f32 v[138:139], v[138:139], v[174:175] op_sel_hi:[1,0]
	v_pk_mul_f32 v[140:141], v[140:141], v[174:175] op_sel_hi:[1,0]
	v_pk_mul_f32 v[142:143], v[142:143], v[174:175] op_sel_hi:[1,0]
	v_pk_mul_f32 v[144:145], v[144:145], v[174:175] op_sel_hi:[1,0]
	v_pk_mul_f32 v[146:147], v[146:147], v[174:175] op_sel_hi:[1,0]
	v_pk_mul_f32 v[148:149], v[148:149], v[174:175] op_sel_hi:[1,0]
	v_pk_mul_f32 v[150:151], v[150:151], v[174:175] op_sel_hi:[1,0]
	v_pk_fma_f32 v[136:137], v[136:137], v[32:33], v[48:49]
	v_pk_fma_f32 v[138:139], v[138:139], v[34:35], v[50:51]
	v_pk_fma_f32 v[140:141], v[140:141], v[36:37], v[52:53]
	v_pk_fma_f32 v[142:143], v[142:143], v[38:39], v[54:55]
	v_pk_fma_f32 v[144:145], v[144:145], v[40:41], v[56:57]
	v_pk_fma_f32 v[146:147], v[146:147], v[42:43], v[58:59]
	v_pk_fma_f32 v[148:149], v[148:149], v[44:45], v[60:61]
	v_pk_fma_f32 v[150:151], v[150:151], v[46:47], v[62:63]
	v_cvt_pk_bf16_f32 v152, v136, v137
	v_cvt_pk_bf16_f32 v153, v138, v139
	v_cvt_pk_bf16_f32 v154, v140, v141
	v_cvt_pk_bf16_f32 v155, v142, v143
	v_cvt_pk_bf16_f32 v156, v144, v145
	v_cvt_pk_bf16_f32 v157, v146, v147
	v_cvt_pk_bf16_f32 v158, v148, v149
	v_cvt_pk_bf16_f32 v159, v150, v151
	global_store_dwordx2 v177, v[152:153], s[12:13] offset:0
	global_store_dwordx2 v177, v[154:155], s[12:13] offset:512
	global_store_dwordx2 v177, v[156:157], s[12:13] offset:1024
	global_store_dwordx2 v177, v[158:159], s[12:13] offset:1536
	s_add_u32 s8, s8, 0x1000
	s_addc_u32 s9, s9, 0
	s_add_u32 s12, s12, 0x800
	s_addc_u32 s13, s13, 0
	global_load_dwordx4 v[96:99], v176, s[2:3] offset:0
	global_load_dwordx4 v[100:103], v176, s[2:3] offset:1024
	global_load_dwordx4 v[104:107], v176, s[2:3] offset:2048
	global_load_dwordx4 v[108:111], v176, s[2:3] offset:3072
	global_load_dwordx2 v[128:129], v177, s[6:7] offset:0
	global_load_dwordx2 v[130:131], v177, s[6:7] offset:512
	global_load_dwordx2 v[132:133], v177, s[6:7] offset:1024
	global_load_dwordx2 v[134:135], v177, s[6:7] offset:1536
	s_add_u32 s2, s2, 0x1000
	s_addc_u32 s3, s3, 0
	s_add_u32 s6, s6, 0x800
	s_addc_u32 s7, s7, 0
	s_waitcnt vmcnt(32)
	v_lshlrev_b32_e32 v136, 16, v112
	v_and_b32_e32 v137, 0xffff0000, v112
	v_lshlrev_b32_e32 v138, 16, v113
	v_and_b32_e32 v139, 0xffff0000, v113
	v_lshlrev_b32_e32 v140, 16, v114
	v_and_b32_e32 v141, 0xffff0000, v114
	v_lshlrev_b32_e32 v142, 16, v115
	v_and_b32_e32 v143, 0xffff0000, v115
	v_lshlrev_b32_e32 v144, 16, v116
	v_and_b32_e32 v145, 0xffff0000, v116
	v_lshlrev_b32_e32 v146, 16, v117
	v_and_b32_e32 v147, 0xffff0000, v117
	v_lshlrev_b32_e32 v148, 16, v118
	v_and_b32_e32 v149, 0xffff0000, v118
	v_lshlrev_b32_e32 v150, 16, v119
	v_and_b32_e32 v151, 0xffff0000, v119
	v_pk_fma_f32 v[136:137], v[64:65], s[44:45], v[136:137]
	v_pk_fma_f32 v[138:139], v[66:67], s[44:45], v[138:139]
	v_pk_fma_f32 v[140:141], v[68:69], s[44:45], v[140:141]
	v_pk_fma_f32 v[142:143], v[70:71], s[44:45], v[142:143]
	v_pk_fma_f32 v[144:145], v[72:73], s[44:45], v[144:145]
	v_pk_fma_f32 v[146:147], v[74:75], s[44:45], v[146:147]
	v_pk_fma_f32 v[148:149], v[76:77], s[44:45], v[148:149]
	v_pk_fma_f32 v[150:151], v[78:79], s[44:45], v[150:151]
	v_pk_add_f32 v[152:153], v[136:137], v[138:139]
	v_pk_add_f32 v[152:153], v[152:153], v[140:141]
	v_pk_add_f32 v[152:153], v[152:153], v[142:143]
	v_pk_add_f32 v[152:153], v[152:153], v[144:145]
	v_pk_add_f32 v[152:153], v[152:153], v[146:147]
	v_pk_add_f32 v[152:153], v[152:153], v[148:149]
	v_pk_add_f32 v[152:153], v[152:153], v[150:151]
	v_add_f32_e32 v170, v152, v153
	s_nop 1
	v_add_f32_dpp v168, v170, v170 quad_perm:[1,0,3,2] row_mask:0xf bank_mask:0xf
	s_nop 1
	v_add_f32_dpp v168, v168, v168 quad_perm:[2,3,0,1] row_mask:0xf bank_mask:0xf
	s_nop 1
	v_add_f32_dpp v168, v168, v168 row_half_mirror row_mask:0xf bank_mask:0xf
	s_nop 1
	v_add_f32_dpp v168, v168, v168 row_mirror row_mask:0xf bank_mask:0xf
	s_nop 1
	v_add_f32_dpp v168, v168, v168 row_bcast:15 row_mask:0xa bank_mask:0xf
	s_nop 1
	v_add_f32_dpp v168, v168, v168 row_bcast:31 row_mask:0xc bank_mask:0xf
	s_nop 1
	v_readlane_b32 s42, v168, 63
	s_nop 3
	s_mov_b32 s43, s42
	v_pk_fma_f32 v[136:137], s[42:43], v[172:173], v[136:137]
	v_pk_fma_f32 v[138:139], s[42:43], v[172:173], v[138:139]
	v_pk_fma_f32 v[140:141], s[42:43], v[172:173], v[140:141]
	v_pk_fma_f32 v[142:143], s[42:43], v[172:173], v[142:143]
	v_pk_fma_f32 v[144:145], s[42:43], v[172:173], v[144:145]
	v_pk_fma_f32 v[146:147], s[42:43], v[172:173], v[146:147]
	v_pk_fma_f32 v[148:149], s[42:43], v[172:173], v[148:149]
	v_pk_fma_f32 v[150:151], s[42:43], v[172:173], v[150:151]
	v_pk_mul_f32 v[152:153], v[136:137], v[136:137]
	v_pk_fma_f32 v[152:153], v[138:139], v[138:139], v[152:153]
	v_pk_fma_f32 v[152:153], v[140:141], v[140:141], v[152:153]
	v_pk_fma_f32 v[152:153], v[142:143], v[142:143], v[152:153]
	v_pk_fma_f32 v[152:153], v[144:145], v[144:145], v[152:153]
	v_pk_fma_f32 v[152:153], v[146:147], v[146:147], v[152:153]
	v_pk_fma_f32 v[152:153], v[148:149], v[148:149], v[152:153]
	v_pk_fma_f32 v[152:153], v[150:151], v[150:151], v[152:153]
	v_add_f32_e32 v170, v152, v153
	s_nop 1
	v_add_f32_dpp v168, v170, v170 quad_perm:[1,0,3,2] row_mask:0xf bank_mask:0xf
	s_nop 1
	v_add_f32_dpp v168, v168, v168 quad_perm:[2,3,0,1] row_mask:0xf bank_mask:0xf
	s_nop 1
	v_add_f32_dpp v168, v168, v168 row_half_mirror row_mask:0xf bank_mask:0xf
	s_nop 1
	v_add_f32_dpp v168, v168, v168 row_mirror row_mask:0xf bank_mask:0xf
	s_nop 1
	v_add_f32_dpp v168, v168, v168 row_bcast:15 row_mask:0xa bank_mask:0xf
	s_nop 1
	v_add_f32_dpp v168, v168, v168 row_bcast:31 row_mask:0xc bank_mask:0xf
	s_nop 1
	v_readlane_b32 s42, v168, 63
	s_nop 3
	v_fma_f32 v174, s42, v178, v179
	v_rsq_f32_e32 v174, v174
	s_nop 0
	v_pk_mul_f32 v[136:137], v[136:137], v[174:175] op_sel_hi:[1,0]
	v_pk_mul_f32 v[138:139], v[138:139], v[174:175] op_sel_hi:[1,0]
	v_pk_mul_f32 v[140:141], v[140:141], v[174:175] op_sel_hi:[1,0]
	v_pk_mul_f32 v[142:143], v[142:143], v[174:175] op_sel_hi:[1,0]
	v_pk_mul_f32 v[144:145], v[144:145], v[174:175] op_sel_hi:[1,0]
	v_pk_mul_f32 v[146:147], v[146:147], v[174:175] op_sel_hi:[1,0]
	v_pk_mul_f32 v[148:149], v[148:149], v[174:175] op_sel_hi:[1,0]
	v_pk_mul_f32 v[150:151], v[150:151], v[174:175] op_sel_hi:[1,0]
	v_pk_fma_f32 v[136:137], v[136:137], v[0:1], v[16:17]
	v_pk_fma_f32 v[138:139], v[138:139], v[2:3], v[18:19]
	v_pk_fma_f32 v[140:141], v[140:141], v[4:5], v[20:21]
	v_pk_fma_f32 v[142:143], v[142:143], v[6:7], v[22:23]
	v_pk_fma_f32 v[144:145], v[144:145], v[8:9], v[24:25]
	v_pk_fma_f32 v[146:147], v[146:147], v[10:11], v[26:27]
	v_pk_fma_f32 v[148:149], v[148:149], v[12:13], v[28:29]
	v_pk_fma_f32 v[150:151], v[150:151], v[14:15], v[30:31]
	global_store_dwordx4 v176, v[136:139], s[8:9] offset:0
	global_store_dwordx4 v176, v[140:143], s[8:9] offset:1024
	global_store_dwordx4 v176, v[144:147], s[8:9] offset:2048
	global_store_dwordx4 v176, v[148:151], s[8:9] offset:3072
	v_pk_add_f32 v[152:153], v[136:137], v[138:139]
	v_pk_add_f32 v[152:153], v[152:153], v[140:141]
	v_pk_add_f32 v[152:153], v[152:153], v[142:143]
	v_pk_add_f32 v[152:153], v[152:153], v[144:145]
	v_pk_add_f32 v[152:153], v[152:153], v[146:147]
	v_pk_add_f32 v[152:153], v[152:153], v[148:149]
	v_pk_add_f32 v[152:153], v[152:153], v[150:151]
	v_add_f32_e32 v170, v152, v153
	s_nop 1
	v_add_f32_dpp v168, v170, v170 quad_perm:[1,0,3,2] row_mask:0xf bank_mask:0xf
	s_nop 1
	v_add_f32_dpp v168, v168, v168 quad_perm:[2,3,0,1] row_mask:0xf bank_mask:0xf
	s_nop 1
	v_add_f32_dpp v168, v168, v168 row_half_mirror row_mask:0xf bank_mask:0xf
	s_nop 1
	v_add_f32_dpp v168, v168, v168 row_mirror row_mask:0xf bank_mask:0xf
	s_nop 1
	v_add_f32_dpp v168, v168, v168 row_bcast:15 row_mask:0xa bank_mask:0xf
	s_nop 1
	v_add_f32_dpp v168, v168, v168 row_bcast:31 row_mask:0xc bank_mask:0xf
	s_nop 1
	v_readlane_b32 s42, v168, 63
	s_nop 3
	s_mov_b32 s43, s42
	v_pk_fma_f32 v[136:137], s[42:43], v[172:173], v[136:137]
	v_pk_fma_f32 v[138:139], s[42:43], v[172:173], v[138:139]
	v_pk_fma_f32 v[140:141], s[42:43], v[172:173], v[140:141]
	v_pk_fma_f32 v[142:143], s[42:43], v[172:173], v[142:143]
	v_pk_fma_f32 v[144:145], s[42:43], v[172:173], v[144:145]
	v_pk_fma_f32 v[146:147], s[42:43], v[172:173], v[146:147]
	v_pk_fma_f32 v[148:149], s[42:43], v[172:173], v[148:149]
	v_pk_fma_f32 v[150:151], s[42:43], v[172:173], v[150:151]
	v_pk_mul_f32 v[152:153], v[136:137], v[136:137]
	v_pk_fma_f32 v[152:153], v[138:139], v[138:139], v[152:153]
	v_pk_fma_f32 v[152:153], v[140:141], v[140:141], v[152:153]
	v_pk_fma_f32 v[152:153], v[142:143], v[142:143], v[152:153]
	v_pk_fma_f32 v[152:153], v[144:145], v[144:145], v[152:153]
	v_pk_fma_f32 v[152:153], v[146:147], v[146:147], v[152:153]
	v_pk_fma_f32 v[152:153], v[148:149], v[148:149], v[152:153]
	v_pk_fma_f32 v[152:153], v[150:151], v[150:151], v[152:153]
	v_add_f32_e32 v170, v152, v153
	s_nop 1
	v_add_f32_dpp v168, v170, v170 quad_perm:[1,0,3,2] row_mask:0xf bank_mask:0xf
	s_nop 1
	v_add_f32_dpp v168, v168, v168 quad_perm:[2,3,0,1] row_mask:0xf bank_mask:0xf
	s_nop 1
	v_add_f32_dpp v168, v168, v168 row_half_mirror row_mask:0xf bank_mask:0xf
	s_nop 1
	v_add_f32_dpp v168, v168, v168 row_mirror row_mask:0xf bank_mask:0xf
	s_nop 1
	v_add_f32_dpp v168, v168, v168 row_bcast:15 row_mask:0xa bank_mask:0xf
	s_nop 1
	v_add_f32_dpp v168, v168, v168 row_bcast:31 row_mask:0xc bank_mask:0xf
	s_nop 1
	v_readlane_b32 s42, v168, 63
	s_nop 3
	v_fma_f32 v174, s42, v178, v179
	v_rsq_f32_e32 v174, v174
	s_nop 0
	v_pk_mul_f32 v[136:137], v[136:137], v[174:175] op_sel_hi:[1,0]
	v_pk_mul_f32 v[138:139], v[138:139], v[174:175] op_sel_hi:[1,0]
	v_pk_mul_f32 v[140:141], v[140:141], v[174:175] op_sel_hi:[1,0]
	v_pk_mul_f32 v[142:143], v[142:143], v[174:175] op_sel_hi:[1,0]
	v_pk_mul_f32 v[144:145], v[144:145], v[174:175] op_sel_hi:[1,0]
	v_pk_mul_f32 v[146:147], v[146:147], v[174:175] op_sel_hi:[1,0]
	v_pk_mul_f32 v[148:149], v[148:149], v[174:175] op_sel_hi:[1,0]
	v_pk_mul_f32 v[150:151], v[150:151], v[174:175] op_sel_hi:[1,0]
	v_pk_fma_f32 v[136:137], v[136:137], v[32:33], v[48:49]
	v_pk_fma_f32 v[138:139], v[138:139], v[34:35], v[50:51]
	v_pk_fma_f32 v[140:141], v[140:141], v[36:37], v[52:53]
	v_pk_fma_f32 v[142:143], v[142:143], v[38:39], v[54:55]
	v_pk_fma_f32 v[144:145], v[144:145], v[40:41], v[56:57]
	v_pk_fma_f32 v[146:147], v[146:147], v[42:43], v[58:59]
	v_pk_fma_f32 v[148:149], v[148:149], v[44:45], v[60:61]
	v_pk_fma_f32 v[150:151], v[150:151], v[46:47], v[62:63]
	v_cvt_pk_bf16_f32 v152, v136, v137
	v_cvt_pk_bf16_f32 v153, v138, v139
	v_cvt_pk_bf16_f32 v154, v140, v141
	v_cvt_pk_bf16_f32 v155, v142, v143
	v_cvt_pk_bf16_f32 v156, v144, v145
	v_cvt_pk_bf16_f32 v157, v146, v147
	v_cvt_pk_bf16_f32 v158, v148, v149
	v_cvt_pk_bf16_f32 v159, v150, v151
	global_store_dwordx2 v177, v[152:153], s[12:13] offset:0
	global_store_dwordx2 v177, v[154:155], s[12:13] offset:512
	global_store_dwordx2 v177, v[156:157], s[12:13] offset:1024
	global_store_dwordx2 v177, v[158:159], s[12:13] offset:1536
	s_add_u32 s8, s8, 0x1000
	s_addc_u32 s9, s9, 0
	s_add_u32 s12, s12, 0x800
	s_addc_u32 s13, s13, 0
	global_load_dwordx4 v[64:67], v176, s[2:3] offset:0
	global_load_dwordx4 v[68:71], v176, s[2:3] offset:1024
	global_load_dwordx4 v[72:75], v176, s[2:3] offset:2048
	global_load_dwordx4 v[76:79], v176, s[2:3] offset:3072
	global_load_dwordx2 v[112:113], v177, s[6:7] offset:0
	global_load_dwordx2 v[114:115], v177, s[6:7] offset:512
	global_load_dwordx2 v[116:117], v177, s[6:7] offset:1024
	global_load_dwordx2 v[118:119], v177, s[6:7] offset:1536
	s_add_u32 s2, s2, 0x1000
	s_addc_u32 s3, s3, 0
	s_add_u32 s6, s6, 0x800
	s_addc_u32 s7, s7, 0
	s_waitcnt vmcnt(32)
	v_lshlrev_b32_e32 v136, 16, v120
	v_and_b32_e32 v137, 0xffff0000, v120
	v_lshlrev_b32_e32 v138, 16, v121
	v_and_b32_e32 v139, 0xffff0000, v121
	v_lshlrev_b32_e32 v140, 16, v122
	v_and_b32_e32 v141, 0xffff0000, v122
	v_lshlrev_b32_e32 v142, 16, v123
	v_and_b32_e32 v143, 0xffff0000, v123
	v_lshlrev_b32_e32 v144, 16, v124
	v_and_b32_e32 v145, 0xffff0000, v124
	v_lshlrev_b32_e32 v146, 16, v125
	v_and_b32_e32 v147, 0xffff0000, v125
	v_lshlrev_b32_e32 v148, 16, v126
	v_and_b32_e32 v149, 0xffff0000, v126
	v_lshlrev_b32_e32 v150, 16, v127
	v_and_b32_e32 v151, 0xffff0000, v127
	v_pk_fma_f32 v[136:137], v[80:81], s[44:45], v[136:137]
	v_pk_fma_f32 v[138:139], v[82:83], s[44:45], v[138:139]
	v_pk_fma_f32 v[140:141], v[84:85], s[44:45], v[140:141]
	v_pk_fma_f32 v[142:143], v[86:87], s[44:45], v[142:143]
	v_pk_fma_f32 v[144:145], v[88:89], s[44:45], v[144:145]
	v_pk_fma_f32 v[146:147], v[90:91], s[44:45], v[146:147]
	v_pk_fma_f32 v[148:149], v[92:93], s[44:45], v[148:149]
	v_pk_fma_f32 v[150:151], v[94:95], s[44:45], v[150:151]
	v_pk_add_f32 v[152:153], v[136:137], v[138:139]
	v_pk_add_f32 v[152:153], v[152:153], v[140:141]
	v_pk_add_f32 v[152:153], v[152:153], v[142:143]
	v_pk_add_f32 v[152:153], v[152:153], v[144:145]
	v_pk_add_f32 v[152:153], v[152:153], v[146:147]
	v_pk_add_f32 v[152:153], v[152:153], v[148:149]
	v_pk_add_f32 v[152:153], v[152:153], v[150:151]
	v_add_f32_e32 v170, v152, v153
	s_nop 1
	v_add_f32_dpp v168, v170, v170 quad_perm:[1,0,3,2] row_mask:0xf bank_mask:0xf
	s_nop 1
	v_add_f32_dpp v168, v168, v168 quad_perm:[2,3,0,1] row_mask:0xf bank_mask:0xf
	s_nop 1
	v_add_f32_dpp v168, v168, v168 row_half_mirror row_mask:0xf bank_mask:0xf
	s_nop 1
	v_add_f32_dpp v168, v168, v168 row_mirror row_mask:0xf bank_mask:0xf
	s_nop 1
	v_add_f32_dpp v168, v168, v168 row_bcast:15 row_mask:0xa bank_mask:0xf
	s_nop 1
	v_add_f32_dpp v168, v168, v168 row_bcast:31 row_mask:0xc bank_mask:0xf
	s_nop 1
	v_readlane_b32 s42, v168, 63
	s_nop 3
	s_mov_b32 s43, s42
	v_pk_fma_f32 v[136:137], s[42:43], v[172:173], v[136:137]
	v_pk_fma_f32 v[138:139], s[42:43], v[172:173], v[138:139]
	v_pk_fma_f32 v[140:141], s[42:43], v[172:173], v[140:141]
	v_pk_fma_f32 v[142:143], s[42:43], v[172:173], v[142:143]
	v_pk_fma_f32 v[144:145], s[42:43], v[172:173], v[144:145]
	v_pk_fma_f32 v[146:147], s[42:43], v[172:173], v[146:147]
	v_pk_fma_f32 v[148:149], s[42:43], v[172:173], v[148:149]
	v_pk_fma_f32 v[150:151], s[42:43], v[172:173], v[150:151]
	v_pk_mul_f32 v[152:153], v[136:137], v[136:137]
	v_pk_fma_f32 v[152:153], v[138:139], v[138:139], v[152:153]
	v_pk_fma_f32 v[152:153], v[140:141], v[140:141], v[152:153]
	v_pk_fma_f32 v[152:153], v[142:143], v[142:143], v[152:153]
	v_pk_fma_f32 v[152:153], v[144:145], v[144:145], v[152:153]
	v_pk_fma_f32 v[152:153], v[146:147], v[146:147], v[152:153]
	v_pk_fma_f32 v[152:153], v[148:149], v[148:149], v[152:153]
	v_pk_fma_f32 v[152:153], v[150:151], v[150:151], v[152:153]
	v_add_f32_e32 v170, v152, v153
	s_nop 1
	v_add_f32_dpp v168, v170, v170 quad_perm:[1,0,3,2] row_mask:0xf bank_mask:0xf
	s_nop 1
	v_add_f32_dpp v168, v168, v168 quad_perm:[2,3,0,1] row_mask:0xf bank_mask:0xf
	s_nop 1
	v_add_f32_dpp v168, v168, v168 row_half_mirror row_mask:0xf bank_mask:0xf
	s_nop 1
	v_add_f32_dpp v168, v168, v168 row_mirror row_mask:0xf bank_mask:0xf
	s_nop 1
	v_add_f32_dpp v168, v168, v168 row_bcast:15 row_mask:0xa bank_mask:0xf
	s_nop 1
	v_add_f32_dpp v168, v168, v168 row_bcast:31 row_mask:0xc bank_mask:0xf
	s_nop 1
	v_readlane_b32 s42, v168, 63
	s_nop 3
	v_fma_f32 v174, s42, v178, v179
	v_rsq_f32_e32 v174, v174
	s_nop 0
	v_pk_mul_f32 v[136:137], v[136:137], v[174:175] op_sel_hi:[1,0]
	v_pk_mul_f32 v[138:139], v[138:139], v[174:175] op_sel_hi:[1,0]
	v_pk_mul_f32 v[140:141], v[140:141], v[174:175] op_sel_hi:[1,0]
	v_pk_mul_f32 v[142:143], v[142:143], v[174:175] op_sel_hi:[1,0]
	v_pk_mul_f32 v[144:145], v[144:145], v[174:175] op_sel_hi:[1,0]
	v_pk_mul_f32 v[146:147], v[146:147], v[174:175] op_sel_hi:[1,0]
	v_pk_mul_f32 v[148:149], v[148:149], v[174:175] op_sel_hi:[1,0]
	v_pk_mul_f32 v[150:151], v[150:151], v[174:175] op_sel_hi:[1,0]
	v_pk_fma_f32 v[136:137], v[136:137], v[0:1], v[16:17]
	v_pk_fma_f32 v[138:139], v[138:139], v[2:3], v[18:19]
	v_pk_fma_f32 v[140:141], v[140:141], v[4:5], v[20:21]
	v_pk_fma_f32 v[142:143], v[142:143], v[6:7], v[22:23]
	v_pk_fma_f32 v[144:145], v[144:145], v[8:9], v[24:25]
	v_pk_fma_f32 v[146:147], v[146:147], v[10:11], v[26:27]
	v_pk_fma_f32 v[148:149], v[148:149], v[12:13], v[28:29]
	v_pk_fma_f32 v[150:151], v[150:151], v[14:15], v[30:31]
	global_store_dwordx4 v176, v[136:139], s[8:9] offset:0
	global_store_dwordx4 v176, v[140:143], s[8:9] offset:1024
	global_store_dwordx4 v176, v[144:147], s[8:9] offset:2048
	global_store_dwordx4 v176, v[148:151], s[8:9] offset:3072
	v_pk_add_f32 v[152:153], v[136:137], v[138:139]
	v_pk_add_f32 v[152:153], v[152:153], v[140:141]
	v_pk_add_f32 v[152:153], v[152:153], v[142:143]
	v_pk_add_f32 v[152:153], v[152:153], v[144:145]
	v_pk_add_f32 v[152:153], v[152:153], v[146:147]
	v_pk_add_f32 v[152:153], v[152:153], v[148:149]
	v_pk_add_f32 v[152:153], v[152:153], v[150:151]
	v_add_f32_e32 v170, v152, v153
	s_nop 1
	v_add_f32_dpp v168, v170, v170 quad_perm:[1,0,3,2] row_mask:0xf bank_mask:0xf
	s_nop 1
	v_add_f32_dpp v168, v168, v168 quad_perm:[2,3,0,1] row_mask:0xf bank_mask:0xf
	s_nop 1
	v_add_f32_dpp v168, v168, v168 row_half_mirror row_mask:0xf bank_mask:0xf
	s_nop 1
	v_add_f32_dpp v168, v168, v168 row_mirror row_mask:0xf bank_mask:0xf
	s_nop 1
	v_add_f32_dpp v168, v168, v168 row_bcast:15 row_mask:0xa bank_mask:0xf
	s_nop 1
	v_add_f32_dpp v168, v168, v168 row_bcast:31 row_mask:0xc bank_mask:0xf
	s_nop 1
	v_readlane_b32 s42, v168, 63
	s_nop 3
	s_mov_b32 s43, s42
	v_pk_fma_f32 v[136:137], s[42:43], v[172:173], v[136:137]
	v_pk_fma_f32 v[138:139], s[42:43], v[172:173], v[138:139]
	v_pk_fma_f32 v[140:141], s[42:43], v[172:173], v[140:141]
	v_pk_fma_f32 v[142:143], s[42:43], v[172:173], v[142:143]
	v_pk_fma_f32 v[144:145], s[42:43], v[172:173], v[144:145]
	v_pk_fma_f32 v[146:147], s[42:43], v[172:173], v[146:147]
	v_pk_fma_f32 v[148:149], s[42:43], v[172:173], v[148:149]
	v_pk_fma_f32 v[150:151], s[42:43], v[172:173], v[150:151]
	v_pk_mul_f32 v[152:153], v[136:137], v[136:137]
	v_pk_fma_f32 v[152:153], v[138:139], v[138:139], v[152:153]
	v_pk_fma_f32 v[152:153], v[140:141], v[140:141], v[152:153]
	v_pk_fma_f32 v[152:153], v[142:143], v[142:143], v[152:153]
	v_pk_fma_f32 v[152:153], v[144:145], v[144:145], v[152:153]
	v_pk_fma_f32 v[152:153], v[146:147], v[146:147], v[152:153]
	v_pk_fma_f32 v[152:153], v[148:149], v[148:149], v[152:153]
	v_pk_fma_f32 v[152:153], v[150:151], v[150:151], v[152:153]
	v_add_f32_e32 v170, v152, v153
	s_nop 1
	v_add_f32_dpp v168, v170, v170 quad_perm:[1,0,3,2] row_mask:0xf bank_mask:0xf
	s_nop 1
	v_add_f32_dpp v168, v168, v168 quad_perm:[2,3,0,1] row_mask:0xf bank_mask:0xf
	s_nop 1
	v_add_f32_dpp v168, v168, v168 row_half_mirror row_mask:0xf bank_mask:0xf
	s_nop 1
	v_add_f32_dpp v168, v168, v168 row_mirror row_mask:0xf bank_mask:0xf
	s_nop 1
	v_add_f32_dpp v168, v168, v168 row_bcast:15 row_mask:0xa bank_mask:0xf
	s_nop 1
	v_add_f32_dpp v168, v168, v168 row_bcast:31 row_mask:0xc bank_mask:0xf
	s_nop 1
	v_readlane_b32 s42, v168, 63
	s_nop 3
	v_fma_f32 v174, s42, v178, v179
	v_rsq_f32_e32 v174, v174
	s_nop 0
	v_pk_mul_f32 v[136:137], v[136:137], v[174:175] op_sel_hi:[1,0]
	v_pk_mul_f32 v[138:139], v[138:139], v[174:175] op_sel_hi:[1,0]
	v_pk_mul_f32 v[140:141], v[140:141], v[174:175] op_sel_hi:[1,0]
	v_pk_mul_f32 v[142:143], v[142:143], v[174:175] op_sel_hi:[1,0]
	v_pk_mul_f32 v[144:145], v[144:145], v[174:175] op_sel_hi:[1,0]
	v_pk_mul_f32 v[146:147], v[146:147], v[174:175] op_sel_hi:[1,0]
	v_pk_mul_f32 v[148:149], v[148:149], v[174:175] op_sel_hi:[1,0]
	v_pk_mul_f32 v[150:151], v[150:151], v[174:175] op_sel_hi:[1,0]
	v_pk_fma_f32 v[136:137], v[136:137], v[32:33], v[48:49]
	v_pk_fma_f32 v[138:139], v[138:139], v[34:35], v[50:51]
	v_pk_fma_f32 v[140:141], v[140:141], v[36:37], v[52:53]
	v_pk_fma_f32 v[142:143], v[142:143], v[38:39], v[54:55]
	v_pk_fma_f32 v[144:145], v[144:145], v[40:41], v[56:57]
	v_pk_fma_f32 v[146:147], v[146:147], v[42:43], v[58:59]
	v_pk_fma_f32 v[148:149], v[148:149], v[44:45], v[60:61]
	v_pk_fma_f32 v[150:151], v[150:151], v[46:47], v[62:63]
	v_cvt_pk_bf16_f32 v152, v136, v137
	v_cvt_pk_bf16_f32 v153, v138, v139
	v_cvt_pk_bf16_f32 v154, v140, v141
	v_cvt_pk_bf16_f32 v155, v142, v143
	v_cvt_pk_bf16_f32 v156, v144, v145
	v_cvt_pk_bf16_f32 v157, v146, v147
	v_cvt_pk_bf16_f32 v158, v148, v149
	v_cvt_pk_bf16_f32 v159, v150, v151
	global_store_dwordx2 v177, v[152:153], s[12:13] offset:0
	global_store_dwordx2 v177, v[154:155], s[12:13] offset:512
	global_store_dwordx2 v177, v[156:157], s[12:13] offset:1024
	global_store_dwordx2 v177, v[158:159], s[12:13] offset:1536
	s_add_u32 s8, s8, 0x1000
	s_addc_u32 s9, s9, 0
	s_add_u32 s12, s12, 0x800
	s_addc_u32 s13, s13, 0
	global_load_dwordx4 v[80:83], v176, s[2:3] offset:0
	global_load_dwordx4 v[84:87], v176, s[2:3] offset:1024
	global_load_dwordx4 v[88:91], v176, s[2:3] offset:2048
	global_load_dwordx4 v[92:95], v176, s[2:3] offset:3072
	global_load_dwordx2 v[120:121], v177, s[6:7] offset:0
	global_load_dwordx2 v[122:123], v177, s[6:7] offset:512
	global_load_dwordx2 v[124:125], v177, s[6:7] offset:1024
	global_load_dwordx2 v[126:127], v177, s[6:7] offset:1536
	s_add_u32 s2, s2, 0x1000
	s_addc_u32 s3, s3, 0
	s_add_u32 s6, s6, 0x800
	s_addc_u32 s7, s7, 0
	s_waitcnt vmcnt(32)
	v_lshlrev_b32_e32 v136, 16, v128
	v_and_b32_e32 v137, 0xffff0000, v128
	v_lshlrev_b32_e32 v138, 16, v129
	v_and_b32_e32 v139, 0xffff0000, v129
	v_lshlrev_b32_e32 v140, 16, v130
	v_and_b32_e32 v141, 0xffff0000, v130
	v_lshlrev_b32_e32 v142, 16, v131
	v_and_b32_e32 v143, 0xffff0000, v131
	v_lshlrev_b32_e32 v144, 16, v132
	v_and_b32_e32 v145, 0xffff0000, v132
	v_lshlrev_b32_e32 v146, 16, v133
	v_and_b32_e32 v147, 0xffff0000, v133
	v_lshlrev_b32_e32 v148, 16, v134
	v_and_b32_e32 v149, 0xffff0000, v134
	v_lshlrev_b32_e32 v150, 16, v135
	v_and_b32_e32 v151, 0xffff0000, v135
	v_pk_fma_f32 v[136:137], v[96:97], s[44:45], v[136:137]
	v_pk_fma_f32 v[138:139], v[98:99], s[44:45], v[138:139]
	v_pk_fma_f32 v[140:141], v[100:101], s[44:45], v[140:141]
	v_pk_fma_f32 v[142:143], v[102:103], s[44:45], v[142:143]
	v_pk_fma_f32 v[144:145], v[104:105], s[44:45], v[144:145]
	v_pk_fma_f32 v[146:147], v[106:107], s[44:45], v[146:147]
	v_pk_fma_f32 v[148:149], v[108:109], s[44:45], v[148:149]
	v_pk_fma_f32 v[150:151], v[110:111], s[44:45], v[150:151]
	v_pk_add_f32 v[152:153], v[136:137], v[138:139]
	v_pk_add_f32 v[152:153], v[152:153], v[140:141]
	v_pk_add_f32 v[152:153], v[152:153], v[142:143]
	v_pk_add_f32 v[152:153], v[152:153], v[144:145]
	v_pk_add_f32 v[152:153], v[152:153], v[146:147]
	v_pk_add_f32 v[152:153], v[152:153], v[148:149]
	v_pk_add_f32 v[152:153], v[152:153], v[150:151]
	v_add_f32_e32 v170, v152, v153
	s_nop 1
	v_add_f32_dpp v168, v170, v170 quad_perm:[1,0,3,2] row_mask:0xf bank_mask:0xf
	s_nop 1
	v_add_f32_dpp v168, v168, v168 quad_perm:[2,3,0,1] row_mask:0xf bank_mask:0xf
	s_nop 1
	v_add_f32_dpp v168, v168, v168 row_half_mirror row_mask:0xf bank_mask:0xf
	s_nop 1
	v_add_f32_dpp v168, v168, v168 row_mirror row_mask:0xf bank_mask:0xf
	s_nop 1
	v_add_f32_dpp v168, v168, v168 row_bcast:15 row_mask:0xa bank_mask:0xf
	s_nop 1
	v_add_f32_dpp v168, v168, v168 row_bcast:31 row_mask:0xc bank_mask:0xf
	s_nop 1
	v_readlane_b32 s42, v168, 63
	s_nop 3
	s_mov_b32 s43, s42
	v_pk_fma_f32 v[136:137], s[42:43], v[172:173], v[136:137]
	v_pk_fma_f32 v[138:139], s[42:43], v[172:173], v[138:139]
	v_pk_fma_f32 v[140:141], s[42:43], v[172:173], v[140:141]
	v_pk_fma_f32 v[142:143], s[42:43], v[172:173], v[142:143]
	v_pk_fma_f32 v[144:145], s[42:43], v[172:173], v[144:145]
	v_pk_fma_f32 v[146:147], s[42:43], v[172:173], v[146:147]
	v_pk_fma_f32 v[148:149], s[42:43], v[172:173], v[148:149]
	v_pk_fma_f32 v[150:151], s[42:43], v[172:173], v[150:151]
	v_pk_mul_f32 v[152:153], v[136:137], v[136:137]
	v_pk_fma_f32 v[152:153], v[138:139], v[138:139], v[152:153]
	v_pk_fma_f32 v[152:153], v[140:141], v[140:141], v[152:153]
	v_pk_fma_f32 v[152:153], v[142:143], v[142:143], v[152:153]
	v_pk_fma_f32 v[152:153], v[144:145], v[144:145], v[152:153]
	v_pk_fma_f32 v[152:153], v[146:147], v[146:147], v[152:153]
	v_pk_fma_f32 v[152:153], v[148:149], v[148:149], v[152:153]
	v_pk_fma_f32 v[152:153], v[150:151], v[150:151], v[152:153]
	v_add_f32_e32 v170, v152, v153
	s_nop 1
	v_add_f32_dpp v168, v170, v170 quad_perm:[1,0,3,2] row_mask:0xf bank_mask:0xf
	s_nop 1
	v_add_f32_dpp v168, v168, v168 quad_perm:[2,3,0,1] row_mask:0xf bank_mask:0xf
	s_nop 1
	v_add_f32_dpp v168, v168, v168 row_half_mirror row_mask:0xf bank_mask:0xf
	s_nop 1
	v_add_f32_dpp v168, v168, v168 row_mirror row_mask:0xf bank_mask:0xf
	s_nop 1
	v_add_f32_dpp v168, v168, v168 row_bcast:15 row_mask:0xa bank_mask:0xf
	s_nop 1
	v_add_f32_dpp v168, v168, v168 row_bcast:31 row_mask:0xc bank_mask:0xf
	s_nop 1
	v_readlane_b32 s42, v168, 63
	s_nop 3
	v_fma_f32 v174, s42, v178, v179
	v_rsq_f32_e32 v174, v174
	s_nop 0
	v_pk_mul_f32 v[136:137], v[136:137], v[174:175] op_sel_hi:[1,0]
	v_pk_mul_f32 v[138:139], v[138:139], v[174:175] op_sel_hi:[1,0]
	v_pk_mul_f32 v[140:141], v[140:141], v[174:175] op_sel_hi:[1,0]
	v_pk_mul_f32 v[142:143], v[142:143], v[174:175] op_sel_hi:[1,0]
	v_pk_mul_f32 v[144:145], v[144:145], v[174:175] op_sel_hi:[1,0]
	v_pk_mul_f32 v[146:147], v[146:147], v[174:175] op_sel_hi:[1,0]
	v_pk_mul_f32 v[148:149], v[148:149], v[174:175] op_sel_hi:[1,0]
	v_pk_mul_f32 v[150:151], v[150:151], v[174:175] op_sel_hi:[1,0]
	v_pk_fma_f32 v[136:137], v[136:137], v[0:1], v[16:17]
	v_pk_fma_f32 v[138:139], v[138:139], v[2:3], v[18:19]
	v_pk_fma_f32 v[140:141], v[140:141], v[4:5], v[20:21]
	v_pk_fma_f32 v[142:143], v[142:143], v[6:7], v[22:23]
	v_pk_fma_f32 v[144:145], v[144:145], v[8:9], v[24:25]
	v_pk_fma_f32 v[146:147], v[146:147], v[10:11], v[26:27]
	v_pk_fma_f32 v[148:149], v[148:149], v[12:13], v[28:29]
	v_pk_fma_f32 v[150:151], v[150:151], v[14:15], v[30:31]
	global_store_dwordx4 v176, v[136:139], s[8:9] offset:0
	global_store_dwordx4 v176, v[140:143], s[8:9] offset:1024
	global_store_dwordx4 v176, v[144:147], s[8:9] offset:2048
	global_store_dwordx4 v176, v[148:151], s[8:9] offset:3072
	v_pk_add_f32 v[152:153], v[136:137], v[138:139]
	v_pk_add_f32 v[152:153], v[152:153], v[140:141]
	v_pk_add_f32 v[152:153], v[152:153], v[142:143]
	v_pk_add_f32 v[152:153], v[152:153], v[144:145]
	v_pk_add_f32 v[152:153], v[152:153], v[146:147]
	v_pk_add_f32 v[152:153], v[152:153], v[148:149]
	v_pk_add_f32 v[152:153], v[152:153], v[150:151]
	v_add_f32_e32 v170, v152, v153
	s_nop 1
	v_add_f32_dpp v168, v170, v170 quad_perm:[1,0,3,2] row_mask:0xf bank_mask:0xf
	s_nop 1
	v_add_f32_dpp v168, v168, v168 quad_perm:[2,3,0,1] row_mask:0xf bank_mask:0xf
	s_nop 1
	v_add_f32_dpp v168, v168, v168 row_half_mirror row_mask:0xf bank_mask:0xf
	s_nop 1
	v_add_f32_dpp v168, v168, v168 row_mirror row_mask:0xf bank_mask:0xf
	s_nop 1
	v_add_f32_dpp v168, v168, v168 row_bcast:15 row_mask:0xa bank_mask:0xf
	s_nop 1
	v_add_f32_dpp v168, v168, v168 row_bcast:31 row_mask:0xc bank_mask:0xf
	s_nop 1
	v_readlane_b32 s42, v168, 63
	s_nop 3
	s_mov_b32 s43, s42
	v_pk_fma_f32 v[136:137], s[42:43], v[172:173], v[136:137]
	v_pk_fma_f32 v[138:139], s[42:43], v[172:173], v[138:139]
	v_pk_fma_f32 v[140:141], s[42:43], v[172:173], v[140:141]
	v_pk_fma_f32 v[142:143], s[42:43], v[172:173], v[142:143]
	v_pk_fma_f32 v[144:145], s[42:43], v[172:173], v[144:145]
	v_pk_fma_f32 v[146:147], s[42:43], v[172:173], v[146:147]
	v_pk_fma_f32 v[148:149], s[42:43], v[172:173], v[148:149]
	v_pk_fma_f32 v[150:151], s[42:43], v[172:173], v[150:151]
	v_pk_mul_f32 v[152:153], v[136:137], v[136:137]
	v_pk_fma_f32 v[152:153], v[138:139], v[138:139], v[152:153]
	v_pk_fma_f32 v[152:153], v[140:141], v[140:141], v[152:153]
	v_pk_fma_f32 v[152:153], v[142:143], v[142:143], v[152:153]
	v_pk_fma_f32 v[152:153], v[144:145], v[144:145], v[152:153]
	v_pk_fma_f32 v[152:153], v[146:147], v[146:147], v[152:153]
	v_pk_fma_f32 v[152:153], v[148:149], v[148:149], v[152:153]
	v_pk_fma_f32 v[152:153], v[150:151], v[150:151], v[152:153]
	v_add_f32_e32 v170, v152, v153
	s_nop 1
	v_add_f32_dpp v168, v170, v170 quad_perm:[1,0,3,2] row_mask:0xf bank_mask:0xf
	s_nop 1
	v_add_f32_dpp v168, v168, v168 quad_perm:[2,3,0,1] row_mask:0xf bank_mask:0xf
	s_nop 1
	v_add_f32_dpp v168, v168, v168 row_half_mirror row_mask:0xf bank_mask:0xf
	s_nop 1
	v_add_f32_dpp v168, v168, v168 row_mirror row_mask:0xf bank_mask:0xf
	s_nop 1
	v_add_f32_dpp v168, v168, v168 row_bcast:15 row_mask:0xa bank_mask:0xf
	s_nop 1
	v_add_f32_dpp v168, v168, v168 row_bcast:31 row_mask:0xc bank_mask:0xf
	s_nop 1
	v_readlane_b32 s42, v168, 63
	s_nop 3
	v_fma_f32 v174, s42, v178, v179
	v_rsq_f32_e32 v174, v174
	s_nop 0
	v_pk_mul_f32 v[136:137], v[136:137], v[174:175] op_sel_hi:[1,0]
	v_pk_mul_f32 v[138:139], v[138:139], v[174:175] op_sel_hi:[1,0]
	v_pk_mul_f32 v[140:141], v[140:141], v[174:175] op_sel_hi:[1,0]
	v_pk_mul_f32 v[142:143], v[142:143], v[174:175] op_sel_hi:[1,0]
	v_pk_mul_f32 v[144:145], v[144:145], v[174:175] op_sel_hi:[1,0]
	v_pk_mul_f32 v[146:147], v[146:147], v[174:175] op_sel_hi:[1,0]
	v_pk_mul_f32 v[148:149], v[148:149], v[174:175] op_sel_hi:[1,0]
	v_pk_mul_f32 v[150:151], v[150:151], v[174:175] op_sel_hi:[1,0]
	v_pk_fma_f32 v[136:137], v[136:137], v[32:33], v[48:49]
	v_pk_fma_f32 v[138:139], v[138:139], v[34:35], v[50:51]
	v_pk_fma_f32 v[140:141], v[140:141], v[36:37], v[52:53]
	v_pk_fma_f32 v[142:143], v[142:143], v[38:39], v[54:55]
	v_pk_fma_f32 v[144:145], v[144:145], v[40:41], v[56:57]
	v_pk_fma_f32 v[146:147], v[146:147], v[42:43], v[58:59]
	v_pk_fma_f32 v[148:149], v[148:149], v[44:45], v[60:61]
	v_pk_fma_f32 v[150:151], v[150:151], v[46:47], v[62:63]
	v_cvt_pk_bf16_f32 v152, v136, v137
	v_cvt_pk_bf16_f32 v153, v138, v139
	v_cvt_pk_bf16_f32 v154, v140, v141
	v_cvt_pk_bf16_f32 v155, v142, v143
	v_cvt_pk_bf16_f32 v156, v144, v145
	v_cvt_pk_bf16_f32 v157, v146, v147
	v_cvt_pk_bf16_f32 v158, v148, v149
	v_cvt_pk_bf16_f32 v159, v150, v151
	global_store_dwordx2 v177, v[152:153], s[12:13] offset:0
	global_store_dwordx2 v177, v[154:155], s[12:13] offset:512
	global_store_dwordx2 v177, v[156:157], s[12:13] offset:1024
	global_store_dwordx2 v177, v[158:159], s[12:13] offset:1536
	s_add_u32 s8, s8, 0x1000
	s_addc_u32 s9, s9, 0
	s_add_u32 s12, s12, 0x800
	s_addc_u32 s13, s13, 0
	global_load_dwordx4 v[96:99], v176, s[2:3] offset:0
	global_load_dwordx4 v[100:103], v176, s[2:3] offset:1024
	global_load_dwordx4 v[104:107], v176, s[2:3] offset:2048
	global_load_dwordx4 v[108:111], v176, s[2:3] offset:3072
	global_load_dwordx2 v[128:129], v177, s[6:7] offset:0
	global_load_dwordx2 v[130:131], v177, s[6:7] offset:512
	global_load_dwordx2 v[132:133], v177, s[6:7] offset:1024
	global_load_dwordx2 v[134:135], v177, s[6:7] offset:1536
	s_add_u32 s2, s2, 0x1000
	s_addc_u32 s3, s3, 0
	s_add_u32 s6, s6, 0x800
	s_addc_u32 s7, s7, 0
	s_waitcnt vmcnt(32)
	v_lshlrev_b32_e32 v136, 16, v112
	v_and_b32_e32 v137, 0xffff0000, v112
	v_lshlrev_b32_e32 v138, 16, v113
	v_and_b32_e32 v139, 0xffff0000, v113
	v_lshlrev_b32_e32 v140, 16, v114
	v_and_b32_e32 v141, 0xffff0000, v114
	v_lshlrev_b32_e32 v142, 16, v115
	v_and_b32_e32 v143, 0xffff0000, v115
	v_lshlrev_b32_e32 v144, 16, v116
	v_and_b32_e32 v145, 0xffff0000, v116
	v_lshlrev_b32_e32 v146, 16, v117
	v_and_b32_e32 v147, 0xffff0000, v117
	v_lshlrev_b32_e32 v148, 16, v118
	v_and_b32_e32 v149, 0xffff0000, v118
	v_lshlrev_b32_e32 v150, 16, v119
	v_and_b32_e32 v151, 0xffff0000, v119
	v_pk_fma_f32 v[136:137], v[64:65], s[44:45], v[136:137]
	v_pk_fma_f32 v[138:139], v[66:67], s[44:45], v[138:139]
	v_pk_fma_f32 v[140:141], v[68:69], s[44:45], v[140:141]
	v_pk_fma_f32 v[142:143], v[70:71], s[44:45], v[142:143]
	v_pk_fma_f32 v[144:145], v[72:73], s[44:45], v[144:145]
	v_pk_fma_f32 v[146:147], v[74:75], s[44:45], v[146:147]
	v_pk_fma_f32 v[148:149], v[76:77], s[44:45], v[148:149]
	v_pk_fma_f32 v[150:151], v[78:79], s[44:45], v[150:151]
	v_pk_add_f32 v[152:153], v[136:137], v[138:139]
	v_pk_add_f32 v[152:153], v[152:153], v[140:141]
	v_pk_add_f32 v[152:153], v[152:153], v[142:143]
	v_pk_add_f32 v[152:153], v[152:153], v[144:145]
	v_pk_add_f32 v[152:153], v[152:153], v[146:147]
	v_pk_add_f32 v[152:153], v[152:153], v[148:149]
	v_pk_add_f32 v[152:153], v[152:153], v[150:151]
	v_add_f32_e32 v170, v152, v153
	s_nop 1
	v_add_f32_dpp v168, v170, v170 quad_perm:[1,0,3,2] row_mask:0xf bank_mask:0xf
	s_nop 1
	v_add_f32_dpp v168, v168, v168 quad_perm:[2,3,0,1] row_mask:0xf bank_mask:0xf
	s_nop 1
	v_add_f32_dpp v168, v168, v168 row_half_mirror row_mask:0xf bank_mask:0xf
	s_nop 1
	v_add_f32_dpp v168, v168, v168 row_mirror row_mask:0xf bank_mask:0xf
	s_nop 1
	v_add_f32_dpp v168, v168, v168 row_bcast:15 row_mask:0xa bank_mask:0xf
	s_nop 1
	v_add_f32_dpp v168, v168, v168 row_bcast:31 row_mask:0xc bank_mask:0xf
	s_nop 1
	v_readlane_b32 s42, v168, 63
	s_nop 3
	s_mov_b32 s43, s42
	v_pk_fma_f32 v[136:137], s[42:43], v[172:173], v[136:137]
	v_pk_fma_f32 v[138:139], s[42:43], v[172:173], v[138:139]
	v_pk_fma_f32 v[140:141], s[42:43], v[172:173], v[140:141]
	v_pk_fma_f32 v[142:143], s[42:43], v[172:173], v[142:143]
	v_pk_fma_f32 v[144:145], s[42:43], v[172:173], v[144:145]
	v_pk_fma_f32 v[146:147], s[42:43], v[172:173], v[146:147]
	v_pk_fma_f32 v[148:149], s[42:43], v[172:173], v[148:149]
	v_pk_fma_f32 v[150:151], s[42:43], v[172:173], v[150:151]
	v_pk_mul_f32 v[152:153], v[136:137], v[136:137]
	v_pk_fma_f32 v[152:153], v[138:139], v[138:139], v[152:153]
	v_pk_fma_f32 v[152:153], v[140:141], v[140:141], v[152:153]
	v_pk_fma_f32 v[152:153], v[142:143], v[142:143], v[152:153]
	v_pk_fma_f32 v[152:153], v[144:145], v[144:145], v[152:153]
	v_pk_fma_f32 v[152:153], v[146:147], v[146:147], v[152:153]
	v_pk_fma_f32 v[152:153], v[148:149], v[148:149], v[152:153]
	v_pk_fma_f32 v[152:153], v[150:151], v[150:151], v[152:153]
	v_add_f32_e32 v170, v152, v153
	s_nop 1
	v_add_f32_dpp v168, v170, v170 quad_perm:[1,0,3,2] row_mask:0xf bank_mask:0xf
	s_nop 1
	v_add_f32_dpp v168, v168, v168 quad_perm:[2,3,0,1] row_mask:0xf bank_mask:0xf
	s_nop 1
	v_add_f32_dpp v168, v168, v168 row_half_mirror row_mask:0xf bank_mask:0xf
	s_nop 1
	v_add_f32_dpp v168, v168, v168 row_mirror row_mask:0xf bank_mask:0xf
	s_nop 1
	v_add_f32_dpp v168, v168, v168 row_bcast:15 row_mask:0xa bank_mask:0xf
	s_nop 1
	v_add_f32_dpp v168, v168, v168 row_bcast:31 row_mask:0xc bank_mask:0xf
	s_nop 1
	v_readlane_b32 s42, v168, 63
	s_nop 3
	v_fma_f32 v174, s42, v178, v179
	v_rsq_f32_e32 v174, v174
	s_nop 0
	v_pk_mul_f32 v[136:137], v[136:137], v[174:175] op_sel_hi:[1,0]
	v_pk_mul_f32 v[138:139], v[138:139], v[174:175] op_sel_hi:[1,0]
	v_pk_mul_f32 v[140:141], v[140:141], v[174:175] op_sel_hi:[1,0]
	v_pk_mul_f32 v[142:143], v[142:143], v[174:175] op_sel_hi:[1,0]
	v_pk_mul_f32 v[144:145], v[144:145], v[174:175] op_sel_hi:[1,0]
	v_pk_mul_f32 v[146:147], v[146:147], v[174:175] op_sel_hi:[1,0]
	v_pk_mul_f32 v[148:149], v[148:149], v[174:175] op_sel_hi:[1,0]
	v_pk_mul_f32 v[150:151], v[150:151], v[174:175] op_sel_hi:[1,0]
	v_pk_fma_f32 v[136:137], v[136:137], v[0:1], v[16:17]
	v_pk_fma_f32 v[138:139], v[138:139], v[2:3], v[18:19]
	v_pk_fma_f32 v[140:141], v[140:141], v[4:5], v[20:21]
	v_pk_fma_f32 v[142:143], v[142:143], v[6:7], v[22:23]
	v_pk_fma_f32 v[144:145], v[144:145], v[8:9], v[24:25]
	v_pk_fma_f32 v[146:147], v[146:147], v[10:11], v[26:27]
	v_pk_fma_f32 v[148:149], v[148:149], v[12:13], v[28:29]
	v_pk_fma_f32 v[150:151], v[150:151], v[14:15], v[30:31]
	global_store_dwordx4 v176, v[136:139], s[8:9] offset:0
	global_store_dwordx4 v176, v[140:143], s[8:9] offset:1024
	global_store_dwordx4 v176, v[144:147], s[8:9] offset:2048
	global_store_dwordx4 v176, v[148:151], s[8:9] offset:3072
	v_pk_add_f32 v[152:153], v[136:137], v[138:139]
	v_pk_add_f32 v[152:153], v[152:153], v[140:141]
	v_pk_add_f32 v[152:153], v[152:153], v[142:143]
	v_pk_add_f32 v[152:153], v[152:153], v[144:145]
	v_pk_add_f32 v[152:153], v[152:153], v[146:147]
	v_pk_add_f32 v[152:153], v[152:153], v[148:149]
	v_pk_add_f32 v[152:153], v[152:153], v[150:151]
	v_add_f32_e32 v170, v152, v153
	s_nop 1
	v_add_f32_dpp v168, v170, v170 quad_perm:[1,0,3,2] row_mask:0xf bank_mask:0xf
	s_nop 1
	v_add_f32_dpp v168, v168, v168 quad_perm:[2,3,0,1] row_mask:0xf bank_mask:0xf
	s_nop 1
	v_add_f32_dpp v168, v168, v168 row_half_mirror row_mask:0xf bank_mask:0xf
	s_nop 1
	v_add_f32_dpp v168, v168, v168 row_mirror row_mask:0xf bank_mask:0xf
	s_nop 1
	v_add_f32_dpp v168, v168, v168 row_bcast:15 row_mask:0xa bank_mask:0xf
	s_nop 1
	v_add_f32_dpp v168, v168, v168 row_bcast:31 row_mask:0xc bank_mask:0xf
	s_nop 1
	v_readlane_b32 s42, v168, 63
	s_nop 3
	s_mov_b32 s43, s42
	v_pk_fma_f32 v[136:137], s[42:43], v[172:173], v[136:137]
	v_pk_fma_f32 v[138:139], s[42:43], v[172:173], v[138:139]
	v_pk_fma_f32 v[140:141], s[42:43], v[172:173], v[140:141]
	v_pk_fma_f32 v[142:143], s[42:43], v[172:173], v[142:143]
	v_pk_fma_f32 v[144:145], s[42:43], v[172:173], v[144:145]
	v_pk_fma_f32 v[146:147], s[42:43], v[172:173], v[146:147]
	v_pk_fma_f32 v[148:149], s[42:43], v[172:173], v[148:149]
	v_pk_fma_f32 v[150:151], s[42:43], v[172:173], v[150:151]
	v_pk_mul_f32 v[152:153], v[136:137], v[136:137]
	v_pk_fma_f32 v[152:153], v[138:139], v[138:139], v[152:153]
	v_pk_fma_f32 v[152:153], v[140:141], v[140:141], v[152:153]
	v_pk_fma_f32 v[152:153], v[142:143], v[142:143], v[152:153]
	v_pk_fma_f32 v[152:153], v[144:145], v[144:145], v[152:153]
	v_pk_fma_f32 v[152:153], v[146:147], v[146:147], v[152:153]
	v_pk_fma_f32 v[152:153], v[148:149], v[148:149], v[152:153]
	v_pk_fma_f32 v[152:153], v[150:151], v[150:151], v[152:153]
	v_add_f32_e32 v170, v152, v153
	s_nop 1
	v_add_f32_dpp v168, v170, v170 quad_perm:[1,0,3,2] row_mask:0xf bank_mask:0xf
	s_nop 1
	v_add_f32_dpp v168, v168, v168 quad_perm:[2,3,0,1] row_mask:0xf bank_mask:0xf
	s_nop 1
	v_add_f32_dpp v168, v168, v168 row_half_mirror row_mask:0xf bank_mask:0xf
	s_nop 1
	v_add_f32_dpp v168, v168, v168 row_mirror row_mask:0xf bank_mask:0xf
	s_nop 1
	v_add_f32_dpp v168, v168, v168 row_bcast:15 row_mask:0xa bank_mask:0xf
	s_nop 1
	v_add_f32_dpp v168, v168, v168 row_bcast:31 row_mask:0xc bank_mask:0xf
	s_nop 1
	v_readlane_b32 s42, v168, 63
	s_nop 3
	v_fma_f32 v174, s42, v178, v179
	v_rsq_f32_e32 v174, v174
	s_nop 0
	v_pk_mul_f32 v[136:137], v[136:137], v[174:175] op_sel_hi:[1,0]
	v_pk_mul_f32 v[138:139], v[138:139], v[174:175] op_sel_hi:[1,0]
	v_pk_mul_f32 v[140:141], v[140:141], v[174:175] op_sel_hi:[1,0]
	v_pk_mul_f32 v[142:143], v[142:143], v[174:175] op_sel_hi:[1,0]
	v_pk_mul_f32 v[144:145], v[144:145], v[174:175] op_sel_hi:[1,0]
	v_pk_mul_f32 v[146:147], v[146:147], v[174:175] op_sel_hi:[1,0]
	v_pk_mul_f32 v[148:149], v[148:149], v[174:175] op_sel_hi:[1,0]
	v_pk_mul_f32 v[150:151], v[150:151], v[174:175] op_sel_hi:[1,0]
	v_pk_fma_f32 v[136:137], v[136:137], v[32:33], v[48:49]
	v_pk_fma_f32 v[138:139], v[138:139], v[34:35], v[50:51]
	v_pk_fma_f32 v[140:141], v[140:141], v[36:37], v[52:53]
	v_pk_fma_f32 v[142:143], v[142:143], v[38:39], v[54:55]
	v_pk_fma_f32 v[144:145], v[144:145], v[40:41], v[56:57]
	v_pk_fma_f32 v[146:147], v[146:147], v[42:43], v[58:59]
	v_pk_fma_f32 v[148:149], v[148:149], v[44:45], v[60:61]
	v_pk_fma_f32 v[150:151], v[150:151], v[46:47], v[62:63]
	v_cvt_pk_bf16_f32 v152, v136, v137
	v_cvt_pk_bf16_f32 v153, v138, v139
	v_cvt_pk_bf16_f32 v154, v140, v141
	v_cvt_pk_bf16_f32 v155, v142, v143
	v_cvt_pk_bf16_f32 v156, v144, v145
	v_cvt_pk_bf16_f32 v157, v146, v147
	v_cvt_pk_bf16_f32 v158, v148, v149
	v_cvt_pk_bf16_f32 v159, v150, v151
	global_store_dwordx2 v177, v[152:153], s[12:13] offset:0
	global_store_dwordx2 v177, v[154:155], s[12:13] offset:512
	global_store_dwordx2 v177, v[156:157], s[12:13] offset:1024
	global_store_dwordx2 v177, v[158:159], s[12:13] offset:1536
	s_add_u32 s8, s8, 0x1000
	s_addc_u32 s9, s9, 0
	s_add_u32 s12, s12, 0x800
	s_addc_u32 s13, s13, 0
	global_load_dwordx4 v[64:67], v176, s[2:3] offset:0
	global_load_dwordx4 v[68:71], v176, s[2:3] offset:1024
	global_load_dwordx4 v[72:75], v176, s[2:3] offset:2048
	global_load_dwordx4 v[76:79], v176, s[2:3] offset:3072
	global_load_dwordx2 v[112:113], v177, s[6:7] offset:0
	global_load_dwordx2 v[114:115], v177, s[6:7] offset:512
	global_load_dwordx2 v[116:117], v177, s[6:7] offset:1024
	global_load_dwordx2 v[118:119], v177, s[6:7] offset:1536
	s_add_u32 s2, s2, 0x1000
	s_addc_u32 s3, s3, 0
	s_add_u32 s6, s6, 0x800
	s_addc_u32 s7, s7, 0
	s_waitcnt vmcnt(32)
	v_lshlrev_b32_e32 v136, 16, v120
	v_and_b32_e32 v137, 0xffff0000, v120
	v_lshlrev_b32_e32 v138, 16, v121
	v_and_b32_e32 v139, 0xffff0000, v121
	v_lshlrev_b32_e32 v140, 16, v122
	v_and_b32_e32 v141, 0xffff0000, v122
	v_lshlrev_b32_e32 v142, 16, v123
	v_and_b32_e32 v143, 0xffff0000, v123
	v_lshlrev_b32_e32 v144, 16, v124
	v_and_b32_e32 v145, 0xffff0000, v124
	v_lshlrev_b32_e32 v146, 16, v125
	v_and_b32_e32 v147, 0xffff0000, v125
	v_lshlrev_b32_e32 v148, 16, v126
	v_and_b32_e32 v149, 0xffff0000, v126
	v_lshlrev_b32_e32 v150, 16, v127
	v_and_b32_e32 v151, 0xffff0000, v127
	v_pk_fma_f32 v[136:137], v[80:81], s[44:45], v[136:137]
	v_pk_fma_f32 v[138:139], v[82:83], s[44:45], v[138:139]
	v_pk_fma_f32 v[140:141], v[84:85], s[44:45], v[140:141]
	v_pk_fma_f32 v[142:143], v[86:87], s[44:45], v[142:143]
	v_pk_fma_f32 v[144:145], v[88:89], s[44:45], v[144:145]
	v_pk_fma_f32 v[146:147], v[90:91], s[44:45], v[146:147]
	v_pk_fma_f32 v[148:149], v[92:93], s[44:45], v[148:149]
	v_pk_fma_f32 v[150:151], v[94:95], s[44:45], v[150:151]
	v_pk_add_f32 v[152:153], v[136:137], v[138:139]
	v_pk_add_f32 v[152:153], v[152:153], v[140:141]
	v_pk_add_f32 v[152:153], v[152:153], v[142:143]
	v_pk_add_f32 v[152:153], v[152:153], v[144:145]
	v_pk_add_f32 v[152:153], v[152:153], v[146:147]
	v_pk_add_f32 v[152:153], v[152:153], v[148:149]
	v_pk_add_f32 v[152:153], v[152:153], v[150:151]
	v_add_f32_e32 v170, v152, v153
	s_nop 1
	v_add_f32_dpp v168, v170, v170 quad_perm:[1,0,3,2] row_mask:0xf bank_mask:0xf
	s_nop 1
	v_add_f32_dpp v168, v168, v168 quad_perm:[2,3,0,1] row_mask:0xf bank_mask:0xf
	s_nop 1
	v_add_f32_dpp v168, v168, v168 row_half_mirror row_mask:0xf bank_mask:0xf
	s_nop 1
	v_add_f32_dpp v168, v168, v168 row_mirror row_mask:0xf bank_mask:0xf
	s_nop 1
	v_add_f32_dpp v168, v168, v168 row_bcast:15 row_mask:0xa bank_mask:0xf
	s_nop 1
	v_add_f32_dpp v168, v168, v168 row_bcast:31 row_mask:0xc bank_mask:0xf
	s_nop 1
	v_readlane_b32 s42, v168, 63
	s_nop 3
	s_mov_b32 s43, s42
	v_pk_fma_f32 v[136:137], s[42:43], v[172:173], v[136:137]
	v_pk_fma_f32 v[138:139], s[42:43], v[172:173], v[138:139]
	v_pk_fma_f32 v[140:141], s[42:43], v[172:173], v[140:141]
	v_pk_fma_f32 v[142:143], s[42:43], v[172:173], v[142:143]
	v_pk_fma_f32 v[144:145], s[42:43], v[172:173], v[144:145]
	v_pk_fma_f32 v[146:147], s[42:43], v[172:173], v[146:147]
	v_pk_fma_f32 v[148:149], s[42:43], v[172:173], v[148:149]
	v_pk_fma_f32 v[150:151], s[42:43], v[172:173], v[150:151]
	v_pk_mul_f32 v[152:153], v[136:137], v[136:137]
	v_pk_fma_f32 v[152:153], v[138:139], v[138:139], v[152:153]
	v_pk_fma_f32 v[152:153], v[140:141], v[140:141], v[152:153]
	v_pk_fma_f32 v[152:153], v[142:143], v[142:143], v[152:153]
	v_pk_fma_f32 v[152:153], v[144:145], v[144:145], v[152:153]
	v_pk_fma_f32 v[152:153], v[146:147], v[146:147], v[152:153]
	v_pk_fma_f32 v[152:153], v[148:149], v[148:149], v[152:153]
	v_pk_fma_f32 v[152:153], v[150:151], v[150:151], v[152:153]
	v_add_f32_e32 v170, v152, v153
	s_nop 1
	v_add_f32_dpp v168, v170, v170 quad_perm:[1,0,3,2] row_mask:0xf bank_mask:0xf
	s_nop 1
	v_add_f32_dpp v168, v168, v168 quad_perm:[2,3,0,1] row_mask:0xf bank_mask:0xf
	s_nop 1
	v_add_f32_dpp v168, v168, v168 row_half_mirror row_mask:0xf bank_mask:0xf
	s_nop 1
	v_add_f32_dpp v168, v168, v168 row_mirror row_mask:0xf bank_mask:0xf
	s_nop 1
	v_add_f32_dpp v168, v168, v168 row_bcast:15 row_mask:0xa bank_mask:0xf
	s_nop 1
	v_add_f32_dpp v168, v168, v168 row_bcast:31 row_mask:0xc bank_mask:0xf
	s_nop 1
	v_readlane_b32 s42, v168, 63
	s_nop 3
	v_fma_f32 v174, s42, v178, v179
	v_rsq_f32_e32 v174, v174
	s_nop 0
	v_pk_mul_f32 v[136:137], v[136:137], v[174:175] op_sel_hi:[1,0]
	v_pk_mul_f32 v[138:139], v[138:139], v[174:175] op_sel_hi:[1,0]
	v_pk_mul_f32 v[140:141], v[140:141], v[174:175] op_sel_hi:[1,0]
	v_pk_mul_f32 v[142:143], v[142:143], v[174:175] op_sel_hi:[1,0]
	v_pk_mul_f32 v[144:145], v[144:145], v[174:175] op_sel_hi:[1,0]
	v_pk_mul_f32 v[146:147], v[146:147], v[174:175] op_sel_hi:[1,0]
	v_pk_mul_f32 v[148:149], v[148:149], v[174:175] op_sel_hi:[1,0]
	v_pk_mul_f32 v[150:151], v[150:151], v[174:175] op_sel_hi:[1,0]
	v_pk_fma_f32 v[136:137], v[136:137], v[0:1], v[16:17]
	v_pk_fma_f32 v[138:139], v[138:139], v[2:3], v[18:19]
	v_pk_fma_f32 v[140:141], v[140:141], v[4:5], v[20:21]
	v_pk_fma_f32 v[142:143], v[142:143], v[6:7], v[22:23]
	v_pk_fma_f32 v[144:145], v[144:145], v[8:9], v[24:25]
	v_pk_fma_f32 v[146:147], v[146:147], v[10:11], v[26:27]
	v_pk_fma_f32 v[148:149], v[148:149], v[12:13], v[28:29]
	v_pk_fma_f32 v[150:151], v[150:151], v[14:15], v[30:31]
	global_store_dwordx4 v176, v[136:139], s[8:9] offset:0
	global_store_dwordx4 v176, v[140:143], s[8:9] offset:1024
	global_store_dwordx4 v176, v[144:147], s[8:9] offset:2048
	global_store_dwordx4 v176, v[148:151], s[8:9] offset:3072
	v_pk_add_f32 v[152:153], v[136:137], v[138:139]
	v_pk_add_f32 v[152:153], v[152:153], v[140:141]
	v_pk_add_f32 v[152:153], v[152:153], v[142:143]
	v_pk_add_f32 v[152:153], v[152:153], v[144:145]
	v_pk_add_f32 v[152:153], v[152:153], v[146:147]
	v_pk_add_f32 v[152:153], v[152:153], v[148:149]
	v_pk_add_f32 v[152:153], v[152:153], v[150:151]
	v_add_f32_e32 v170, v152, v153
	s_nop 1
	v_add_f32_dpp v168, v170, v170 quad_perm:[1,0,3,2] row_mask:0xf bank_mask:0xf
	s_nop 1
	v_add_f32_dpp v168, v168, v168 quad_perm:[2,3,0,1] row_mask:0xf bank_mask:0xf
	s_nop 1
	v_add_f32_dpp v168, v168, v168 row_half_mirror row_mask:0xf bank_mask:0xf
	s_nop 1
	v_add_f32_dpp v168, v168, v168 row_mirror row_mask:0xf bank_mask:0xf
	s_nop 1
	v_add_f32_dpp v168, v168, v168 row_bcast:15 row_mask:0xa bank_mask:0xf
	s_nop 1
	v_add_f32_dpp v168, v168, v168 row_bcast:31 row_mask:0xc bank_mask:0xf
	s_nop 1
	v_readlane_b32 s42, v168, 63
	s_nop 3
	s_mov_b32 s43, s42
	v_pk_fma_f32 v[136:137], s[42:43], v[172:173], v[136:137]
	v_pk_fma_f32 v[138:139], s[42:43], v[172:173], v[138:139]
	v_pk_fma_f32 v[140:141], s[42:43], v[172:173], v[140:141]
	v_pk_fma_f32 v[142:143], s[42:43], v[172:173], v[142:143]
	v_pk_fma_f32 v[144:145], s[42:43], v[172:173], v[144:145]
	v_pk_fma_f32 v[146:147], s[42:43], v[172:173], v[146:147]
	v_pk_fma_f32 v[148:149], s[42:43], v[172:173], v[148:149]
	v_pk_fma_f32 v[150:151], s[42:43], v[172:173], v[150:151]
	v_pk_mul_f32 v[152:153], v[136:137], v[136:137]
	v_pk_fma_f32 v[152:153], v[138:139], v[138:139], v[152:153]
	v_pk_fma_f32 v[152:153], v[140:141], v[140:141], v[152:153]
	v_pk_fma_f32 v[152:153], v[142:143], v[142:143], v[152:153]
	v_pk_fma_f32 v[152:153], v[144:145], v[144:145], v[152:153]
	v_pk_fma_f32 v[152:153], v[146:147], v[146:147], v[152:153]
	v_pk_fma_f32 v[152:153], v[148:149], v[148:149], v[152:153]
	v_pk_fma_f32 v[152:153], v[150:151], v[150:151], v[152:153]
	v_add_f32_e32 v170, v152, v153
	s_nop 1
	v_add_f32_dpp v168, v170, v170 quad_perm:[1,0,3,2] row_mask:0xf bank_mask:0xf
	s_nop 1
	v_add_f32_dpp v168, v168, v168 quad_perm:[2,3,0,1] row_mask:0xf bank_mask:0xf
	s_nop 1
	v_add_f32_dpp v168, v168, v168 row_half_mirror row_mask:0xf bank_mask:0xf
	s_nop 1
	v_add_f32_dpp v168, v168, v168 row_mirror row_mask:0xf bank_mask:0xf
	s_nop 1
	v_add_f32_dpp v168, v168, v168 row_bcast:15 row_mask:0xa bank_mask:0xf
	s_nop 1
	v_add_f32_dpp v168, v168, v168 row_bcast:31 row_mask:0xc bank_mask:0xf
	s_nop 1
	v_readlane_b32 s42, v168, 63
	s_nop 3
	v_fma_f32 v174, s42, v178, v179
	v_rsq_f32_e32 v174, v174
	s_nop 0
	v_pk_mul_f32 v[136:137], v[136:137], v[174:175] op_sel_hi:[1,0]
	v_pk_mul_f32 v[138:139], v[138:139], v[174:175] op_sel_hi:[1,0]
	v_pk_mul_f32 v[140:141], v[140:141], v[174:175] op_sel_hi:[1,0]
	v_pk_mul_f32 v[142:143], v[142:143], v[174:175] op_sel_hi:[1,0]
	v_pk_mul_f32 v[144:145], v[144:145], v[174:175] op_sel_hi:[1,0]
	v_pk_mul_f32 v[146:147], v[146:147], v[174:175] op_sel_hi:[1,0]
	v_pk_mul_f32 v[148:149], v[148:149], v[174:175] op_sel_hi:[1,0]
	v_pk_mul_f32 v[150:151], v[150:151], v[174:175] op_sel_hi:[1,0]
	v_pk_fma_f32 v[136:137], v[136:137], v[32:33], v[48:49]
	v_pk_fma_f32 v[138:139], v[138:139], v[34:35], v[50:51]
	v_pk_fma_f32 v[140:141], v[140:141], v[36:37], v[52:53]
	v_pk_fma_f32 v[142:143], v[142:143], v[38:39], v[54:55]
	v_pk_fma_f32 v[144:145], v[144:145], v[40:41], v[56:57]
	v_pk_fma_f32 v[146:147], v[146:147], v[42:43], v[58:59]
	v_pk_fma_f32 v[148:149], v[148:149], v[44:45], v[60:61]
	v_pk_fma_f32 v[150:151], v[150:151], v[46:47], v[62:63]
	v_cvt_pk_bf16_f32 v152, v136, v137
	v_cvt_pk_bf16_f32 v153, v138, v139
	v_cvt_pk_bf16_f32 v154, v140, v141
	v_cvt_pk_bf16_f32 v155, v142, v143
	v_cvt_pk_bf16_f32 v156, v144, v145
	v_cvt_pk_bf16_f32 v157, v146, v147
	v_cvt_pk_bf16_f32 v158, v148, v149
	v_cvt_pk_bf16_f32 v159, v150, v151
	global_store_dwordx2 v177, v[152:153], s[12:13] offset:0
	global_store_dwordx2 v177, v[154:155], s[12:13] offset:512
	global_store_dwordx2 v177, v[156:157], s[12:13] offset:1024
	global_store_dwordx2 v177, v[158:159], s[12:13] offset:1536
	s_add_u32 s8, s8, 0x1000
	s_addc_u32 s9, s9, 0
	s_add_u32 s12, s12, 0x800
	s_addc_u32 s13, s13, 0
	s_waitcnt vmcnt(24)
	v_lshlrev_b32_e32 v136, 16, v128
	v_and_b32_e32 v137, 0xffff0000, v128
	v_lshlrev_b32_e32 v138, 16, v129
	v_and_b32_e32 v139, 0xffff0000, v129
	v_lshlrev_b32_e32 v140, 16, v130
	v_and_b32_e32 v141, 0xffff0000, v130
	v_lshlrev_b32_e32 v142, 16, v131
	v_and_b32_e32 v143, 0xffff0000, v131
	v_lshlrev_b32_e32 v144, 16, v132
	v_and_b32_e32 v145, 0xffff0000, v132
	v_lshlrev_b32_e32 v146, 16, v133
	v_and_b32_e32 v147, 0xffff0000, v133
	v_lshlrev_b32_e32 v148, 16, v134
	v_and_b32_e32 v149, 0xffff0000, v134
	v_lshlrev_b32_e32 v150, 16, v135
	v_and_b32_e32 v151, 0xffff0000, v135
	v_pk_fma_f32 v[136:137], v[96:97], s[44:45], v[136:137]
	v_pk_fma_f32 v[138:139], v[98:99], s[44:45], v[138:139]
	v_pk_fma_f32 v[140:141], v[100:101], s[44:45], v[140:141]
	v_pk_fma_f32 v[142:143], v[102:103], s[44:45], v[142:143]
	v_pk_fma_f32 v[144:145], v[104:105], s[44:45], v[144:145]
	v_pk_fma_f32 v[146:147], v[106:107], s[44:45], v[146:147]
	v_pk_fma_f32 v[148:149], v[108:109], s[44:45], v[148:149]
	v_pk_fma_f32 v[150:151], v[110:111], s[44:45], v[150:151]
	v_pk_add_f32 v[152:153], v[136:137], v[138:139]
	v_pk_add_f32 v[152:153], v[152:153], v[140:141]
	v_pk_add_f32 v[152:153], v[152:153], v[142:143]
	v_pk_add_f32 v[152:153], v[152:153], v[144:145]
	v_pk_add_f32 v[152:153], v[152:153], v[146:147]
	v_pk_add_f32 v[152:153], v[152:153], v[148:149]
	v_pk_add_f32 v[152:153], v[152:153], v[150:151]
	v_add_f32_e32 v170, v152, v153
	s_nop 1
	v_add_f32_dpp v168, v170, v170 quad_perm:[1,0,3,2] row_mask:0xf bank_mask:0xf
	s_nop 1
	v_add_f32_dpp v168, v168, v168 quad_perm:[2,3,0,1] row_mask:0xf bank_mask:0xf
	s_nop 1
	v_add_f32_dpp v168, v168, v168 row_half_mirror row_mask:0xf bank_mask:0xf
	s_nop 1
	v_add_f32_dpp v168, v168, v168 row_mirror row_mask:0xf bank_mask:0xf
	s_nop 1
	v_add_f32_dpp v168, v168, v168 row_bcast:15 row_mask:0xa bank_mask:0xf
	s_nop 1
	v_add_f32_dpp v168, v168, v168 row_bcast:31 row_mask:0xc bank_mask:0xf
	s_nop 1
	v_readlane_b32 s42, v168, 63
	s_nop 3
	s_mov_b32 s43, s42
	v_pk_fma_f32 v[136:137], s[42:43], v[172:173], v[136:137]
	v_pk_fma_f32 v[138:139], s[42:43], v[172:173], v[138:139]
	v_pk_fma_f32 v[140:141], s[42:43], v[172:173], v[140:141]
	v_pk_fma_f32 v[142:143], s[42:43], v[172:173], v[142:143]
	v_pk_fma_f32 v[144:145], s[42:43], v[172:173], v[144:145]
	v_pk_fma_f32 v[146:147], s[42:43], v[172:173], v[146:147]
	v_pk_fma_f32 v[148:149], s[42:43], v[172:173], v[148:149]
	v_pk_fma_f32 v[150:151], s[42:43], v[172:173], v[150:151]
	v_pk_mul_f32 v[152:153], v[136:137], v[136:137]
	v_pk_fma_f32 v[152:153], v[138:139], v[138:139], v[152:153]
	v_pk_fma_f32 v[152:153], v[140:141], v[140:141], v[152:153]
	v_pk_fma_f32 v[152:153], v[142:143], v[142:143], v[152:153]
	v_pk_fma_f32 v[152:153], v[144:145], v[144:145], v[152:153]
	v_pk_fma_f32 v[152:153], v[146:147], v[146:147], v[152:153]
	v_pk_fma_f32 v[152:153], v[148:149], v[148:149], v[152:153]
	v_pk_fma_f32 v[152:153], v[150:151], v[150:151], v[152:153]
	v_add_f32_e32 v170, v152, v153
	s_nop 1
	v_add_f32_dpp v168, v170, v170 quad_perm:[1,0,3,2] row_mask:0xf bank_mask:0xf
	s_nop 1
	v_add_f32_dpp v168, v168, v168 quad_perm:[2,3,0,1] row_mask:0xf bank_mask:0xf
	s_nop 1
	v_add_f32_dpp v168, v168, v168 row_half_mirror row_mask:0xf bank_mask:0xf
	s_nop 1
	v_add_f32_dpp v168, v168, v168 row_mirror row_mask:0xf bank_mask:0xf
	s_nop 1
	v_add_f32_dpp v168, v168, v168 row_bcast:15 row_mask:0xa bank_mask:0xf
	s_nop 1
	v_add_f32_dpp v168, v168, v168 row_bcast:31 row_mask:0xc bank_mask:0xf
	s_nop 1
	v_readlane_b32 s42, v168, 63
	s_nop 3
	v_fma_f32 v174, s42, v178, v179
	v_rsq_f32_e32 v174, v174
	s_nop 0
	v_pk_mul_f32 v[136:137], v[136:137], v[174:175] op_sel_hi:[1,0]
	v_pk_mul_f32 v[138:139], v[138:139], v[174:175] op_sel_hi:[1,0]
	v_pk_mul_f32 v[140:141], v[140:141], v[174:175] op_sel_hi:[1,0]
	v_pk_mul_f32 v[142:143], v[142:143], v[174:175] op_sel_hi:[1,0]
	v_pk_mul_f32 v[144:145], v[144:145], v[174:175] op_sel_hi:[1,0]
	v_pk_mul_f32 v[146:147], v[146:147], v[174:175] op_sel_hi:[1,0]
	v_pk_mul_f32 v[148:149], v[148:149], v[174:175] op_sel_hi:[1,0]
	v_pk_mul_f32 v[150:151], v[150:151], v[174:175] op_sel_hi:[1,0]
	v_pk_fma_f32 v[136:137], v[136:137], v[0:1], v[16:17]
	v_pk_fma_f32 v[138:139], v[138:139], v[2:3], v[18:19]
	v_pk_fma_f32 v[140:141], v[140:141], v[4:5], v[20:21]
	v_pk_fma_f32 v[142:143], v[142:143], v[6:7], v[22:23]
	v_pk_fma_f32 v[144:145], v[144:145], v[8:9], v[24:25]
	v_pk_fma_f32 v[146:147], v[146:147], v[10:11], v[26:27]
	v_pk_fma_f32 v[148:149], v[148:149], v[12:13], v[28:29]
	v_pk_fma_f32 v[150:151], v[150:151], v[14:15], v[30:31]
	global_store_dwordx4 v176, v[136:139], s[8:9] offset:0
	global_store_dwordx4 v176, v[140:143], s[8:9] offset:1024
	global_store_dwordx4 v176, v[144:147], s[8:9] offset:2048
	global_store_dwordx4 v176, v[148:151], s[8:9] offset:3072
	v_pk_add_f32 v[152:153], v[136:137], v[138:139]
	v_pk_add_f32 v[152:153], v[152:153], v[140:141]
	v_pk_add_f32 v[152:153], v[152:153], v[142:143]
	v_pk_add_f32 v[152:153], v[152:153], v[144:145]
	v_pk_add_f32 v[152:153], v[152:153], v[146:147]
	v_pk_add_f32 v[152:153], v[152:153], v[148:149]
	v_pk_add_f32 v[152:153], v[152:153], v[150:151]
	v_add_f32_e32 v170, v152, v153
	s_nop 1
	v_add_f32_dpp v168, v170, v170 quad_perm:[1,0,3,2] row_mask:0xf bank_mask:0xf
	s_nop 1
	v_add_f32_dpp v168, v168, v168 quad_perm:[2,3,0,1] row_mask:0xf bank_mask:0xf
	s_nop 1
	v_add_f32_dpp v168, v168, v168 row_half_mirror row_mask:0xf bank_mask:0xf
	s_nop 1
	v_add_f32_dpp v168, v168, v168 row_mirror row_mask:0xf bank_mask:0xf
	s_nop 1
	v_add_f32_dpp v168, v168, v168 row_bcast:15 row_mask:0xa bank_mask:0xf
	s_nop 1
	v_add_f32_dpp v168, v168, v168 row_bcast:31 row_mask:0xc bank_mask:0xf
	s_nop 1
	v_readlane_b32 s42, v168, 63
	s_nop 3
	s_mov_b32 s43, s42
	v_pk_fma_f32 v[136:137], s[42:43], v[172:173], v[136:137]
	v_pk_fma_f32 v[138:139], s[42:43], v[172:173], v[138:139]
	v_pk_fma_f32 v[140:141], s[42:43], v[172:173], v[140:141]
	v_pk_fma_f32 v[142:143], s[42:43], v[172:173], v[142:143]
	v_pk_fma_f32 v[144:145], s[42:43], v[172:173], v[144:145]
	v_pk_fma_f32 v[146:147], s[42:43], v[172:173], v[146:147]
	v_pk_fma_f32 v[148:149], s[42:43], v[172:173], v[148:149]
	v_pk_fma_f32 v[150:151], s[42:43], v[172:173], v[150:151]
	v_pk_mul_f32 v[152:153], v[136:137], v[136:137]
	v_pk_fma_f32 v[152:153], v[138:139], v[138:139], v[152:153]
	v_pk_fma_f32 v[152:153], v[140:141], v[140:141], v[152:153]
	v_pk_fma_f32 v[152:153], v[142:143], v[142:143], v[152:153]
	v_pk_fma_f32 v[152:153], v[144:145], v[144:145], v[152:153]
	v_pk_fma_f32 v[152:153], v[146:147], v[146:147], v[152:153]
	v_pk_fma_f32 v[152:153], v[148:149], v[148:149], v[152:153]
	v_pk_fma_f32 v[152:153], v[150:151], v[150:151], v[152:153]
	v_add_f32_e32 v170, v152, v153
	s_nop 1
	v_add_f32_dpp v168, v170, v170 quad_perm:[1,0,3,2] row_mask:0xf bank_mask:0xf
	s_nop 1
	v_add_f32_dpp v168, v168, v168 quad_perm:[2,3,0,1] row_mask:0xf bank_mask:0xf
	s_nop 1
	v_add_f32_dpp v168, v168, v168 row_half_mirror row_mask:0xf bank_mask:0xf
	s_nop 1
	v_add_f32_dpp v168, v168, v168 row_mirror row_mask:0xf bank_mask:0xf
	s_nop 1
	v_add_f32_dpp v168, v168, v168 row_bcast:15 row_mask:0xa bank_mask:0xf
	s_nop 1
	v_add_f32_dpp v168, v168, v168 row_bcast:31 row_mask:0xc bank_mask:0xf
	s_nop 1
	v_readlane_b32 s42, v168, 63
	s_nop 3
	v_fma_f32 v174, s42, v178, v179
	v_rsq_f32_e32 v174, v174
	s_nop 0
	v_pk_mul_f32 v[136:137], v[136:137], v[174:175] op_sel_hi:[1,0]
	v_pk_mul_f32 v[138:139], v[138:139], v[174:175] op_sel_hi:[1,0]
	v_pk_mul_f32 v[140:141], v[140:141], v[174:175] op_sel_hi:[1,0]
	v_pk_mul_f32 v[142:143], v[142:143], v[174:175] op_sel_hi:[1,0]
	v_pk_mul_f32 v[144:145], v[144:145], v[174:175] op_sel_hi:[1,0]
	v_pk_mul_f32 v[146:147], v[146:147], v[174:175] op_sel_hi:[1,0]
	v_pk_mul_f32 v[148:149], v[148:149], v[174:175] op_sel_hi:[1,0]
	v_pk_mul_f32 v[150:151], v[150:151], v[174:175] op_sel_hi:[1,0]
	v_pk_fma_f32 v[136:137], v[136:137], v[32:33], v[48:49]
	v_pk_fma_f32 v[138:139], v[138:139], v[34:35], v[50:51]
	v_pk_fma_f32 v[140:141], v[140:141], v[36:37], v[52:53]
	v_pk_fma_f32 v[142:143], v[142:143], v[38:39], v[54:55]
	v_pk_fma_f32 v[144:145], v[144:145], v[40:41], v[56:57]
	v_pk_fma_f32 v[146:147], v[146:147], v[42:43], v[58:59]
	v_pk_fma_f32 v[148:149], v[148:149], v[44:45], v[60:61]
	v_pk_fma_f32 v[150:151], v[150:151], v[46:47], v[62:63]
	v_cvt_pk_bf16_f32 v152, v136, v137
	v_cvt_pk_bf16_f32 v153, v138, v139
	v_cvt_pk_bf16_f32 v154, v140, v141
	v_cvt_pk_bf16_f32 v155, v142, v143
	v_cvt_pk_bf16_f32 v156, v144, v145
	v_cvt_pk_bf16_f32 v157, v146, v147
	v_cvt_pk_bf16_f32 v158, v148, v149
	v_cvt_pk_bf16_f32 v159, v150, v151
	global_store_dwordx2 v177, v[152:153], s[12:13] offset:0
	global_store_dwordx2 v177, v[154:155], s[12:13] offset:512
	global_store_dwordx2 v177, v[156:157], s[12:13] offset:1024
	global_store_dwordx2 v177, v[158:159], s[12:13] offset:1536
	s_add_u32 s8, s8, 0x1000
	s_addc_u32 s9, s9, 0
	s_add_u32 s12, s12, 0x800
	s_addc_u32 s13, s13, 0
	s_waitcnt vmcnt(16)
	v_lshlrev_b32_e32 v136, 16, v112
	v_and_b32_e32 v137, 0xffff0000, v112
	v_lshlrev_b32_e32 v138, 16, v113
	v_and_b32_e32 v139, 0xffff0000, v113
	v_lshlrev_b32_e32 v140, 16, v114
	v_and_b32_e32 v141, 0xffff0000, v114
	v_lshlrev_b32_e32 v142, 16, v115
	v_and_b32_e32 v143, 0xffff0000, v115
	v_lshlrev_b32_e32 v144, 16, v116
	v_and_b32_e32 v145, 0xffff0000, v116
	v_lshlrev_b32_e32 v146, 16, v117
	v_and_b32_e32 v147, 0xffff0000, v117
	v_lshlrev_b32_e32 v148, 16, v118
	v_and_b32_e32 v149, 0xffff0000, v118
	v_lshlrev_b32_e32 v150, 16, v119
	v_and_b32_e32 v151, 0xffff0000, v119
	v_pk_fma_f32 v[136:137], v[64:65], s[44:45], v[136:137]
	v_pk_fma_f32 v[138:139], v[66:67], s[44:45], v[138:139]
	v_pk_fma_f32 v[140:141], v[68:69], s[44:45], v[140:141]
	v_pk_fma_f32 v[142:143], v[70:71], s[44:45], v[142:143]
	v_pk_fma_f32 v[144:145], v[72:73], s[44:45], v[144:145]
	v_pk_fma_f32 v[146:147], v[74:75], s[44:45], v[146:147]
	v_pk_fma_f32 v[148:149], v[76:77], s[44:45], v[148:149]
	v_pk_fma_f32 v[150:151], v[78:79], s[44:45], v[150:151]
	v_pk_add_f32 v[152:153], v[136:137], v[138:139]
	v_pk_add_f32 v[152:153], v[152:153], v[140:141]
	v_pk_add_f32 v[152:153], v[152:153], v[142:143]
	v_pk_add_f32 v[152:153], v[152:153], v[144:145]
	v_pk_add_f32 v[152:153], v[152:153], v[146:147]
	v_pk_add_f32 v[152:153], v[152:153], v[148:149]
	v_pk_add_f32 v[152:153], v[152:153], v[150:151]
	v_add_f32_e32 v170, v152, v153
	s_nop 1
	v_add_f32_dpp v168, v170, v170 quad_perm:[1,0,3,2] row_mask:0xf bank_mask:0xf
	s_nop 1
	v_add_f32_dpp v168, v168, v168 quad_perm:[2,3,0,1] row_mask:0xf bank_mask:0xf
	s_nop 1
	v_add_f32_dpp v168, v168, v168 row_half_mirror row_mask:0xf bank_mask:0xf
	s_nop 1
	v_add_f32_dpp v168, v168, v168 row_mirror row_mask:0xf bank_mask:0xf
	s_nop 1
	v_add_f32_dpp v168, v168, v168 row_bcast:15 row_mask:0xa bank_mask:0xf
	s_nop 1
	v_add_f32_dpp v168, v168, v168 row_bcast:31 row_mask:0xc bank_mask:0xf
	s_nop 1
	v_readlane_b32 s42, v168, 63
	s_nop 3
	s_mov_b32 s43, s42
	v_pk_fma_f32 v[136:137], s[42:43], v[172:173], v[136:137]
	v_pk_fma_f32 v[138:139], s[42:43], v[172:173], v[138:139]
	v_pk_fma_f32 v[140:141], s[42:43], v[172:173], v[140:141]
	v_pk_fma_f32 v[142:143], s[42:43], v[172:173], v[142:143]
	v_pk_fma_f32 v[144:145], s[42:43], v[172:173], v[144:145]
	v_pk_fma_f32 v[146:147], s[42:43], v[172:173], v[146:147]
	v_pk_fma_f32 v[148:149], s[42:43], v[172:173], v[148:149]
	v_pk_fma_f32 v[150:151], s[42:43], v[172:173], v[150:151]
	v_pk_mul_f32 v[152:153], v[136:137], v[136:137]
	v_pk_fma_f32 v[152:153], v[138:139], v[138:139], v[152:153]
	v_pk_fma_f32 v[152:153], v[140:141], v[140:141], v[152:153]
	v_pk_fma_f32 v[152:153], v[142:143], v[142:143], v[152:153]
	v_pk_fma_f32 v[152:153], v[144:145], v[144:145], v[152:153]
	v_pk_fma_f32 v[152:153], v[146:147], v[146:147], v[152:153]
	v_pk_fma_f32 v[152:153], v[148:149], v[148:149], v[152:153]
	v_pk_fma_f32 v[152:153], v[150:151], v[150:151], v[152:153]
	v_add_f32_e32 v170, v152, v153
	s_nop 1
	v_add_f32_dpp v168, v170, v170 quad_perm:[1,0,3,2] row_mask:0xf bank_mask:0xf
	s_nop 1
	v_add_f32_dpp v168, v168, v168 quad_perm:[2,3,0,1] row_mask:0xf bank_mask:0xf
	s_nop 1
	v_add_f32_dpp v168, v168, v168 row_half_mirror row_mask:0xf bank_mask:0xf
	s_nop 1
	v_add_f32_dpp v168, v168, v168 row_mirror row_mask:0xf bank_mask:0xf
	s_nop 1
	v_add_f32_dpp v168, v168, v168 row_bcast:15 row_mask:0xa bank_mask:0xf
	s_nop 1
	v_add_f32_dpp v168, v168, v168 row_bcast:31 row_mask:0xc bank_mask:0xf
	s_nop 1
	v_readlane_b32 s42, v168, 63
	s_nop 3
	v_fma_f32 v174, s42, v178, v179
	v_rsq_f32_e32 v174, v174
	s_nop 0
	v_pk_mul_f32 v[136:137], v[136:137], v[174:175] op_sel_hi:[1,0]
	v_pk_mul_f32 v[138:139], v[138:139], v[174:175] op_sel_hi:[1,0]
	v_pk_mul_f32 v[140:141], v[140:141], v[174:175] op_sel_hi:[1,0]
	v_pk_mul_f32 v[142:143], v[142:143], v[174:175] op_sel_hi:[1,0]
	v_pk_mul_f32 v[144:145], v[144:145], v[174:175] op_sel_hi:[1,0]
	v_pk_mul_f32 v[146:147], v[146:147], v[174:175] op_sel_hi:[1,0]
	v_pk_mul_f32 v[148:149], v[148:149], v[174:175] op_sel_hi:[1,0]
	v_pk_mul_f32 v[150:151], v[150:151], v[174:175] op_sel_hi:[1,0]
	v_pk_fma_f32 v[136:137], v[136:137], v[0:1], v[16:17]
	v_pk_fma_f32 v[138:139], v[138:139], v[2:3], v[18:19]
	v_pk_fma_f32 v[140:141], v[140:141], v[4:5], v[20:21]
	v_pk_fma_f32 v[142:143], v[142:143], v[6:7], v[22:23]
	v_pk_fma_f32 v[144:145], v[144:145], v[8:9], v[24:25]
	v_pk_fma_f32 v[146:147], v[146:147], v[10:11], v[26:27]
	v_pk_fma_f32 v[148:149], v[148:149], v[12:13], v[28:29]
	v_pk_fma_f32 v[150:151], v[150:151], v[14:15], v[30:31]
	global_store_dwordx4 v176, v[136:139], s[8:9] offset:0
	global_store_dwordx4 v176, v[140:143], s[8:9] offset:1024
	global_store_dwordx4 v176, v[144:147], s[8:9] offset:2048
	global_store_dwordx4 v176, v[148:151], s[8:9] offset:3072
	v_pk_add_f32 v[152:153], v[136:137], v[138:139]
	v_pk_add_f32 v[152:153], v[152:153], v[140:141]
	v_pk_add_f32 v[152:153], v[152:153], v[142:143]
	v_pk_add_f32 v[152:153], v[152:153], v[144:145]
	v_pk_add_f32 v[152:153], v[152:153], v[146:147]
	v_pk_add_f32 v[152:153], v[152:153], v[148:149]
	v_pk_add_f32 v[152:153], v[152:153], v[150:151]
	v_add_f32_e32 v170, v152, v153
	s_nop 1
	v_add_f32_dpp v168, v170, v170 quad_perm:[1,0,3,2] row_mask:0xf bank_mask:0xf
	s_nop 1
	v_add_f32_dpp v168, v168, v168 quad_perm:[2,3,0,1] row_mask:0xf bank_mask:0xf
	s_nop 1
	v_add_f32_dpp v168, v168, v168 row_half_mirror row_mask:0xf bank_mask:0xf
	s_nop 1
	v_add_f32_dpp v168, v168, v168 row_mirror row_mask:0xf bank_mask:0xf
	s_nop 1
	v_add_f32_dpp v168, v168, v168 row_bcast:15 row_mask:0xa bank_mask:0xf
	s_nop 1
	v_add_f32_dpp v168, v168, v168 row_bcast:31 row_mask:0xc bank_mask:0xf
	s_nop 1
	v_readlane_b32 s42, v168, 63
	s_nop 3
	s_mov_b32 s43, s42
	v_pk_fma_f32 v[136:137], s[42:43], v[172:173], v[136:137]
	v_pk_fma_f32 v[138:139], s[42:43], v[172:173], v[138:139]
	v_pk_fma_f32 v[140:141], s[42:43], v[172:173], v[140:141]
	v_pk_fma_f32 v[142:143], s[42:43], v[172:173], v[142:143]
	v_pk_fma_f32 v[144:145], s[42:43], v[172:173], v[144:145]
	v_pk_fma_f32 v[146:147], s[42:43], v[172:173], v[146:147]
	v_pk_fma_f32 v[148:149], s[42:43], v[172:173], v[148:149]
	v_pk_fma_f32 v[150:151], s[42:43], v[172:173], v[150:151]
	v_pk_mul_f32 v[152:153], v[136:137], v[136:137]
	v_pk_fma_f32 v[152:153], v[138:139], v[138:139], v[152:153]
	v_pk_fma_f32 v[152:153], v[140:141], v[140:141], v[152:153]
	v_pk_fma_f32 v[152:153], v[142:143], v[142:143], v[152:153]
	v_pk_fma_f32 v[152:153], v[144:145], v[144:145], v[152:153]
	v_pk_fma_f32 v[152:153], v[146:147], v[146:147], v[152:153]
	v_pk_fma_f32 v[152:153], v[148:149], v[148:149], v[152:153]
	v_pk_fma_f32 v[152:153], v[150:151], v[150:151], v[152:153]
	v_add_f32_e32 v170, v152, v153
	s_nop 1
	v_add_f32_dpp v168, v170, v170 quad_perm:[1,0,3,2] row_mask:0xf bank_mask:0xf
	s_nop 1
	v_add_f32_dpp v168, v168, v168 quad_perm:[2,3,0,1] row_mask:0xf bank_mask:0xf
	s_nop 1
	v_add_f32_dpp v168, v168, v168 row_half_mirror row_mask:0xf bank_mask:0xf
	s_nop 1
	v_add_f32_dpp v168, v168, v168 row_mirror row_mask:0xf bank_mask:0xf
	s_nop 1
	v_add_f32_dpp v168, v168, v168 row_bcast:15 row_mask:0xa bank_mask:0xf
	s_nop 1
	v_add_f32_dpp v168, v168, v168 row_bcast:31 row_mask:0xc bank_mask:0xf
	s_nop 1
	v_readlane_b32 s42, v168, 63
	s_nop 3
	v_fma_f32 v174, s42, v178, v179
	v_rsq_f32_e32 v174, v174
	s_nop 0
	v_pk_mul_f32 v[136:137], v[136:137], v[174:175] op_sel_hi:[1,0]
	v_pk_mul_f32 v[138:139], v[138:139], v[174:175] op_sel_hi:[1,0]
	v_pk_mul_f32 v[140:141], v[140:141], v[174:175] op_sel_hi:[1,0]
	v_pk_mul_f32 v[142:143], v[142:143], v[174:175] op_sel_hi:[1,0]
	v_pk_mul_f32 v[144:145], v[144:145], v[174:175] op_sel_hi:[1,0]
	v_pk_mul_f32 v[146:147], v[146:147], v[174:175] op_sel_hi:[1,0]
	v_pk_mul_f32 v[148:149], v[148:149], v[174:175] op_sel_hi:[1,0]
	v_pk_mul_f32 v[150:151], v[150:151], v[174:175] op_sel_hi:[1,0]
	v_pk_fma_f32 v[136:137], v[136:137], v[32:33], v[48:49]
	v_pk_fma_f32 v[138:139], v[138:139], v[34:35], v[50:51]
	v_pk_fma_f32 v[140:141], v[140:141], v[36:37], v[52:53]
	v_pk_fma_f32 v[142:143], v[142:143], v[38:39], v[54:55]
	v_pk_fma_f32 v[144:145], v[144:145], v[40:41], v[56:57]
	v_pk_fma_f32 v[146:147], v[146:147], v[42:43], v[58:59]
	v_pk_fma_f32 v[148:149], v[148:149], v[44:45], v[60:61]
	v_pk_fma_f32 v[150:151], v[150:151], v[46:47], v[62:63]
	v_cvt_pk_bf16_f32 v152, v136, v137
	v_cvt_pk_bf16_f32 v153, v138, v139
	v_cvt_pk_bf16_f32 v154, v140, v141
	v_cvt_pk_bf16_f32 v155, v142, v143
	v_cvt_pk_bf16_f32 v156, v144, v145
	v_cvt_pk_bf16_f32 v157, v146, v147
	v_cvt_pk_bf16_f32 v158, v148, v149
	v_cvt_pk_bf16_f32 v159, v150, v151
	global_store_dwordx2 v177, v[152:153], s[12:13] offset:0
	global_store_dwordx2 v177, v[154:155], s[12:13] offset:512
	global_store_dwordx2 v177, v[156:157], s[12:13] offset:1024
	global_store_dwordx2 v177, v[158:159], s[12:13] offset:1536
	s_add_u32 s8, s8, 0x1000
	s_addc_u32 s9, s9, 0
	s_add_u32 s12, s12, 0x800
	s_addc_u32 s13, s13, 0
	s_mov_b64 s[16:17], 0x1000
	s_mov_b32 s18, 0x800000
	s_mov_b32 s19, 0xec00000
	s_mov_b32 s20, 0x2400000
	s_add_u32 s28, s90, 0x21b3000
	s_addc_u32 s29, s91, 0
	s_mov_b32 s15, 0x8000
	s_mov_b32 s14, 0x3fb504f3
